# GEMM K-loops: redundant lgkmcnt(0) after each barrier removed and the block-closing s_setprio 0 moved behind the barrier (fewer instructions on the MFMA half's path to the rendezvous)
# speedup vs baseline: 1.0054x; 1.0010x over previous
.LBB0_117:
	ds_read_b128 v[130:133], v161
	ds_read_b128 v[134:137], v161 offset:1024
	ds_read_b128 v[170:173], v161 offset:2048
	ds_read_b128 v[174:177], v161 offset:3072
	ds_read_b128 v[178:181], v163
	ds_read_b128 v[182:185], v163 offset:1024
	ds_read_b128 v[186:189], v163 offset:2048
	ds_read_b128 v[190:193], v163 offset:3072
	s_add_u32 s50, s48, 0xfff80080
	s_addc_u32 s51, s49, -1
	s_cmp_eq_u32 s74, 28
	s_cselect_b32 s53, s9, s51
	s_cselect_b32 s52, s43, s50
	s_cselect_b32 s51, s41, s73
	s_cselect_b32 s50, s71, s72
	v_lshl_add_u64 v[154:155], s[48:49], 0, v[146:147]
	s_add_i32 m0, s56, 0xc000
	ds_read_b128 v[194:197], v165
	ds_read_b128 v[198:201], v165 offset:1024
	ds_read_b128 v[202:205], v165 offset:2048
	ds_read_b128 v[206:209], v165 offset:3072
	ds_read_b128 v[210:213], v165 offset:4096
	ds_read_b128 v[214:217], v165 offset:5120
	ds_read_b128 v[218:221], v165 offset:6144
	ds_read_b128 v[222:225], v165 offset:7168
	global_load_lds_dwordx4 v[154:155], off
	v_lshl_add_u64 v[154:155], s[48:49], 0, v[148:149]
	s_add_i32 m0, s56, 0xe000
	s_nop 0
	global_load_lds_dwordx4 v[154:155], off
	s_waitcnt vmcnt(8)
	s_waitcnt lgkmcnt(0)
	s_barrier
	s_setprio 1
	v_mfma_f32_16x16x32_bf16 v[126:129], v[130:133], v[194:197], v[126:129]
	v_mfma_f32_16x16x32_bf16 v[122:125], v[170:173], v[194:197], v[122:125]
	v_mfma_f32_16x16x32_bf16 v[118:121], v[130:133], v[202:205], v[118:121]
	v_mfma_f32_16x16x32_bf16 v[110:113], v[170:173], v[202:205], v[110:113]
	v_mfma_f32_16x16x32_bf16 v[102:105], v[130:133], v[210:213], v[102:105]
	v_mfma_f32_16x16x32_bf16 v[94:97], v[170:173], v[210:213], v[94:97]
	v_mfma_f32_16x16x32_bf16 v[86:89], v[130:133], v[218:221], v[86:89]
	v_mfma_f32_16x16x32_bf16 v[78:81], v[170:173], v[218:221], v[78:81]
	v_mfma_f32_16x16x32_bf16 v[126:129], v[134:137], v[198:201], v[126:129]
	v_mfma_f32_16x16x32_bf16 v[122:125], v[174:177], v[198:201], v[122:125]
	v_mfma_f32_16x16x32_bf16 v[118:121], v[134:137], v[206:209], v[118:121]
	v_mfma_f32_16x16x32_bf16 v[110:113], v[174:177], v[206:209], v[110:113]
	v_mfma_f32_16x16x32_bf16 v[102:105], v[134:137], v[214:217], v[102:105]
	v_mfma_f32_16x16x32_bf16 v[94:97], v[174:177], v[214:217], v[94:97]
	v_mfma_f32_16x16x32_bf16 v[86:89], v[134:137], v[222:225], v[86:89]
	v_mfma_f32_16x16x32_bf16 v[78:81], v[174:177], v[222:225], v[78:81]
	s_setprio 0
	s_setprio 1
	v_mfma_f32_16x16x32_bf16 v[114:117], v[178:181], v[194:197], v[114:117]
	v_mfma_f32_16x16x32_bf16 v[106:109], v[186:189], v[194:197], v[106:109]
	v_mfma_f32_16x16x32_bf16 v[98:101], v[178:181], v[202:205], v[98:101]
	v_mfma_f32_16x16x32_bf16 v[90:93], v[186:189], v[202:205], v[90:93]
	v_mfma_f32_16x16x32_bf16 v[82:85], v[178:181], v[210:213], v[82:85]
	v_mfma_f32_16x16x32_bf16 v[74:77], v[186:189], v[210:213], v[74:77]
	v_mfma_f32_16x16x32_bf16 v[70:73], v[178:181], v[218:221], v[70:73]
	v_mfma_f32_16x16x32_bf16 v[66:69], v[186:189], v[218:221], v[66:69]
	v_mfma_f32_16x16x32_bf16 v[114:117], v[182:185], v[198:201], v[114:117]
	v_mfma_f32_16x16x32_bf16 v[106:109], v[190:193], v[198:201], v[106:109]
	v_mfma_f32_16x16x32_bf16 v[98:101], v[182:185], v[206:209], v[98:101]
	v_mfma_f32_16x16x32_bf16 v[90:93], v[190:193], v[206:209], v[90:93]
	v_mfma_f32_16x16x32_bf16 v[82:85], v[182:185], v[214:217], v[82:85]
	v_mfma_f32_16x16x32_bf16 v[74:77], v[190:193], v[214:217], v[74:77]
	v_mfma_f32_16x16x32_bf16 v[70:73], v[182:185], v[222:225], v[70:73]
	v_mfma_f32_16x16x32_bf16 v[66:69], v[190:193], v[222:225], v[66:69]
	s_barrier
	s_setprio 0
	s_add_i32 s75, s67, s55
	v_lshl_add_u64 v[154:155], s[50:51], 0, v[140:141]
	s_mov_b32 m0, s75
	ds_read_b128 v[194:197], v165 offset:16384
	ds_read_b128 v[198:201], v165 offset:17408
	ds_read_b128 v[202:205], v165 offset:18432
	ds_read_b128 v[206:209], v165 offset:19456
	ds_read_b128 v[210:213], v165 offset:20480
	ds_read_b128 v[214:217], v165 offset:21504
	ds_read_b128 v[218:221], v165 offset:22528
	ds_read_b128 v[222:225], v165 offset:23552
	global_load_lds_dwordx4 v[154:155], off
	s_add_i32 m0, s75, 0x2000
	s_add_u32 s76, s50, 0x80000
	v_lshl_add_u64 v[166:167], s[50:51], 0, v[144:145]
	s_addc_u32 s77, s51, 0
	s_add_i32 s75, s68, s55
	global_load_lds_dwordx4 v[166:167], off
	v_lshl_add_u64 v[226:227], s[76:77], 0, v[140:141]
	s_mov_b32 m0, s75
	v_lshl_add_u64 v[228:229], s[52:53], 0, v[142:143]
	global_load_lds_dwordx4 v[226:227], off
	v_lshl_add_u64 v[226:227], s[76:77], 0, v[144:145]
	s_add_i32 m0, s75, 0x2000
	s_nop 0
	global_load_lds_dwordx4 v[226:227], off
	v_lshl_add_u64 v[226:227], s[52:53], 0, v[138:139]
	s_mov_b32 m0, s56
	s_nop 0
	global_load_lds_dwordx4 v[226:227], off
	s_mov_b32 m0, s57
	s_nop 0
	global_load_lds_dwordx4 v[228:229], off
	s_waitcnt vmcnt(8)
	s_waitcnt lgkmcnt(0)
	s_barrier
	s_setprio 1
	v_mfma_f32_16x16x32_bf16 v[62:65], v[130:133], v[194:197], v[62:65]
	v_mfma_f32_16x16x32_bf16 v[58:61], v[170:173], v[194:197], v[58:61]
	v_mfma_f32_16x16x32_bf16 v[54:57], v[130:133], v[202:205], v[54:57]
	v_mfma_f32_16x16x32_bf16 v[46:49], v[170:173], v[202:205], v[46:49]
	v_mfma_f32_16x16x32_bf16 v[38:41], v[130:133], v[210:213], v[38:41]
	v_mfma_f32_16x16x32_bf16 v[30:33], v[170:173], v[210:213], v[30:33]
	v_mfma_f32_16x16x32_bf16 v[22:25], v[130:133], v[218:221], v[22:25]
	v_mfma_f32_16x16x32_bf16 v[14:17], v[170:173], v[218:221], v[14:17]
	v_mfma_f32_16x16x32_bf16 v[62:65], v[134:137], v[198:201], v[62:65]
	v_mfma_f32_16x16x32_bf16 v[58:61], v[174:177], v[198:201], v[58:61]
	v_mfma_f32_16x16x32_bf16 v[54:57], v[134:137], v[206:209], v[54:57]
	v_mfma_f32_16x16x32_bf16 v[46:49], v[174:177], v[206:209], v[46:49]
	v_mfma_f32_16x16x32_bf16 v[38:41], v[134:137], v[214:217], v[38:41]
	v_mfma_f32_16x16x32_bf16 v[30:33], v[174:177], v[214:217], v[30:33]
	v_mfma_f32_16x16x32_bf16 v[22:25], v[134:137], v[222:225], v[22:25]
	v_mfma_f32_16x16x32_bf16 v[14:17], v[174:177], v[222:225], v[14:17]
	s_setprio 0
	s_setprio 1
	v_mfma_f32_16x16x32_bf16 v[50:53], v[178:181], v[194:197], v[50:53]
	v_mfma_f32_16x16x32_bf16 v[42:45], v[186:189], v[194:197], v[42:45]
	v_mfma_f32_16x16x32_bf16 v[34:37], v[178:181], v[202:205], v[34:37]
	v_mfma_f32_16x16x32_bf16 v[26:29], v[186:189], v[202:205], v[26:29]
	v_mfma_f32_16x16x32_bf16 v[18:21], v[178:181], v[210:213], v[18:21]
	v_mfma_f32_16x16x32_bf16 v[10:13], v[186:189], v[210:213], v[10:13]
	v_mfma_f32_16x16x32_bf16 v[6:9], v[178:181], v[218:221], v[6:9]
	v_mfma_f32_16x16x32_bf16 v[2:5], v[186:189], v[218:221], v[2:5]
	v_mfma_f32_16x16x32_bf16 v[50:53], v[182:185], v[198:201], v[50:53]
	v_mfma_f32_16x16x32_bf16 v[42:45], v[190:193], v[198:201], v[42:45]
	v_mfma_f32_16x16x32_bf16 v[34:37], v[182:185], v[206:209], v[34:37]
	v_mfma_f32_16x16x32_bf16 v[26:29], v[190:193], v[206:209], v[26:29]
	v_mfma_f32_16x16x32_bf16 v[18:21], v[182:185], v[214:217], v[18:21]
	v_mfma_f32_16x16x32_bf16 v[10:13], v[190:193], v[214:217], v[10:13]
	v_mfma_f32_16x16x32_bf16 v[6:9], v[182:185], v[222:225], v[6:9]
	v_mfma_f32_16x16x32_bf16 v[2:5], v[190:193], v[222:225], v[2:5]
	s_barrier
	s_setprio 0
	s_add_i32 s75, 0, 0x18000
	v_add_u32_e32 v156, s75, v159
	s_add_i32 s76, 0, 0x1c000
	ds_read_b128 v[130:133], v156
	ds_read_b128 v[134:137], v156 offset:1024
	ds_read_b128 v[170:173], v156 offset:2048
	ds_read_b128 v[174:177], v156 offset:3072
	v_add_u32_e32 v156, s76, v159
	ds_read_b128 v[178:181], v156
	ds_read_b128 v[182:185], v156 offset:1024
	ds_read_b128 v[186:189], v156 offset:2048
	ds_read_b128 v[190:193], v156 offset:3072
	s_add_u32 s52, s52, 0x80000
	s_addc_u32 s53, s53, 0
	s_mov_b32 m0, s58
	v_lshl_add_u64 v[230:231], s[52:53], 0, v[138:139]
	ds_read_b128 v[194:197], v165 offset:32768
	ds_read_b128 v[198:201], v165 offset:33792
	ds_read_b128 v[202:205], v165 offset:34816
	ds_read_b128 v[206:209], v165 offset:35840
	ds_read_b128 v[210:213], v165 offset:36864
	ds_read_b128 v[214:217], v165 offset:37888
	ds_read_b128 v[218:221], v165 offset:38912
	ds_read_b128 v[222:225], v165 offset:39936
	global_load_lds_dwordx4 v[230:231], off
	v_lshl_add_u64 v[230:231], s[52:53], 0, v[142:143]
	s_mov_b32 m0, s59
	s_nop 0
	global_load_lds_dwordx4 v[230:231], off
	s_waitcnt vmcnt(8)
	s_waitcnt lgkmcnt(0)
	s_barrier
	s_setprio 1
	v_mfma_f32_16x16x32_bf16 v[126:129], v[130:133], v[194:197], v[126:129]
	v_mfma_f32_16x16x32_bf16 v[122:125], v[170:173], v[194:197], v[122:125]
	v_mfma_f32_16x16x32_bf16 v[118:121], v[130:133], v[202:205], v[118:121]
	v_mfma_f32_16x16x32_bf16 v[110:113], v[170:173], v[202:205], v[110:113]
	v_mfma_f32_16x16x32_bf16 v[102:105], v[130:133], v[210:213], v[102:105]
	v_mfma_f32_16x16x32_bf16 v[94:97], v[170:173], v[210:213], v[94:97]
	v_mfma_f32_16x16x32_bf16 v[86:89], v[130:133], v[218:221], v[86:89]
	v_mfma_f32_16x16x32_bf16 v[78:81], v[170:173], v[218:221], v[78:81]
	v_mfma_f32_16x16x32_bf16 v[126:129], v[134:137], v[198:201], v[126:129]
	v_mfma_f32_16x16x32_bf16 v[122:125], v[174:177], v[198:201], v[122:125]
	v_mfma_f32_16x16x32_bf16 v[118:121], v[134:137], v[206:209], v[118:121]
	v_mfma_f32_16x16x32_bf16 v[110:113], v[174:177], v[206:209], v[110:113]
	v_mfma_f32_16x16x32_bf16 v[102:105], v[134:137], v[214:217], v[102:105]
	v_mfma_f32_16x16x32_bf16 v[94:97], v[174:177], v[214:217], v[94:97]
	v_mfma_f32_16x16x32_bf16 v[86:89], v[134:137], v[222:225], v[86:89]
	v_mfma_f32_16x16x32_bf16 v[78:81], v[174:177], v[222:225], v[78:81]
	s_setprio 0
	s_setprio 1
	v_mfma_f32_16x16x32_bf16 v[114:117], v[178:181], v[194:197], v[114:117]
	v_mfma_f32_16x16x32_bf16 v[106:109], v[186:189], v[194:197], v[106:109]
	v_mfma_f32_16x16x32_bf16 v[98:101], v[178:181], v[202:205], v[98:101]
	v_mfma_f32_16x16x32_bf16 v[90:93], v[186:189], v[202:205], v[90:93]
	v_mfma_f32_16x16x32_bf16 v[82:85], v[178:181], v[210:213], v[82:85]
	v_mfma_f32_16x16x32_bf16 v[74:77], v[186:189], v[210:213], v[74:77]
	v_mfma_f32_16x16x32_bf16 v[70:73], v[178:181], v[218:221], v[70:73]
	v_mfma_f32_16x16x32_bf16 v[66:69], v[186:189], v[218:221], v[66:69]
	v_mfma_f32_16x16x32_bf16 v[114:117], v[182:185], v[198:201], v[114:117]
	v_mfma_f32_16x16x32_bf16 v[106:109], v[190:193], v[198:201], v[106:109]
	v_mfma_f32_16x16x32_bf16 v[98:101], v[182:185], v[206:209], v[98:101]
	v_mfma_f32_16x16x32_bf16 v[90:93], v[190:193], v[206:209], v[90:93]
	v_mfma_f32_16x16x32_bf16 v[82:85], v[182:185], v[214:217], v[82:85]
	v_mfma_f32_16x16x32_bf16 v[74:77], v[190:193], v[214:217], v[74:77]
	v_mfma_f32_16x16x32_bf16 v[70:73], v[182:185], v[222:225], v[70:73]
	v_mfma_f32_16x16x32_bf16 v[66:69], v[190:193], v[222:225], v[66:69]
	s_barrier
	s_setprio 0
	s_add_i32 s52, s75, s55
	v_lshl_add_u64 v[154:155], v[154:155], 0, s[12:13]
	s_mov_b32 m0, s52
	ds_read_b128 v[194:197], v165 offset:49152
	ds_read_b128 v[198:201], v165 offset:50176
	ds_read_b128 v[202:205], v165 offset:51200
	ds_read_b128 v[206:209], v165 offset:52224
	ds_read_b128 v[210:213], v165 offset:53248
	ds_read_b128 v[214:217], v165 offset:54272
	ds_read_b128 v[218:221], v165 offset:55296
	ds_read_b128 v[222:225], v165 offset:56320
	global_load_lds_dwordx4 v[154:155], off
	s_add_i32 m0, s52, 0x2000
	s_add_u32 s50, s50, 0x80080
	v_lshl_add_u64 v[154:155], v[166:167], 0, s[12:13]
	s_addc_u32 s51, s51, 0
	s_add_i32 s52, s76, s55
	global_load_lds_dwordx4 v[154:155], off
	v_lshl_add_u64 v[154:155], s[50:51], 0, v[140:141]
	s_mov_b32 m0, s52
	s_nop 0
	global_load_lds_dwordx4 v[154:155], off
	v_lshl_add_u64 v[154:155], s[50:51], 0, v[144:145]
	s_add_i32 m0, s52, 0x2000
	s_nop 0
	global_load_lds_dwordx4 v[154:155], off
	v_lshl_add_u64 v[154:155], v[226:227], 0, s[12:13]
	s_mov_b32 m0, s64
	s_nop 0
	global_load_lds_dwordx4 v[154:155], off
	v_lshl_add_u64 v[154:155], v[228:229], 0, s[12:13]
	s_mov_b32 m0, s65
	s_nop 0
	global_load_lds_dwordx4 v[154:155], off
	s_waitcnt vmcnt(8)
	s_waitcnt lgkmcnt(0)
	s_barrier
	s_setprio 1
	v_mfma_f32_16x16x32_bf16 v[62:65], v[130:133], v[194:197], v[62:65]
	v_mfma_f32_16x16x32_bf16 v[58:61], v[170:173], v[194:197], v[58:61]
	v_mfma_f32_16x16x32_bf16 v[54:57], v[130:133], v[202:205], v[54:57]
	v_mfma_f32_16x16x32_bf16 v[46:49], v[170:173], v[202:205], v[46:49]
	v_mfma_f32_16x16x32_bf16 v[38:41], v[130:133], v[210:213], v[38:41]
	v_mfma_f32_16x16x32_bf16 v[30:33], v[170:173], v[210:213], v[30:33]
	v_mfma_f32_16x16x32_bf16 v[22:25], v[130:133], v[218:221], v[22:25]
	v_mfma_f32_16x16x32_bf16 v[14:17], v[170:173], v[218:221], v[14:17]
	v_mfma_f32_16x16x32_bf16 v[62:65], v[134:137], v[198:201], v[62:65]
	v_mfma_f32_16x16x32_bf16 v[58:61], v[174:177], v[198:201], v[58:61]
	v_mfma_f32_16x16x32_bf16 v[54:57], v[134:137], v[206:209], v[54:57]
	v_mfma_f32_16x16x32_bf16 v[46:49], v[174:177], v[206:209], v[46:49]
	v_mfma_f32_16x16x32_bf16 v[38:41], v[134:137], v[214:217], v[38:41]
	v_mfma_f32_16x16x32_bf16 v[30:33], v[174:177], v[214:217], v[30:33]
	v_mfma_f32_16x16x32_bf16 v[22:25], v[134:137], v[222:225], v[22:25]
	v_mfma_f32_16x16x32_bf16 v[14:17], v[174:177], v[222:225], v[14:17]
	s_setprio 0
	s_setprio 1
	v_mfma_f32_16x16x32_bf16 v[50:53], v[178:181], v[194:197], v[50:53]
	v_mfma_f32_16x16x32_bf16 v[42:45], v[186:189], v[194:197], v[42:45]
	v_mfma_f32_16x16x32_bf16 v[34:37], v[178:181], v[202:205], v[34:37]
	v_mfma_f32_16x16x32_bf16 v[26:29], v[186:189], v[202:205], v[26:29]
	v_mfma_f32_16x16x32_bf16 v[18:21], v[178:181], v[210:213], v[18:21]
	v_mfma_f32_16x16x32_bf16 v[10:13], v[186:189], v[210:213], v[10:13]
	v_mfma_f32_16x16x32_bf16 v[6:9], v[178:181], v[218:221], v[6:9]
	v_mfma_f32_16x16x32_bf16 v[2:5], v[186:189], v[218:221], v[2:5]
	v_mfma_f32_16x16x32_bf16 v[50:53], v[182:185], v[198:201], v[50:53]
	v_mfma_f32_16x16x32_bf16 v[42:45], v[190:193], v[198:201], v[42:45]
	v_mfma_f32_16x16x32_bf16 v[34:37], v[182:185], v[206:209], v[34:37]
	v_mfma_f32_16x16x32_bf16 v[26:29], v[190:193], v[206:209], v[26:29]
	v_mfma_f32_16x16x32_bf16 v[18:21], v[182:185], v[214:217], v[18:21]
	v_mfma_f32_16x16x32_bf16 v[10:13], v[190:193], v[214:217], v[10:13]
	v_mfma_f32_16x16x32_bf16 v[6:9], v[182:185], v[222:225], v[6:9]
	v_mfma_f32_16x16x32_bf16 v[2:5], v[190:193], v[222:225], v[2:5]
	s_barrier
	s_setprio 0
	s_add_i32 s74, s74, 2
	s_add_u32 s48, s48, 0x100
	s_addc_u32 s49, s49, 0
	s_add_u32 s72, s72, 0x100
	s_addc_u32 s73, s73, 0
	s_cmp_gt_u32 s74, 29
	s_cbranch_scc0 .LBB0_117
	s_and_b64 vcc, exec, s[28:29]
	s_cbranch_vccz .LBB0_120
	s_barrier

.LBB0_806:
	ds_read_b128 v[138:141], v144
	ds_read_b128 v[148:151], v144 offset:1024
	ds_read_b128 v[152:155], v144 offset:2048
	ds_read_b128 v[156:159], v144 offset:3072
	ds_read_b128 v[160:163], v145
	ds_read_b128 v[164:167], v145 offset:1024
	ds_read_b128 v[168:171], v145 offset:2048
	ds_read_b128 v[172:175], v145 offset:3072
	s_add_u32 s30, s28, 0x100
	s_addc_u32 s31, s29, 0
	s_add_u32 s34, s54, s28
	s_addc_u32 s35, s55, s29
	s_cmp_eq_u32 s56, 60
	s_cselect_b32 s36, 0, s30
	s_cselect_b32 s37, 0, s31
	s_cselect_b32 s34, s21, s34
	s_cselect_b32 s35, s8, s35
	s_add_u32 s36, s2, s36
	s_addc_u32 s37, s3, s37
	s_mov_b32 m0, s50
	v_lshl_add_u64 v[208:209], v[134:135], 0, s[28:29]
	ds_read_b128 v[176:179], v146
	ds_read_b128 v[180:183], v146 offset:1024
	ds_read_b128 v[184:187], v146 offset:2048
	ds_read_b128 v[188:191], v146 offset:3072
	ds_read_b128 v[192:195], v146 offset:4096
	ds_read_b128 v[196:199], v146 offset:5120
	ds_read_b128 v[200:203], v146 offset:6144
	ds_read_b128 v[204:207], v146 offset:7168
	global_load_lds_dwordx4 v[208:209], off
	v_lshl_add_u64 v[208:209], v[136:137], 0, s[28:29]
	s_mov_b32 m0, s51
	s_nop 0
	global_load_lds_dwordx4 v[208:209], off
	s_waitcnt vmcnt(8)
	s_waitcnt lgkmcnt(0)
	s_barrier
	s_setprio 1
	v_mfma_f32_16x16x32_bf16 v[126:129], v[138:141], v[176:179], v[126:129]
	v_mfma_f32_16x16x32_bf16 v[122:125], v[152:155], v[176:179], v[122:125]
	v_mfma_f32_16x16x32_bf16 v[110:113], v[138:141], v[184:187], v[110:113]
	v_mfma_f32_16x16x32_bf16 v[106:109], v[152:155], v[184:187], v[106:109]
	v_mfma_f32_16x16x32_bf16 v[94:97], v[138:141], v[192:195], v[94:97]
	v_mfma_f32_16x16x32_bf16 v[90:93], v[152:155], v[192:195], v[90:93]
	v_mfma_f32_16x16x32_bf16 v[78:81], v[138:141], v[200:203], v[78:81]
	v_mfma_f32_16x16x32_bf16 v[74:77], v[152:155], v[200:203], v[74:77]
	v_mfma_f32_16x16x32_bf16 v[126:129], v[148:151], v[180:183], v[126:129]
	v_mfma_f32_16x16x32_bf16 v[122:125], v[156:159], v[180:183], v[122:125]
	v_mfma_f32_16x16x32_bf16 v[110:113], v[148:151], v[188:191], v[110:113]
	v_mfma_f32_16x16x32_bf16 v[106:109], v[156:159], v[188:191], v[106:109]
	v_mfma_f32_16x16x32_bf16 v[94:97], v[148:151], v[196:199], v[94:97]
	v_mfma_f32_16x16x32_bf16 v[90:93], v[156:159], v[196:199], v[90:93]
	v_mfma_f32_16x16x32_bf16 v[78:81], v[148:151], v[204:207], v[78:81]
	v_mfma_f32_16x16x32_bf16 v[74:77], v[156:159], v[204:207], v[74:77]
	s_setprio 0
	s_setprio 1
	v_mfma_f32_16x16x32_bf16 v[118:121], v[160:163], v[176:179], v[118:121]
	v_mfma_f32_16x16x32_bf16 v[114:117], v[168:171], v[176:179], v[114:117]
	v_mfma_f32_16x16x32_bf16 v[102:105], v[160:163], v[184:187], v[102:105]
	v_mfma_f32_16x16x32_bf16 v[98:101], v[168:171], v[184:187], v[98:101]
	v_mfma_f32_16x16x32_bf16 v[86:89], v[160:163], v[192:195], v[86:89]
	v_mfma_f32_16x16x32_bf16 v[82:85], v[168:171], v[192:195], v[82:85]
	v_mfma_f32_16x16x32_bf16 v[70:73], v[160:163], v[200:203], v[70:73]
	v_mfma_f32_16x16x32_bf16 v[66:69], v[168:171], v[200:203], v[66:69]
	v_mfma_f32_16x16x32_bf16 v[118:121], v[164:167], v[180:183], v[118:121]
	v_mfma_f32_16x16x32_bf16 v[114:117], v[172:175], v[180:183], v[114:117]
	v_mfma_f32_16x16x32_bf16 v[102:105], v[164:167], v[188:191], v[102:105]
	v_mfma_f32_16x16x32_bf16 v[98:101], v[172:175], v[188:191], v[98:101]
	v_mfma_f32_16x16x32_bf16 v[86:89], v[164:167], v[196:199], v[86:89]
	v_mfma_f32_16x16x32_bf16 v[82:85], v[172:175], v[196:199], v[82:85]
	v_mfma_f32_16x16x32_bf16 v[70:73], v[164:167], v[204:207], v[70:73]
	v_mfma_f32_16x16x32_bf16 v[66:69], v[172:175], v[204:207], v[66:69]
	s_barrier
	s_setprio 0
	s_add_i32 s28, s48, s33
	v_lshl_add_u64 v[208:209], s[34:35], 0, v[132:133]
	s_mov_b32 m0, s28
	ds_read_b128 v[176:179], v146 offset:16384
	ds_read_b128 v[180:183], v146 offset:17408
	ds_read_b128 v[184:187], v146 offset:18432
	ds_read_b128 v[188:191], v146 offset:19456
	ds_read_b128 v[192:195], v146 offset:20480
	ds_read_b128 v[196:199], v146 offset:21504
	ds_read_b128 v[200:203], v146 offset:22528
	ds_read_b128 v[204:207], v146 offset:23552
	global_load_lds_dwordx4 v[208:209], off
	s_add_i32 m0, s28, 0x2000
	s_add_u32 s28, s34, 0x100000
	v_lshl_add_u64 v[210:211], s[34:35], 0, v[130:131]
	s_addc_u32 s29, s35, 0
	s_add_i32 s57, s49, s33
	global_load_lds_dwordx4 v[210:211], off
	v_lshl_add_u64 v[212:213], s[28:29], 0, v[132:133]
	s_mov_b32 m0, s57
	v_lshl_add_u64 v[214:215], s[36:37], 0, v[130:131]
	global_load_lds_dwordx4 v[212:213], off
	v_lshl_add_u64 v[212:213], s[28:29], 0, v[130:131]
	s_add_i32 m0, s57, 0x2000
	s_nop 0
	global_load_lds_dwordx4 v[212:213], off
	v_lshl_add_u64 v[212:213], s[36:37], 0, v[132:133]
	s_mov_b32 m0, s39
	s_nop 0
	global_load_lds_dwordx4 v[212:213], off
	s_mov_b32 m0, s40
	s_nop 0
	global_load_lds_dwordx4 v[214:215], off
	s_waitcnt vmcnt(8)
	s_waitcnt lgkmcnt(0)
	s_barrier
	s_setprio 1
	v_mfma_f32_16x16x32_bf16 v[62:65], v[138:141], v[176:179], v[62:65]
	v_mfma_f32_16x16x32_bf16 v[58:61], v[152:155], v[176:179], v[58:61]
	v_mfma_f32_16x16x32_bf16 v[46:49], v[138:141], v[184:187], v[46:49]
	v_mfma_f32_16x16x32_bf16 v[42:45], v[152:155], v[184:187], v[42:45]
	v_mfma_f32_16x16x32_bf16 v[30:33], v[138:141], v[192:195], v[30:33]
	v_mfma_f32_16x16x32_bf16 v[26:29], v[152:155], v[192:195], v[26:29]
	v_mfma_f32_16x16x32_bf16 v[14:17], v[138:141], v[200:203], v[14:17]
	v_mfma_f32_16x16x32_bf16 v[10:13], v[152:155], v[200:203], v[10:13]
	v_mfma_f32_16x16x32_bf16 v[62:65], v[148:151], v[180:183], v[62:65]
	v_mfma_f32_16x16x32_bf16 v[58:61], v[156:159], v[180:183], v[58:61]
	v_mfma_f32_16x16x32_bf16 v[46:49], v[148:151], v[188:191], v[46:49]
	v_mfma_f32_16x16x32_bf16 v[42:45], v[156:159], v[188:191], v[42:45]
	v_mfma_f32_16x16x32_bf16 v[30:33], v[148:151], v[196:199], v[30:33]
	v_mfma_f32_16x16x32_bf16 v[26:29], v[156:159], v[196:199], v[26:29]
	v_mfma_f32_16x16x32_bf16 v[14:17], v[148:151], v[204:207], v[14:17]
	v_mfma_f32_16x16x32_bf16 v[10:13], v[156:159], v[204:207], v[10:13]
	s_setprio 0
	s_setprio 1
	v_mfma_f32_16x16x32_bf16 v[54:57], v[160:163], v[176:179], v[54:57]
	v_mfma_f32_16x16x32_bf16 v[50:53], v[168:171], v[176:179], v[50:53]
	v_mfma_f32_16x16x32_bf16 v[38:41], v[160:163], v[184:187], v[38:41]
	v_mfma_f32_16x16x32_bf16 v[34:37], v[168:171], v[184:187], v[34:37]
	v_mfma_f32_16x16x32_bf16 v[22:25], v[160:163], v[192:195], v[22:25]
	v_mfma_f32_16x16x32_bf16 v[18:21], v[168:171], v[192:195], v[18:21]
	v_mfma_f32_16x16x32_bf16 v[6:9], v[160:163], v[200:203], v[6:9]
	v_mfma_f32_16x16x32_bf16 v[2:5], v[168:171], v[200:203], v[2:5]
	v_mfma_f32_16x16x32_bf16 v[54:57], v[164:167], v[180:183], v[54:57]
	v_mfma_f32_16x16x32_bf16 v[50:53], v[172:175], v[180:183], v[50:53]
	v_mfma_f32_16x16x32_bf16 v[38:41], v[164:167], v[188:191], v[38:41]
	v_mfma_f32_16x16x32_bf16 v[34:37], v[172:175], v[188:191], v[34:37]
	v_mfma_f32_16x16x32_bf16 v[22:25], v[164:167], v[196:199], v[22:25]
	v_mfma_f32_16x16x32_bf16 v[18:21], v[172:175], v[196:199], v[18:21]
	v_mfma_f32_16x16x32_bf16 v[6:9], v[164:167], v[204:207], v[6:9]
	v_mfma_f32_16x16x32_bf16 v[2:5], v[172:175], v[204:207], v[2:5]
	s_barrier
	s_setprio 0
	s_add_i32 s57, 0, 0x18000
	s_add_i32 s58, 0, 0x1c000
	v_add_u32_e32 v156, s57, v143
	v_add_u32_e32 v172, s58, v143
	ds_read_b128 v[138:141], v156
	ds_read_b128 v[148:151], v156 offset:1024
	ds_read_b128 v[152:155], v156 offset:2048
	ds_read_b128 v[156:159], v156 offset:3072
	ds_read_b128 v[160:163], v172
	ds_read_b128 v[164:167], v172 offset:1024
	ds_read_b128 v[168:171], v172 offset:2048
	ds_read_b128 v[172:175], v172 offset:3072
	s_add_u32 s28, s36, 0x100000
	s_addc_u32 s29, s37, 0
	s_mov_b32 m0, s41
	v_lshl_add_u64 v[216:217], s[28:29], 0, v[132:133]
	ds_read_b128 v[176:179], v146 offset:32768
	ds_read_b128 v[180:183], v146 offset:33792
	ds_read_b128 v[184:187], v146 offset:34816
	ds_read_b128 v[188:191], v146 offset:35840
	ds_read_b128 v[192:195], v146 offset:36864
	ds_read_b128 v[196:199], v146 offset:37888
	ds_read_b128 v[200:203], v146 offset:38912
	ds_read_b128 v[204:207], v146 offset:39936
	global_load_lds_dwordx4 v[216:217], off
	v_lshl_add_u64 v[216:217], s[28:29], 0, v[130:131]
	s_mov_b32 m0, s42
	s_nop 0
	global_load_lds_dwordx4 v[216:217], off
	s_waitcnt vmcnt(8)
	s_waitcnt lgkmcnt(0)
	s_barrier
	s_setprio 1
	v_mfma_f32_16x16x32_bf16 v[126:129], v[138:141], v[176:179], v[126:129]
	v_mfma_f32_16x16x32_bf16 v[122:125], v[152:155], v[176:179], v[122:125]
	v_mfma_f32_16x16x32_bf16 v[110:113], v[138:141], v[184:187], v[110:113]
	v_mfma_f32_16x16x32_bf16 v[106:109], v[152:155], v[184:187], v[106:109]
	v_mfma_f32_16x16x32_bf16 v[94:97], v[138:141], v[192:195], v[94:97]
	v_mfma_f32_16x16x32_bf16 v[90:93], v[152:155], v[192:195], v[90:93]
	v_mfma_f32_16x16x32_bf16 v[78:81], v[138:141], v[200:203], v[78:81]
	v_mfma_f32_16x16x32_bf16 v[74:77], v[152:155], v[200:203], v[74:77]
	v_mfma_f32_16x16x32_bf16 v[126:129], v[148:151], v[180:183], v[126:129]
	v_mfma_f32_16x16x32_bf16 v[122:125], v[156:159], v[180:183], v[122:125]
	v_mfma_f32_16x16x32_bf16 v[110:113], v[148:151], v[188:191], v[110:113]
	v_mfma_f32_16x16x32_bf16 v[106:109], v[156:159], v[188:191], v[106:109]
	v_mfma_f32_16x16x32_bf16 v[94:97], v[148:151], v[196:199], v[94:97]
	v_mfma_f32_16x16x32_bf16 v[90:93], v[156:159], v[196:199], v[90:93]
	v_mfma_f32_16x16x32_bf16 v[78:81], v[148:151], v[204:207], v[78:81]
	v_mfma_f32_16x16x32_bf16 v[74:77], v[156:159], v[204:207], v[74:77]
	s_setprio 0
	s_setprio 1
	v_mfma_f32_16x16x32_bf16 v[118:121], v[160:163], v[176:179], v[118:121]
	v_mfma_f32_16x16x32_bf16 v[114:117], v[168:171], v[176:179], v[114:117]
	v_mfma_f32_16x16x32_bf16 v[102:105], v[160:163], v[184:187], v[102:105]
	v_mfma_f32_16x16x32_bf16 v[98:101], v[168:171], v[184:187], v[98:101]
	v_mfma_f32_16x16x32_bf16 v[86:89], v[160:163], v[192:195], v[86:89]
	v_mfma_f32_16x16x32_bf16 v[82:85], v[168:171], v[192:195], v[82:85]
	v_mfma_f32_16x16x32_bf16 v[70:73], v[160:163], v[200:203], v[70:73]
	v_mfma_f32_16x16x32_bf16 v[66:69], v[168:171], v[200:203], v[66:69]
	v_mfma_f32_16x16x32_bf16 v[118:121], v[164:167], v[180:183], v[118:121]
	v_mfma_f32_16x16x32_bf16 v[114:117], v[172:175], v[180:183], v[114:117]
	v_mfma_f32_16x16x32_bf16 v[102:105], v[164:167], v[188:191], v[102:105]
	v_mfma_f32_16x16x32_bf16 v[98:101], v[172:175], v[188:191], v[98:101]
	v_mfma_f32_16x16x32_bf16 v[86:89], v[164:167], v[196:199], v[86:89]
	v_mfma_f32_16x16x32_bf16 v[82:85], v[172:175], v[196:199], v[82:85]
	v_mfma_f32_16x16x32_bf16 v[70:73], v[164:167], v[204:207], v[70:73]
	v_mfma_f32_16x16x32_bf16 v[66:69], v[172:175], v[204:207], v[66:69]
	s_barrier
	s_setprio 0
	s_add_i32 s28, s57, s33
	v_lshl_add_u64 v[208:209], v[208:209], 0, s[16:17]
	s_mov_b32 m0, s28
	ds_read_b128 v[176:179], v146 offset:49152
	ds_read_b128 v[180:183], v146 offset:50176
	ds_read_b128 v[184:187], v146 offset:51200
	ds_read_b128 v[188:191], v146 offset:52224
	ds_read_b128 v[192:195], v146 offset:53248
	ds_read_b128 v[196:199], v146 offset:54272
	ds_read_b128 v[200:203], v146 offset:55296
	ds_read_b128 v[204:207], v146 offset:56320
	global_load_lds_dwordx4 v[208:209], off
	s_add_i32 m0, s28, 0x2000
	s_add_u32 s28, s34, 0x100080
	v_lshl_add_u64 v[208:209], v[210:211], 0, s[16:17]
	s_addc_u32 s29, s35, 0
	s_add_i32 s34, s58, s33
	global_load_lds_dwordx4 v[208:209], off
	v_lshl_add_u64 v[208:209], s[28:29], 0, v[132:133]
	s_mov_b32 m0, s34
	s_nop 0
	global_load_lds_dwordx4 v[208:209], off
	v_lshl_add_u64 v[208:209], s[28:29], 0, v[130:131]
	s_add_i32 m0, s34, 0x2000
	s_nop 0
	global_load_lds_dwordx4 v[208:209], off
	v_lshl_add_u64 v[208:209], v[212:213], 0, s[16:17]
	s_mov_b32 m0, s45
	s_nop 0
	global_load_lds_dwordx4 v[208:209], off
	v_lshl_add_u64 v[208:209], v[214:215], 0, s[16:17]
	s_mov_b32 m0, s46
	s_nop 0
	global_load_lds_dwordx4 v[208:209], off
	s_waitcnt vmcnt(8)
	s_waitcnt lgkmcnt(0)
	s_barrier
	s_setprio 1
	v_mfma_f32_16x16x32_bf16 v[62:65], v[138:141], v[176:179], v[62:65]
	v_mfma_f32_16x16x32_bf16 v[58:61], v[152:155], v[176:179], v[58:61]
	v_mfma_f32_16x16x32_bf16 v[46:49], v[138:141], v[184:187], v[46:49]
	v_mfma_f32_16x16x32_bf16 v[42:45], v[152:155], v[184:187], v[42:45]
	v_mfma_f32_16x16x32_bf16 v[30:33], v[138:141], v[192:195], v[30:33]
	v_mfma_f32_16x16x32_bf16 v[26:29], v[152:155], v[192:195], v[26:29]
	v_mfma_f32_16x16x32_bf16 v[14:17], v[138:141], v[200:203], v[14:17]
	v_mfma_f32_16x16x32_bf16 v[10:13], v[152:155], v[200:203], v[10:13]
	v_mfma_f32_16x16x32_bf16 v[62:65], v[148:151], v[180:183], v[62:65]
	v_mfma_f32_16x16x32_bf16 v[58:61], v[156:159], v[180:183], v[58:61]
	v_mfma_f32_16x16x32_bf16 v[46:49], v[148:151], v[188:191], v[46:49]
	v_mfma_f32_16x16x32_bf16 v[42:45], v[156:159], v[188:191], v[42:45]
	v_mfma_f32_16x16x32_bf16 v[30:33], v[148:151], v[196:199], v[30:33]
	v_mfma_f32_16x16x32_bf16 v[26:29], v[156:159], v[196:199], v[26:29]
	v_mfma_f32_16x16x32_bf16 v[14:17], v[148:151], v[204:207], v[14:17]
	v_mfma_f32_16x16x32_bf16 v[10:13], v[156:159], v[204:207], v[10:13]
	s_setprio 0
	s_setprio 1
	v_mfma_f32_16x16x32_bf16 v[54:57], v[160:163], v[176:179], v[54:57]
	v_mfma_f32_16x16x32_bf16 v[50:53], v[168:171], v[176:179], v[50:53]
	v_mfma_f32_16x16x32_bf16 v[38:41], v[160:163], v[184:187], v[38:41]
	v_mfma_f32_16x16x32_bf16 v[34:37], v[168:171], v[184:187], v[34:37]
	v_mfma_f32_16x16x32_bf16 v[22:25], v[160:163], v[192:195], v[22:25]
	v_mfma_f32_16x16x32_bf16 v[18:21], v[168:171], v[192:195], v[18:21]
	v_mfma_f32_16x16x32_bf16 v[6:9], v[160:163], v[200:203], v[6:9]
	v_mfma_f32_16x16x32_bf16 v[2:5], v[168:171], v[200:203], v[2:5]
	v_mfma_f32_16x16x32_bf16 v[54:57], v[164:167], v[180:183], v[54:57]
	v_mfma_f32_16x16x32_bf16 v[50:53], v[172:175], v[180:183], v[50:53]
	v_mfma_f32_16x16x32_bf16 v[38:41], v[164:167], v[188:191], v[38:41]
	v_mfma_f32_16x16x32_bf16 v[34:37], v[172:175], v[188:191], v[34:37]
	v_mfma_f32_16x16x32_bf16 v[22:25], v[164:167], v[196:199], v[22:25]
	v_mfma_f32_16x16x32_bf16 v[18:21], v[172:175], v[196:199], v[18:21]
	v_mfma_f32_16x16x32_bf16 v[6:9], v[164:167], v[204:207], v[6:9]
	v_mfma_f32_16x16x32_bf16 v[2:5], v[172:175], v[204:207], v[2:5]
	s_barrier
	s_setprio 0
	s_add_i32 s56, s56, 2
	s_cmp_gt_u32 s56, 61
	s_mov_b64 s[28:29], s[30:31]
	s_cbranch_scc0 .LBB0_806
	s_and_b64 vcc, exec, s[18:19]
	s_cbranch_vccz .LBB0_809
	s_barrier

.LBB0_910:
	ds_read_b128 v[130:133], v157
	ds_read_b128 v[134:137], v157 offset:1024
	ds_read_b128 v[164:167], v157 offset:2048
	ds_read_b128 v[168:171], v157 offset:3072
	ds_read_b128 v[172:175], v159
	ds_read_b128 v[176:179], v159 offset:1024
	ds_read_b128 v[180:183], v159 offset:2048
	ds_read_b128 v[184:187], v159 offset:3072
	s_add_u32 s30, s6, 0xfff80080
	s_addc_u32 s31, s7, -1
	s_cmp_eq_u32 s58, 28
	s_cselect_b32 s35, s13, s31
	s_cselect_b32 s34, s12, s30
	s_cselect_b32 s31, s1, s57
	s_cselect_b32 s30, s55, s56
	s_mov_b32 m0, s49
	v_lshl_add_u64 v[154:155], s[6:7], 0, v[146:147]
	ds_read_b128 v[188:191], v161
	ds_read_b128 v[192:195], v161 offset:1024
	ds_read_b128 v[196:199], v161 offset:2048
	ds_read_b128 v[200:203], v161 offset:3072
	ds_read_b128 v[204:207], v161 offset:4096
	ds_read_b128 v[208:211], v161 offset:5120
	ds_read_b128 v[212:215], v161 offset:6144
	ds_read_b128 v[216:219], v161 offset:7168
	global_load_lds_dwordx4 v[154:155], off
	v_lshl_add_u64 v[154:155], s[6:7], 0, v[148:149]
	s_mov_b32 m0, s50
	s_nop 0
	global_load_lds_dwordx4 v[154:155], off
	s_waitcnt vmcnt(8)
	s_waitcnt lgkmcnt(0)
	s_barrier
	s_setprio 1
	v_mfma_f32_16x16x32_bf16 v[126:129], v[130:133], v[188:191], v[126:129]
	v_mfma_f32_16x16x32_bf16 v[122:125], v[164:167], v[188:191], v[122:125]
	v_mfma_f32_16x16x32_bf16 v[118:121], v[130:133], v[196:199], v[118:121]
	v_mfma_f32_16x16x32_bf16 v[110:113], v[164:167], v[196:199], v[110:113]
	v_mfma_f32_16x16x32_bf16 v[102:105], v[130:133], v[204:207], v[102:105]
	v_mfma_f32_16x16x32_bf16 v[94:97], v[164:167], v[204:207], v[94:97]
	v_mfma_f32_16x16x32_bf16 v[86:89], v[130:133], v[212:215], v[86:89]
	v_mfma_f32_16x16x32_bf16 v[78:81], v[164:167], v[212:215], v[78:81]
	v_mfma_f32_16x16x32_bf16 v[126:129], v[134:137], v[192:195], v[126:129]
	v_mfma_f32_16x16x32_bf16 v[122:125], v[168:171], v[192:195], v[122:125]
	v_mfma_f32_16x16x32_bf16 v[118:121], v[134:137], v[200:203], v[118:121]
	v_mfma_f32_16x16x32_bf16 v[110:113], v[168:171], v[200:203], v[110:113]
	v_mfma_f32_16x16x32_bf16 v[102:105], v[134:137], v[208:211], v[102:105]
	v_mfma_f32_16x16x32_bf16 v[94:97], v[168:171], v[208:211], v[94:97]
	v_mfma_f32_16x16x32_bf16 v[86:89], v[134:137], v[216:219], v[86:89]
	v_mfma_f32_16x16x32_bf16 v[78:81], v[168:171], v[216:219], v[78:81]
	s_setprio 0
	s_setprio 1
	v_mfma_f32_16x16x32_bf16 v[114:117], v[172:175], v[188:191], v[114:117]
	v_mfma_f32_16x16x32_bf16 v[106:109], v[180:183], v[188:191], v[106:109]
	v_mfma_f32_16x16x32_bf16 v[98:101], v[172:175], v[196:199], v[98:101]
	v_mfma_f32_16x16x32_bf16 v[90:93], v[180:183], v[196:199], v[90:93]
	v_mfma_f32_16x16x32_bf16 v[82:85], v[172:175], v[204:207], v[82:85]
	v_mfma_f32_16x16x32_bf16 v[74:77], v[180:183], v[204:207], v[74:77]
	v_mfma_f32_16x16x32_bf16 v[70:73], v[172:175], v[212:215], v[70:73]
	v_mfma_f32_16x16x32_bf16 v[66:69], v[180:183], v[212:215], v[66:69]
	v_mfma_f32_16x16x32_bf16 v[114:117], v[176:179], v[192:195], v[114:117]
	v_mfma_f32_16x16x32_bf16 v[106:109], v[184:187], v[192:195], v[106:109]
	v_mfma_f32_16x16x32_bf16 v[98:101], v[176:179], v[200:203], v[98:101]
	v_mfma_f32_16x16x32_bf16 v[90:93], v[184:187], v[200:203], v[90:93]
	v_mfma_f32_16x16x32_bf16 v[82:85], v[176:179], v[208:211], v[82:85]
	v_mfma_f32_16x16x32_bf16 v[74:77], v[184:187], v[208:211], v[74:77]
	v_mfma_f32_16x16x32_bf16 v[70:73], v[176:179], v[216:219], v[70:73]
	v_mfma_f32_16x16x32_bf16 v[66:69], v[184:187], v[216:219], v[66:69]
	s_barrier
	s_setprio 0
	s_mov_b32 m0, s51
	v_lshl_add_u64 v[154:155], s[30:31], 0, v[142:143]
	ds_read_b128 v[188:191], v161 offset:16384
	ds_read_b128 v[192:195], v161 offset:17408
	ds_read_b128 v[196:199], v161 offset:18432
	ds_read_b128 v[200:203], v161 offset:19456
	ds_read_b128 v[204:207], v161 offset:20480
	ds_read_b128 v[208:211], v161 offset:21504
	ds_read_b128 v[212:215], v161 offset:22528
	ds_read_b128 v[216:219], v161 offset:23552
	global_load_lds_dwordx4 v[154:155], off
	s_add_i32 m0, s51, 0x2000
	s_add_u32 s60, s30, 0x80000
	v_lshl_add_u64 v[220:221], s[30:31], 0, v[138:139]
	s_addc_u32 s61, s31, 0
	s_add_i32 s59, s48, s36
	global_load_lds_dwordx4 v[220:221], off
	v_lshl_add_u64 v[222:223], s[60:61], 0, v[142:143]
	s_mov_b32 m0, s59
	v_lshl_add_u64 v[224:225], s[34:35], 0, v[140:141]
	global_load_lds_dwordx4 v[222:223], off
	v_lshl_add_u64 v[222:223], s[60:61], 0, v[138:139]
	s_add_i32 m0, s59, 0x2000
	s_nop 0
	global_load_lds_dwordx4 v[222:223], off
	v_lshl_add_u64 v[222:223], s[34:35], 0, v[144:145]
	s_mov_b32 m0, s37
	s_nop 0
	global_load_lds_dwordx4 v[222:223], off
	s_mov_b32 m0, s40
	s_nop 0
	global_load_lds_dwordx4 v[224:225], off
	s_waitcnt vmcnt(8)
	s_waitcnt lgkmcnt(0)
	s_barrier
	s_setprio 1
	v_mfma_f32_16x16x32_bf16 v[62:65], v[130:133], v[188:191], v[62:65]
	v_mfma_f32_16x16x32_bf16 v[58:61], v[164:167], v[188:191], v[58:61]
	v_mfma_f32_16x16x32_bf16 v[54:57], v[130:133], v[196:199], v[54:57]
	v_mfma_f32_16x16x32_bf16 v[46:49], v[164:167], v[196:199], v[46:49]
	v_mfma_f32_16x16x32_bf16 v[38:41], v[130:133], v[204:207], v[38:41]
	v_mfma_f32_16x16x32_bf16 v[30:33], v[164:167], v[204:207], v[30:33]
	v_mfma_f32_16x16x32_bf16 v[22:25], v[130:133], v[212:215], v[22:25]
	v_mfma_f32_16x16x32_bf16 v[14:17], v[164:167], v[212:215], v[14:17]
	v_mfma_f32_16x16x32_bf16 v[62:65], v[134:137], v[192:195], v[62:65]
	v_mfma_f32_16x16x32_bf16 v[58:61], v[168:171], v[192:195], v[58:61]
	v_mfma_f32_16x16x32_bf16 v[54:57], v[134:137], v[200:203], v[54:57]
	v_mfma_f32_16x16x32_bf16 v[46:49], v[168:171], v[200:203], v[46:49]
	v_mfma_f32_16x16x32_bf16 v[38:41], v[134:137], v[208:211], v[38:41]
	v_mfma_f32_16x16x32_bf16 v[30:33], v[168:171], v[208:211], v[30:33]
	v_mfma_f32_16x16x32_bf16 v[22:25], v[134:137], v[216:219], v[22:25]
	v_mfma_f32_16x16x32_bf16 v[14:17], v[168:171], v[216:219], v[14:17]
	s_setprio 0
	s_setprio 1
	v_mfma_f32_16x16x32_bf16 v[50:53], v[172:175], v[188:191], v[50:53]
	v_mfma_f32_16x16x32_bf16 v[42:45], v[180:183], v[188:191], v[42:45]
	v_mfma_f32_16x16x32_bf16 v[34:37], v[172:175], v[196:199], v[34:37]
	v_mfma_f32_16x16x32_bf16 v[26:29], v[180:183], v[196:199], v[26:29]
	v_mfma_f32_16x16x32_bf16 v[18:21], v[172:175], v[204:207], v[18:21]
	v_mfma_f32_16x16x32_bf16 v[10:13], v[180:183], v[204:207], v[10:13]
	v_mfma_f32_16x16x32_bf16 v[6:9], v[172:175], v[212:215], v[6:9]
	v_mfma_f32_16x16x32_bf16 v[2:5], v[180:183], v[212:215], v[2:5]
	v_mfma_f32_16x16x32_bf16 v[50:53], v[176:179], v[192:195], v[50:53]
	v_mfma_f32_16x16x32_bf16 v[42:45], v[184:187], v[192:195], v[42:45]
	v_mfma_f32_16x16x32_bf16 v[34:37], v[176:179], v[200:203], v[34:37]
	v_mfma_f32_16x16x32_bf16 v[26:29], v[184:187], v[200:203], v[26:29]
	v_mfma_f32_16x16x32_bf16 v[18:21], v[176:179], v[208:211], v[18:21]
	v_mfma_f32_16x16x32_bf16 v[10:13], v[184:187], v[208:211], v[10:13]
	v_mfma_f32_16x16x32_bf16 v[6:9], v[176:179], v[216:219], v[6:9]
	v_mfma_f32_16x16x32_bf16 v[2:5], v[184:187], v[216:219], v[2:5]
	s_barrier
	s_setprio 0
	s_add_i32 s59, 0, 0x18000
	v_add_u32_e32 v150, s59, v153
	s_add_i32 s60, 0, 0x1c000
	ds_read_b128 v[130:133], v150
	ds_read_b128 v[134:137], v150 offset:1024
	ds_read_b128 v[164:167], v150 offset:2048
	ds_read_b128 v[168:171], v150 offset:3072
	v_add_u32_e32 v150, s60, v153
	ds_read_b128 v[172:175], v150
	ds_read_b128 v[176:179], v150 offset:1024
	ds_read_b128 v[180:183], v150 offset:2048
	ds_read_b128 v[184:187], v150 offset:3072
	s_add_u32 s34, s34, 0x80000
	s_addc_u32 s35, s35, 0
	s_mov_b32 m0, s41
	v_lshl_add_u64 v[226:227], s[34:35], 0, v[144:145]
	ds_read_b128 v[188:191], v161 offset:32768
	ds_read_b128 v[192:195], v161 offset:33792
	ds_read_b128 v[196:199], v161 offset:34816
	ds_read_b128 v[200:203], v161 offset:35840
	ds_read_b128 v[204:207], v161 offset:36864
	ds_read_b128 v[208:211], v161 offset:37888
	ds_read_b128 v[212:215], v161 offset:38912
	ds_read_b128 v[216:219], v161 offset:39936
	global_load_lds_dwordx4 v[226:227], off
	v_lshl_add_u64 v[226:227], s[34:35], 0, v[140:141]
	s_mov_b32 m0, s42
	s_nop 0
	global_load_lds_dwordx4 v[226:227], off
	s_waitcnt vmcnt(8)
	s_waitcnt lgkmcnt(0)
	s_barrier
	s_setprio 1
	v_mfma_f32_16x16x32_bf16 v[126:129], v[130:133], v[188:191], v[126:129]
	v_mfma_f32_16x16x32_bf16 v[122:125], v[164:167], v[188:191], v[122:125]
	v_mfma_f32_16x16x32_bf16 v[118:121], v[130:133], v[196:199], v[118:121]
	v_mfma_f32_16x16x32_bf16 v[110:113], v[164:167], v[196:199], v[110:113]
	v_mfma_f32_16x16x32_bf16 v[102:105], v[130:133], v[204:207], v[102:105]
	v_mfma_f32_16x16x32_bf16 v[94:97], v[164:167], v[204:207], v[94:97]
	v_mfma_f32_16x16x32_bf16 v[86:89], v[130:133], v[212:215], v[86:89]
	v_mfma_f32_16x16x32_bf16 v[78:81], v[164:167], v[212:215], v[78:81]
	v_mfma_f32_16x16x32_bf16 v[126:129], v[134:137], v[192:195], v[126:129]
	v_mfma_f32_16x16x32_bf16 v[122:125], v[168:171], v[192:195], v[122:125]
	v_mfma_f32_16x16x32_bf16 v[118:121], v[134:137], v[200:203], v[118:121]
	v_mfma_f32_16x16x32_bf16 v[110:113], v[168:171], v[200:203], v[110:113]
	v_mfma_f32_16x16x32_bf16 v[102:105], v[134:137], v[208:211], v[102:105]
	v_mfma_f32_16x16x32_bf16 v[94:97], v[168:171], v[208:211], v[94:97]
	v_mfma_f32_16x16x32_bf16 v[86:89], v[134:137], v[216:219], v[86:89]
	v_mfma_f32_16x16x32_bf16 v[78:81], v[168:171], v[216:219], v[78:81]
	s_setprio 0
	s_setprio 1
	v_mfma_f32_16x16x32_bf16 v[114:117], v[172:175], v[188:191], v[114:117]
	v_mfma_f32_16x16x32_bf16 v[106:109], v[180:183], v[188:191], v[106:109]
	v_mfma_f32_16x16x32_bf16 v[98:101], v[172:175], v[196:199], v[98:101]
	v_mfma_f32_16x16x32_bf16 v[90:93], v[180:183], v[196:199], v[90:93]
	v_mfma_f32_16x16x32_bf16 v[82:85], v[172:175], v[204:207], v[82:85]
	v_mfma_f32_16x16x32_bf16 v[74:77], v[180:183], v[204:207], v[74:77]
	v_mfma_f32_16x16x32_bf16 v[70:73], v[172:175], v[212:215], v[70:73]
	v_mfma_f32_16x16x32_bf16 v[66:69], v[180:183], v[212:215], v[66:69]
	v_mfma_f32_16x16x32_bf16 v[114:117], v[176:179], v[192:195], v[114:117]
	v_mfma_f32_16x16x32_bf16 v[106:109], v[184:187], v[192:195], v[106:109]
	v_mfma_f32_16x16x32_bf16 v[98:101], v[176:179], v[200:203], v[98:101]
	v_mfma_f32_16x16x32_bf16 v[90:93], v[184:187], v[200:203], v[90:93]
	v_mfma_f32_16x16x32_bf16 v[82:85], v[176:179], v[208:211], v[82:85]
	v_mfma_f32_16x16x32_bf16 v[74:77], v[184:187], v[208:211], v[74:77]
	v_mfma_f32_16x16x32_bf16 v[70:73], v[176:179], v[216:219], v[70:73]
	v_mfma_f32_16x16x32_bf16 v[66:69], v[184:187], v[216:219], v[66:69]
	s_barrier
	s_setprio 0
	s_add_i32 s34, s59, s36
	v_lshl_add_u64 v[154:155], v[154:155], 0, s[16:17]
	s_mov_b32 m0, s34
	ds_read_b128 v[188:191], v161 offset:49152
	ds_read_b128 v[192:195], v161 offset:50176
	ds_read_b128 v[196:199], v161 offset:51200
	ds_read_b128 v[200:203], v161 offset:52224
	ds_read_b128 v[204:207], v161 offset:53248
	ds_read_b128 v[208:211], v161 offset:54272
	ds_read_b128 v[212:215], v161 offset:55296
	ds_read_b128 v[216:219], v161 offset:56320
	global_load_lds_dwordx4 v[154:155], off
	s_add_i32 m0, s34, 0x2000
	s_add_u32 s30, s30, 0x80080
	v_lshl_add_u64 v[154:155], v[220:221], 0, s[16:17]
	s_addc_u32 s31, s31, 0
	s_add_i32 s34, s60, s36
	global_load_lds_dwordx4 v[154:155], off
	v_lshl_add_u64 v[154:155], s[30:31], 0, v[142:143]
	s_mov_b32 m0, s34
	s_nop 0
	global_load_lds_dwordx4 v[154:155], off
	v_lshl_add_u64 v[154:155], s[30:31], 0, v[138:139]
	s_add_i32 m0, s34, 0x2000
	s_nop 0
	global_load_lds_dwordx4 v[154:155], off
	v_lshl_add_u64 v[154:155], v[222:223], 0, s[16:17]
	s_mov_b32 m0, s45
	s_nop 0
	global_load_lds_dwordx4 v[154:155], off
	v_lshl_add_u64 v[154:155], v[224:225], 0, s[16:17]
	s_mov_b32 m0, s46
	s_nop 0
	global_load_lds_dwordx4 v[154:155], off
	s_waitcnt vmcnt(8)
	s_waitcnt lgkmcnt(0)
	s_barrier
	s_setprio 1
	v_mfma_f32_16x16x32_bf16 v[62:65], v[130:133], v[188:191], v[62:65]
	v_mfma_f32_16x16x32_bf16 v[58:61], v[164:167], v[188:191], v[58:61]
	v_mfma_f32_16x16x32_bf16 v[54:57], v[130:133], v[196:199], v[54:57]
	v_mfma_f32_16x16x32_bf16 v[46:49], v[164:167], v[196:199], v[46:49]
	v_mfma_f32_16x16x32_bf16 v[38:41], v[130:133], v[204:207], v[38:41]
	v_mfma_f32_16x16x32_bf16 v[30:33], v[164:167], v[204:207], v[30:33]
	v_mfma_f32_16x16x32_bf16 v[22:25], v[130:133], v[212:215], v[22:25]
	v_mfma_f32_16x16x32_bf16 v[14:17], v[164:167], v[212:215], v[14:17]
	v_mfma_f32_16x16x32_bf16 v[62:65], v[134:137], v[192:195], v[62:65]
	v_mfma_f32_16x16x32_bf16 v[58:61], v[168:171], v[192:195], v[58:61]
	v_mfma_f32_16x16x32_bf16 v[54:57], v[134:137], v[200:203], v[54:57]
	v_mfma_f32_16x16x32_bf16 v[46:49], v[168:171], v[200:203], v[46:49]
	v_mfma_f32_16x16x32_bf16 v[38:41], v[134:137], v[208:211], v[38:41]
	v_mfma_f32_16x16x32_bf16 v[30:33], v[168:171], v[208:211], v[30:33]
	v_mfma_f32_16x16x32_bf16 v[22:25], v[134:137], v[216:219], v[22:25]
	v_mfma_f32_16x16x32_bf16 v[14:17], v[168:171], v[216:219], v[14:17]
	s_setprio 0
	s_setprio 1
	v_mfma_f32_16x16x32_bf16 v[50:53], v[172:175], v[188:191], v[50:53]
	v_mfma_f32_16x16x32_bf16 v[42:45], v[180:183], v[188:191], v[42:45]
	v_mfma_f32_16x16x32_bf16 v[34:37], v[172:175], v[196:199], v[34:37]
	v_mfma_f32_16x16x32_bf16 v[26:29], v[180:183], v[196:199], v[26:29]
	v_mfma_f32_16x16x32_bf16 v[18:21], v[172:175], v[204:207], v[18:21]
	v_mfma_f32_16x16x32_bf16 v[10:13], v[180:183], v[204:207], v[10:13]
	v_mfma_f32_16x16x32_bf16 v[6:9], v[172:175], v[212:215], v[6:9]
	v_mfma_f32_16x16x32_bf16 v[2:5], v[180:183], v[212:215], v[2:5]
	v_mfma_f32_16x16x32_bf16 v[50:53], v[176:179], v[192:195], v[50:53]
	v_mfma_f32_16x16x32_bf16 v[42:45], v[184:187], v[192:195], v[42:45]
	v_mfma_f32_16x16x32_bf16 v[34:37], v[176:179], v[200:203], v[34:37]
	v_mfma_f32_16x16x32_bf16 v[26:29], v[184:187], v[200:203], v[26:29]
	v_mfma_f32_16x16x32_bf16 v[18:21], v[176:179], v[208:211], v[18:21]
	v_mfma_f32_16x16x32_bf16 v[10:13], v[184:187], v[208:211], v[10:13]
	v_mfma_f32_16x16x32_bf16 v[6:9], v[176:179], v[216:219], v[6:9]
	v_mfma_f32_16x16x32_bf16 v[2:5], v[184:187], v[216:219], v[2:5]
	s_barrier
	s_setprio 0
	s_add_i32 s58, s58, 2
	s_add_u32 s6, s6, 0x100
	s_addc_u32 s7, s7, 0
	s_add_u32 s56, s56, 0x100
	s_addc_u32 s57, s57, 0
	s_cmp_gt_u32 s58, 29
	s_cbranch_scc0 .LBB0_910
	s_and_b64 vcc, exec, s[18:19]
	s_cbranch_vccz .LBB0_913
	s_barrier

.LBB0_1112:
	ds_read_b128 v[138:141], v143
	ds_read_b128 v[150:153], v143 offset:1024
	ds_read_b128 v[154:157], v143 offset:2048
	ds_read_b128 v[158:161], v143 offset:3072
	ds_read_b128 v[162:165], v144
	ds_read_b128 v[166:169], v144 offset:1024
	ds_read_b128 v[170:173], v144 offset:2048
	ds_read_b128 v[174:177], v144 offset:3072
	s_add_u32 s22, s20, 0x100
	s_addc_u32 s23, s21, 0
	s_add_u32 s24, s0, s20
	s_addc_u32 s25, s1, s21
	s_cmpk_eq_i32 s6, 0x54
	s_cselect_b32 s26, 0, s22
	s_cselect_b32 s27, 0, s23
	s_cselect_b32 s24, s16, s24
	s_cselect_b32 s25, s17, s25
	s_add_u32 s26, s2, s26
	s_addc_u32 s27, s3, s27
	s_mov_b32 m0, s41
	v_lshl_add_u64 v[210:211], v[134:135], 0, s[20:21]
	ds_read_b128 v[178:181], v145
	ds_read_b128 v[182:185], v145 offset:1024
	ds_read_b128 v[186:189], v145 offset:2048
	ds_read_b128 v[190:193], v145 offset:3072
	ds_read_b128 v[194:197], v145 offset:4096
	ds_read_b128 v[198:201], v145 offset:5120
	ds_read_b128 v[202:205], v145 offset:6144
	ds_read_b128 v[206:209], v145 offset:7168
	global_load_lds_dwordx4 v[210:211], off
	v_lshl_add_u64 v[210:211], v[136:137], 0, s[20:21]
	s_mov_b32 m0, s42
	s_nop 0
	global_load_lds_dwordx4 v[210:211], off
	s_waitcnt vmcnt(8)
	s_waitcnt lgkmcnt(0)
	s_barrier
	s_setprio 1
	v_mfma_f32_16x16x32_bf16 v[126:129], v[138:141], v[178:181], v[126:129]
	v_mfma_f32_16x16x32_bf16 v[122:125], v[154:157], v[178:181], v[122:125]
	v_mfma_f32_16x16x32_bf16 v[110:113], v[138:141], v[186:189], v[110:113]
	v_mfma_f32_16x16x32_bf16 v[106:109], v[154:157], v[186:189], v[106:109]
	v_mfma_f32_16x16x32_bf16 v[94:97], v[138:141], v[194:197], v[94:97]
	v_mfma_f32_16x16x32_bf16 v[90:93], v[154:157], v[194:197], v[90:93]
	v_mfma_f32_16x16x32_bf16 v[78:81], v[138:141], v[202:205], v[78:81]
	v_mfma_f32_16x16x32_bf16 v[74:77], v[154:157], v[202:205], v[74:77]
	v_mfma_f32_16x16x32_bf16 v[126:129], v[150:153], v[182:185], v[126:129]
	v_mfma_f32_16x16x32_bf16 v[122:125], v[158:161], v[182:185], v[122:125]
	v_mfma_f32_16x16x32_bf16 v[110:113], v[150:153], v[190:193], v[110:113]
	v_mfma_f32_16x16x32_bf16 v[106:109], v[158:161], v[190:193], v[106:109]
	v_mfma_f32_16x16x32_bf16 v[94:97], v[150:153], v[198:201], v[94:97]
	v_mfma_f32_16x16x32_bf16 v[90:93], v[158:161], v[198:201], v[90:93]
	v_mfma_f32_16x16x32_bf16 v[78:81], v[150:153], v[206:209], v[78:81]
	v_mfma_f32_16x16x32_bf16 v[74:77], v[158:161], v[206:209], v[74:77]
	s_setprio 0
	s_setprio 1
	v_mfma_f32_16x16x32_bf16 v[118:121], v[162:165], v[178:181], v[118:121]
	v_mfma_f32_16x16x32_bf16 v[114:117], v[170:173], v[178:181], v[114:117]
	v_mfma_f32_16x16x32_bf16 v[102:105], v[162:165], v[186:189], v[102:105]
	v_mfma_f32_16x16x32_bf16 v[98:101], v[170:173], v[186:189], v[98:101]
	v_mfma_f32_16x16x32_bf16 v[86:89], v[162:165], v[194:197], v[86:89]
	v_mfma_f32_16x16x32_bf16 v[82:85], v[170:173], v[194:197], v[82:85]
	v_mfma_f32_16x16x32_bf16 v[70:73], v[162:165], v[202:205], v[70:73]
	v_mfma_f32_16x16x32_bf16 v[66:69], v[170:173], v[202:205], v[66:69]
	v_mfma_f32_16x16x32_bf16 v[118:121], v[166:169], v[182:185], v[118:121]
	v_mfma_f32_16x16x32_bf16 v[114:117], v[174:177], v[182:185], v[114:117]
	v_mfma_f32_16x16x32_bf16 v[102:105], v[166:169], v[190:193], v[102:105]
	v_mfma_f32_16x16x32_bf16 v[98:101], v[174:177], v[190:193], v[98:101]
	v_mfma_f32_16x16x32_bf16 v[86:89], v[166:169], v[198:201], v[86:89]
	v_mfma_f32_16x16x32_bf16 v[82:85], v[174:177], v[198:201], v[82:85]
	v_mfma_f32_16x16x32_bf16 v[70:73], v[166:169], v[206:209], v[70:73]
	v_mfma_f32_16x16x32_bf16 v[66:69], v[174:177], v[206:209], v[66:69]
	s_barrier
	s_setprio 0
	s_mov_b32 m0, s43
	v_lshl_add_u64 v[210:211], s[24:25], 0, v[132:133]
	s_add_u32 s20, s24, 0x160000
	ds_read_b128 v[178:181], v145 offset:16384
	ds_read_b128 v[182:185], v145 offset:17408
	ds_read_b128 v[186:189], v145 offset:18432
	ds_read_b128 v[190:193], v145 offset:19456
	ds_read_b128 v[194:197], v145 offset:20480
	ds_read_b128 v[198:201], v145 offset:21504
	ds_read_b128 v[202:205], v145 offset:22528
	ds_read_b128 v[206:209], v145 offset:23552
	global_load_lds_dwordx4 v[210:211], off
	v_lshl_add_u64 v[212:213], s[24:25], 0, v[130:131]
	s_mov_b32 m0, s44
	s_addc_u32 s21, s25, 0
	global_load_lds_dwordx4 v[212:213], off
	v_lshl_add_u64 v[214:215], s[20:21], 0, v[132:133]
	s_mov_b32 m0, s45
	v_lshl_add_u64 v[216:217], s[26:27], 0, v[130:131]
	global_load_lds_dwordx4 v[214:215], off
	v_lshl_add_u64 v[214:215], s[20:21], 0, v[130:131]
	s_mov_b32 m0, s46
	s_nop 0
	global_load_lds_dwordx4 v[214:215], off
	v_lshl_add_u64 v[214:215], s[26:27], 0, v[132:133]
	s_mov_b32 m0, s30
	s_nop 0
	global_load_lds_dwordx4 v[214:215], off
	s_mov_b32 m0, s31
	s_nop 0
	global_load_lds_dwordx4 v[216:217], off
	s_waitcnt vmcnt(8)
	s_waitcnt lgkmcnt(0)
	s_barrier
	s_setprio 1
	v_mfma_f32_16x16x32_bf16 v[62:65], v[138:141], v[178:181], v[62:65]
	v_mfma_f32_16x16x32_bf16 v[58:61], v[154:157], v[178:181], v[58:61]
	v_mfma_f32_16x16x32_bf16 v[46:49], v[138:141], v[186:189], v[46:49]
	v_mfma_f32_16x16x32_bf16 v[42:45], v[154:157], v[186:189], v[42:45]
	v_mfma_f32_16x16x32_bf16 v[30:33], v[138:141], v[194:197], v[30:33]
	v_mfma_f32_16x16x32_bf16 v[26:29], v[154:157], v[194:197], v[26:29]
	v_mfma_f32_16x16x32_bf16 v[14:17], v[138:141], v[202:205], v[14:17]
	v_mfma_f32_16x16x32_bf16 v[10:13], v[154:157], v[202:205], v[10:13]
	v_mfma_f32_16x16x32_bf16 v[62:65], v[150:153], v[182:185], v[62:65]
	v_mfma_f32_16x16x32_bf16 v[58:61], v[158:161], v[182:185], v[58:61]
	v_mfma_f32_16x16x32_bf16 v[46:49], v[150:153], v[190:193], v[46:49]
	v_mfma_f32_16x16x32_bf16 v[42:45], v[158:161], v[190:193], v[42:45]
	v_mfma_f32_16x16x32_bf16 v[30:33], v[150:153], v[198:201], v[30:33]
	v_mfma_f32_16x16x32_bf16 v[26:29], v[158:161], v[198:201], v[26:29]
	v_mfma_f32_16x16x32_bf16 v[14:17], v[150:153], v[206:209], v[14:17]
	v_mfma_f32_16x16x32_bf16 v[10:13], v[158:161], v[206:209], v[10:13]
	s_setprio 0
	s_setprio 1
	v_mfma_f32_16x16x32_bf16 v[54:57], v[162:165], v[178:181], v[54:57]
	v_mfma_f32_16x16x32_bf16 v[50:53], v[170:173], v[178:181], v[50:53]
	v_mfma_f32_16x16x32_bf16 v[38:41], v[162:165], v[186:189], v[38:41]
	v_mfma_f32_16x16x32_bf16 v[34:37], v[170:173], v[186:189], v[34:37]
	v_mfma_f32_16x16x32_bf16 v[22:25], v[162:165], v[194:197], v[22:25]
	v_mfma_f32_16x16x32_bf16 v[18:21], v[170:173], v[194:197], v[18:21]
	v_mfma_f32_16x16x32_bf16 v[6:9], v[162:165], v[202:205], v[6:9]
	v_mfma_f32_16x16x32_bf16 v[2:5], v[170:173], v[202:205], v[2:5]
	v_mfma_f32_16x16x32_bf16 v[54:57], v[166:169], v[182:185], v[54:57]
	v_mfma_f32_16x16x32_bf16 v[50:53], v[174:177], v[182:185], v[50:53]
	v_mfma_f32_16x16x32_bf16 v[38:41], v[166:169], v[190:193], v[38:41]
	v_mfma_f32_16x16x32_bf16 v[34:37], v[174:177], v[190:193], v[34:37]
	v_mfma_f32_16x16x32_bf16 v[22:25], v[166:169], v[198:201], v[22:25]
	v_mfma_f32_16x16x32_bf16 v[18:21], v[174:177], v[198:201], v[18:21]
	v_mfma_f32_16x16x32_bf16 v[6:9], v[166:169], v[206:209], v[6:9]
	v_mfma_f32_16x16x32_bf16 v[2:5], v[174:177], v[206:209], v[2:5]
	s_barrier
	s_setprio 0
	ds_read_b128 v[138:141], v147
	ds_read_b128 v[150:153], v147 offset:1024
	ds_read_b128 v[154:157], v147 offset:2048
	ds_read_b128 v[158:161], v147 offset:3072
	ds_read_b128 v[162:165], v148
	ds_read_b128 v[166:169], v148 offset:1024
	ds_read_b128 v[170:173], v148 offset:2048
	ds_read_b128 v[174:177], v148 offset:3072
	s_add_u32 s20, s26, 0x160000
	s_addc_u32 s21, s27, 0
	s_mov_b32 m0, s33
	v_lshl_add_u64 v[218:219], s[20:21], 0, v[132:133]
	ds_read_b128 v[178:181], v145 offset:32768
	ds_read_b128 v[182:185], v145 offset:33792
	ds_read_b128 v[186:189], v145 offset:34816
	ds_read_b128 v[190:193], v145 offset:35840
	ds_read_b128 v[194:197], v145 offset:36864
	ds_read_b128 v[198:201], v145 offset:37888
	ds_read_b128 v[202:205], v145 offset:38912
	ds_read_b128 v[206:209], v145 offset:39936
	global_load_lds_dwordx4 v[218:219], off
	v_lshl_add_u64 v[218:219], s[20:21], 0, v[130:131]
	s_mov_b32 m0, s34
	s_nop 0
	global_load_lds_dwordx4 v[218:219], off
	s_waitcnt vmcnt(8)
	s_waitcnt lgkmcnt(0)
	s_barrier
	s_setprio 1
	v_mfma_f32_16x16x32_bf16 v[126:129], v[138:141], v[178:181], v[126:129]
	v_mfma_f32_16x16x32_bf16 v[122:125], v[154:157], v[178:181], v[122:125]
	v_mfma_f32_16x16x32_bf16 v[110:113], v[138:141], v[186:189], v[110:113]
	v_mfma_f32_16x16x32_bf16 v[106:109], v[154:157], v[186:189], v[106:109]
	v_mfma_f32_16x16x32_bf16 v[94:97], v[138:141], v[194:197], v[94:97]
	v_mfma_f32_16x16x32_bf16 v[90:93], v[154:157], v[194:197], v[90:93]
	v_mfma_f32_16x16x32_bf16 v[78:81], v[138:141], v[202:205], v[78:81]
	v_mfma_f32_16x16x32_bf16 v[74:77], v[154:157], v[202:205], v[74:77]
	v_mfma_f32_16x16x32_bf16 v[126:129], v[150:153], v[182:185], v[126:129]
	v_mfma_f32_16x16x32_bf16 v[122:125], v[158:161], v[182:185], v[122:125]
	v_mfma_f32_16x16x32_bf16 v[110:113], v[150:153], v[190:193], v[110:113]
	v_mfma_f32_16x16x32_bf16 v[106:109], v[158:161], v[190:193], v[106:109]
	v_mfma_f32_16x16x32_bf16 v[94:97], v[150:153], v[198:201], v[94:97]
	v_mfma_f32_16x16x32_bf16 v[90:93], v[158:161], v[198:201], v[90:93]
	v_mfma_f32_16x16x32_bf16 v[78:81], v[150:153], v[206:209], v[78:81]
	v_mfma_f32_16x16x32_bf16 v[74:77], v[158:161], v[206:209], v[74:77]
	s_setprio 0
	s_setprio 1
	v_mfma_f32_16x16x32_bf16 v[118:121], v[162:165], v[178:181], v[118:121]
	v_mfma_f32_16x16x32_bf16 v[114:117], v[170:173], v[178:181], v[114:117]
	v_mfma_f32_16x16x32_bf16 v[102:105], v[162:165], v[186:189], v[102:105]
	v_mfma_f32_16x16x32_bf16 v[98:101], v[170:173], v[186:189], v[98:101]
	v_mfma_f32_16x16x32_bf16 v[86:89], v[162:165], v[194:197], v[86:89]
	v_mfma_f32_16x16x32_bf16 v[82:85], v[170:173], v[194:197], v[82:85]
	v_mfma_f32_16x16x32_bf16 v[70:73], v[162:165], v[202:205], v[70:73]
	v_mfma_f32_16x16x32_bf16 v[66:69], v[170:173], v[202:205], v[66:69]
	v_mfma_f32_16x16x32_bf16 v[118:121], v[166:169], v[182:185], v[118:121]
	v_mfma_f32_16x16x32_bf16 v[114:117], v[174:177], v[182:185], v[114:117]
	v_mfma_f32_16x16x32_bf16 v[102:105], v[166:169], v[190:193], v[102:105]
	v_mfma_f32_16x16x32_bf16 v[98:101], v[174:177], v[190:193], v[98:101]
	v_mfma_f32_16x16x32_bf16 v[86:89], v[166:169], v[198:201], v[86:89]
	v_mfma_f32_16x16x32_bf16 v[82:85], v[174:177], v[198:201], v[82:85]
	v_mfma_f32_16x16x32_bf16 v[70:73], v[166:169], v[206:209], v[70:73]
	v_mfma_f32_16x16x32_bf16 v[66:69], v[174:177], v[206:209], v[66:69]
	s_barrier
	s_setprio 0
	s_mov_b32 m0, s47
	v_lshl_add_u64 v[210:211], v[210:211], 0, s[12:13]
	s_add_u32 s20, s24, 0x160080
	ds_read_b128 v[178:181], v145 offset:49152
	ds_read_b128 v[182:185], v145 offset:50176
	ds_read_b128 v[186:189], v145 offset:51200
	ds_read_b128 v[190:193], v145 offset:52224
	ds_read_b128 v[194:197], v145 offset:53248
	ds_read_b128 v[198:201], v145 offset:54272
	ds_read_b128 v[202:205], v145 offset:55296
	ds_read_b128 v[206:209], v145 offset:56320
	global_load_lds_dwordx4 v[210:211], off
	v_lshl_add_u64 v[210:211], v[212:213], 0, s[12:13]
	s_mov_b32 m0, s48
	s_addc_u32 s21, s25, 0
	global_load_lds_dwordx4 v[210:211], off
	v_lshl_add_u64 v[210:211], s[20:21], 0, v[132:133]
	s_mov_b32 m0, s49
	s_nop 0
	global_load_lds_dwordx4 v[210:211], off
	v_lshl_add_u64 v[210:211], s[20:21], 0, v[130:131]
	s_mov_b32 m0, s50
	s_nop 0
	global_load_lds_dwordx4 v[210:211], off
	v_lshl_add_u64 v[210:211], v[214:215], 0, s[12:13]
	s_mov_b32 m0, s37
	s_nop 0
	global_load_lds_dwordx4 v[210:211], off
	v_lshl_add_u64 v[210:211], v[216:217], 0, s[12:13]
	s_mov_b32 m0, s39
	s_nop 0
	global_load_lds_dwordx4 v[210:211], off
	s_waitcnt vmcnt(8)
	s_waitcnt lgkmcnt(0)
	s_barrier
	s_setprio 1
	v_mfma_f32_16x16x32_bf16 v[62:65], v[138:141], v[178:181], v[62:65]
	v_mfma_f32_16x16x32_bf16 v[58:61], v[154:157], v[178:181], v[58:61]
	v_mfma_f32_16x16x32_bf16 v[46:49], v[138:141], v[186:189], v[46:49]
	v_mfma_f32_16x16x32_bf16 v[42:45], v[154:157], v[186:189], v[42:45]
	v_mfma_f32_16x16x32_bf16 v[30:33], v[138:141], v[194:197], v[30:33]
	v_mfma_f32_16x16x32_bf16 v[26:29], v[154:157], v[194:197], v[26:29]
	v_mfma_f32_16x16x32_bf16 v[14:17], v[138:141], v[202:205], v[14:17]
	v_mfma_f32_16x16x32_bf16 v[10:13], v[154:157], v[202:205], v[10:13]
	v_mfma_f32_16x16x32_bf16 v[62:65], v[150:153], v[182:185], v[62:65]
	v_mfma_f32_16x16x32_bf16 v[58:61], v[158:161], v[182:185], v[58:61]
	v_mfma_f32_16x16x32_bf16 v[46:49], v[150:153], v[190:193], v[46:49]
	v_mfma_f32_16x16x32_bf16 v[42:45], v[158:161], v[190:193], v[42:45]
	v_mfma_f32_16x16x32_bf16 v[30:33], v[150:153], v[198:201], v[30:33]
	v_mfma_f32_16x16x32_bf16 v[26:29], v[158:161], v[198:201], v[26:29]
	v_mfma_f32_16x16x32_bf16 v[14:17], v[150:153], v[206:209], v[14:17]
	v_mfma_f32_16x16x32_bf16 v[10:13], v[158:161], v[206:209], v[10:13]
	s_setprio 0
	s_setprio 1
	v_mfma_f32_16x16x32_bf16 v[54:57], v[162:165], v[178:181], v[54:57]
	v_mfma_f32_16x16x32_bf16 v[50:53], v[170:173], v[178:181], v[50:53]
	v_mfma_f32_16x16x32_bf16 v[38:41], v[162:165], v[186:189], v[38:41]
	v_mfma_f32_16x16x32_bf16 v[34:37], v[170:173], v[186:189], v[34:37]
	v_mfma_f32_16x16x32_bf16 v[22:25], v[162:165], v[194:197], v[22:25]
	v_mfma_f32_16x16x32_bf16 v[18:21], v[170:173], v[194:197], v[18:21]
	v_mfma_f32_16x16x32_bf16 v[6:9], v[162:165], v[202:205], v[6:9]
	v_mfma_f32_16x16x32_bf16 v[2:5], v[170:173], v[202:205], v[2:5]
	v_mfma_f32_16x16x32_bf16 v[54:57], v[166:169], v[182:185], v[54:57]
	v_mfma_f32_16x16x32_bf16 v[50:53], v[174:177], v[182:185], v[50:53]
	v_mfma_f32_16x16x32_bf16 v[38:41], v[166:169], v[190:193], v[38:41]
	v_mfma_f32_16x16x32_bf16 v[34:37], v[174:177], v[190:193], v[34:37]
	v_mfma_f32_16x16x32_bf16 v[22:25], v[166:169], v[198:201], v[22:25]
	v_mfma_f32_16x16x32_bf16 v[18:21], v[174:177], v[198:201], v[18:21]
	v_mfma_f32_16x16x32_bf16 v[6:9], v[166:169], v[206:209], v[6:9]
	v_mfma_f32_16x16x32_bf16 v[2:5], v[174:177], v[206:209], v[2:5]
	s_barrier
	s_setprio 0
	s_add_i32 s6, s6, 2
	s_cmpk_gt_u32 s6, 0x55
	s_mov_b64 s[20:21], s[22:23]
	s_cbranch_scc0 .LBB0_1112
	s_and_b64 vcc, exec, s[14:15]
	s_cbranch_vccz .LBB0_1115
	s_barrier

.LBB0_1199:
	ds_read_b128 v[130:133], v169
	ds_read_b128 v[134:137], v169 offset:1024
	ds_read_b128 v[150:153], v169 offset:2048
	ds_read_b128 v[154:157], v169 offset:3072
	ds_read_b128 v[158:161], v170
	ds_read_b128 v[162:165], v170 offset:1024
	ds_read_b128 v[174:177], v170 offset:2048
	ds_read_b128 v[178:181], v170 offset:3072
	s_add_u32 s6, s0, 0xfff80080
	s_addc_u32 s7, s1, -1
	s_cmp_eq_u32 s54, 28
	s_cselect_b32 s27, s11, s7
	s_cselect_b32 s26, s10, s6
	s_cselect_b32 s7, s29, s53
	s_cselect_b32 s6, s30, s31
	s_mov_b32 m0, s48
	v_lshl_add_u64 v[166:167], s[0:1], 0, v[144:145]
	ds_read_b128 v[182:185], v171
	ds_read_b128 v[186:189], v171 offset:1024
	ds_read_b128 v[190:193], v171 offset:2048
	ds_read_b128 v[194:197], v171 offset:3072
	ds_read_b128 v[198:201], v171 offset:4096
	ds_read_b128 v[202:205], v171 offset:5120
	ds_read_b128 v[206:209], v171 offset:6144
	ds_read_b128 v[210:213], v171 offset:7168
	global_load_lds_dwordx4 v[166:167], off
	v_lshl_add_u64 v[166:167], s[0:1], 0, v[146:147]
	s_mov_b32 m0, s49
	s_nop 0
	global_load_lds_dwordx4 v[166:167], off
	s_waitcnt vmcnt(8)
	s_waitcnt lgkmcnt(0)
	s_barrier
	s_setprio 1
	v_mfma_f32_16x16x32_bf16 v[126:129], v[130:133], v[182:185], v[126:129]
	v_mfma_f32_16x16x32_bf16 v[122:125], v[150:153], v[182:185], v[122:125]
	v_mfma_f32_16x16x32_bf16 v[110:113], v[130:133], v[190:193], v[110:113]
	v_mfma_f32_16x16x32_bf16 v[106:109], v[150:153], v[190:193], v[106:109]
	v_mfma_f32_16x16x32_bf16 v[94:97], v[130:133], v[198:201], v[94:97]
	v_mfma_f32_16x16x32_bf16 v[90:93], v[150:153], v[198:201], v[90:93]
	v_mfma_f32_16x16x32_bf16 v[78:81], v[130:133], v[206:209], v[78:81]
	v_mfma_f32_16x16x32_bf16 v[74:77], v[150:153], v[206:209], v[74:77]
	v_mfma_f32_16x16x32_bf16 v[126:129], v[134:137], v[186:189], v[126:129]
	v_mfma_f32_16x16x32_bf16 v[122:125], v[154:157], v[186:189], v[122:125]
	v_mfma_f32_16x16x32_bf16 v[110:113], v[134:137], v[194:197], v[110:113]
	v_mfma_f32_16x16x32_bf16 v[106:109], v[154:157], v[194:197], v[106:109]
	v_mfma_f32_16x16x32_bf16 v[94:97], v[134:137], v[202:205], v[94:97]
	v_mfma_f32_16x16x32_bf16 v[90:93], v[154:157], v[202:205], v[90:93]
	v_mfma_f32_16x16x32_bf16 v[78:81], v[134:137], v[210:213], v[78:81]
	v_mfma_f32_16x16x32_bf16 v[74:77], v[154:157], v[210:213], v[74:77]
	s_setprio 0
	s_setprio 1
	v_mfma_f32_16x16x32_bf16 v[118:121], v[158:161], v[182:185], v[118:121]
	v_mfma_f32_16x16x32_bf16 v[114:117], v[174:177], v[182:185], v[114:117]
	v_mfma_f32_16x16x32_bf16 v[102:105], v[158:161], v[190:193], v[102:105]
	v_mfma_f32_16x16x32_bf16 v[98:101], v[174:177], v[190:193], v[98:101]
	v_mfma_f32_16x16x32_bf16 v[86:89], v[158:161], v[198:201], v[86:89]
	v_mfma_f32_16x16x32_bf16 v[82:85], v[174:177], v[198:201], v[82:85]
	v_mfma_f32_16x16x32_bf16 v[70:73], v[158:161], v[206:209], v[70:73]
	v_mfma_f32_16x16x32_bf16 v[66:69], v[174:177], v[206:209], v[66:69]
	v_mfma_f32_16x16x32_bf16 v[118:121], v[162:165], v[186:189], v[118:121]
	v_mfma_f32_16x16x32_bf16 v[114:117], v[178:181], v[186:189], v[114:117]
	v_mfma_f32_16x16x32_bf16 v[102:105], v[162:165], v[194:197], v[102:105]
	v_mfma_f32_16x16x32_bf16 v[98:101], v[178:181], v[194:197], v[98:101]
	v_mfma_f32_16x16x32_bf16 v[86:89], v[162:165], v[202:205], v[86:89]
	v_mfma_f32_16x16x32_bf16 v[82:85], v[178:181], v[202:205], v[82:85]
	v_mfma_f32_16x16x32_bf16 v[70:73], v[162:165], v[210:213], v[70:73]
	v_mfma_f32_16x16x32_bf16 v[66:69], v[178:181], v[210:213], v[66:69]
	s_barrier
	s_setprio 0
	s_add_i32 s55, s46, s34
	v_lshl_add_u64 v[166:167], s[6:7], 0, v[140:141]
	s_mov_b32 m0, s55
	ds_read_b128 v[182:185], v171 offset:16384
	ds_read_b128 v[186:189], v171 offset:17408
	ds_read_b128 v[190:193], v171 offset:18432
	ds_read_b128 v[194:197], v171 offset:19456
	ds_read_b128 v[198:201], v171 offset:20480
	ds_read_b128 v[202:205], v171 offset:21504
	ds_read_b128 v[206:209], v171 offset:22528
	ds_read_b128 v[210:213], v171 offset:23552
	global_load_lds_dwordx4 v[166:167], off
	s_add_i32 m0, s55, 0x2000
	s_add_u32 s56, s6, 0x80000
	v_lshl_add_u64 v[214:215], s[6:7], 0, v[138:139]
	s_addc_u32 s57, s7, 0
	s_add_i32 s55, s47, s34
	global_load_lds_dwordx4 v[214:215], off
	v_lshl_add_u64 v[216:217], s[56:57], 0, v[140:141]
	s_mov_b32 m0, s55
	v_lshl_add_u64 v[218:219], s[26:27], 0, v[138:139]
	global_load_lds_dwordx4 v[216:217], off
	v_lshl_add_u64 v[216:217], s[56:57], 0, v[138:139]
	s_add_i32 m0, s55, 0x2000
	s_nop 0
	global_load_lds_dwordx4 v[216:217], off
	v_lshl_add_u64 v[216:217], s[26:27], 0, v[140:141]
	s_mov_b32 m0, s35
	s_nop 0
	global_load_lds_dwordx4 v[216:217], off
	s_mov_b32 m0, s36
	s_nop 0
	global_load_lds_dwordx4 v[218:219], off
	s_waitcnt vmcnt(8)
	s_waitcnt lgkmcnt(0)
	s_barrier
	s_setprio 1
	v_mfma_f32_16x16x32_bf16 v[62:65], v[130:133], v[182:185], v[62:65]
	v_mfma_f32_16x16x32_bf16 v[58:61], v[150:153], v[182:185], v[58:61]
	v_mfma_f32_16x16x32_bf16 v[46:49], v[130:133], v[190:193], v[46:49]
	v_mfma_f32_16x16x32_bf16 v[42:45], v[150:153], v[190:193], v[42:45]
	v_mfma_f32_16x16x32_bf16 v[30:33], v[130:133], v[198:201], v[30:33]
	v_mfma_f32_16x16x32_bf16 v[26:29], v[150:153], v[198:201], v[26:29]
	v_mfma_f32_16x16x32_bf16 v[14:17], v[130:133], v[206:209], v[14:17]
	v_mfma_f32_16x16x32_bf16 v[10:13], v[150:153], v[206:209], v[10:13]
	v_mfma_f32_16x16x32_bf16 v[62:65], v[134:137], v[186:189], v[62:65]
	v_mfma_f32_16x16x32_bf16 v[58:61], v[154:157], v[186:189], v[58:61]
	v_mfma_f32_16x16x32_bf16 v[46:49], v[134:137], v[194:197], v[46:49]
	v_mfma_f32_16x16x32_bf16 v[42:45], v[154:157], v[194:197], v[42:45]
	v_mfma_f32_16x16x32_bf16 v[30:33], v[134:137], v[202:205], v[30:33]
	v_mfma_f32_16x16x32_bf16 v[26:29], v[154:157], v[202:205], v[26:29]
	v_mfma_f32_16x16x32_bf16 v[14:17], v[134:137], v[210:213], v[14:17]
	v_mfma_f32_16x16x32_bf16 v[10:13], v[154:157], v[210:213], v[10:13]
	s_setprio 0
	s_setprio 1
	v_mfma_f32_16x16x32_bf16 v[54:57], v[158:161], v[182:185], v[54:57]
	v_mfma_f32_16x16x32_bf16 v[50:53], v[174:177], v[182:185], v[50:53]
	v_mfma_f32_16x16x32_bf16 v[38:41], v[158:161], v[190:193], v[38:41]
	v_mfma_f32_16x16x32_bf16 v[34:37], v[174:177], v[190:193], v[34:37]
	v_mfma_f32_16x16x32_bf16 v[22:25], v[158:161], v[198:201], v[22:25]
	v_mfma_f32_16x16x32_bf16 v[18:21], v[174:177], v[198:201], v[18:21]
	v_mfma_f32_16x16x32_bf16 v[6:9], v[158:161], v[206:209], v[6:9]
	v_mfma_f32_16x16x32_bf16 v[2:5], v[174:177], v[206:209], v[2:5]
	v_mfma_f32_16x16x32_bf16 v[54:57], v[162:165], v[186:189], v[54:57]
	v_mfma_f32_16x16x32_bf16 v[50:53], v[178:181], v[186:189], v[50:53]
	v_mfma_f32_16x16x32_bf16 v[38:41], v[162:165], v[194:197], v[38:41]
	v_mfma_f32_16x16x32_bf16 v[34:37], v[178:181], v[194:197], v[34:37]
	v_mfma_f32_16x16x32_bf16 v[22:25], v[162:165], v[202:205], v[22:25]
	v_mfma_f32_16x16x32_bf16 v[18:21], v[178:181], v[202:205], v[18:21]
	v_mfma_f32_16x16x32_bf16 v[6:9], v[162:165], v[210:213], v[6:9]
	v_mfma_f32_16x16x32_bf16 v[2:5], v[178:181], v[210:213], v[2:5]
	s_barrier
	s_setprio 0
	s_add_i32 s55, 0, 0x18000
	v_add_u32_e32 v142, s55, v168
	s_add_i32 s56, 0, 0x1c000
	ds_read_b128 v[130:133], v142
	ds_read_b128 v[134:137], v142 offset:1024
	ds_read_b128 v[150:153], v142 offset:2048
	ds_read_b128 v[154:157], v142 offset:3072
	v_add_u32_e32 v142, s56, v168
	ds_read_b128 v[158:161], v142
	ds_read_b128 v[162:165], v142 offset:1024
	ds_read_b128 v[174:177], v142 offset:2048
	ds_read_b128 v[178:181], v142 offset:3072
	s_add_u32 s26, s26, 0x80000
	s_addc_u32 s27, s27, 0
	s_mov_b32 m0, s37
	v_lshl_add_u64 v[220:221], s[26:27], 0, v[140:141]
	ds_read_b128 v[182:185], v171 offset:32768
	ds_read_b128 v[186:189], v171 offset:33792
	ds_read_b128 v[190:193], v171 offset:34816
	ds_read_b128 v[194:197], v171 offset:35840
	ds_read_b128 v[198:201], v171 offset:36864
	ds_read_b128 v[202:205], v171 offset:37888
	ds_read_b128 v[206:209], v171 offset:38912
	ds_read_b128 v[210:213], v171 offset:39936
	global_load_lds_dwordx4 v[220:221], off
	v_lshl_add_u64 v[220:221], s[26:27], 0, v[138:139]
	s_mov_b32 m0, s39
	s_nop 0
	global_load_lds_dwordx4 v[220:221], off
	s_waitcnt vmcnt(8)
	s_waitcnt lgkmcnt(0)
	s_barrier
	s_setprio 1
	v_mfma_f32_16x16x32_bf16 v[126:129], v[130:133], v[182:185], v[126:129]
	v_mfma_f32_16x16x32_bf16 v[122:125], v[150:153], v[182:185], v[122:125]
	v_mfma_f32_16x16x32_bf16 v[110:113], v[130:133], v[190:193], v[110:113]
	v_mfma_f32_16x16x32_bf16 v[106:109], v[150:153], v[190:193], v[106:109]
	v_mfma_f32_16x16x32_bf16 v[94:97], v[130:133], v[198:201], v[94:97]
	v_mfma_f32_16x16x32_bf16 v[90:93], v[150:153], v[198:201], v[90:93]
	v_mfma_f32_16x16x32_bf16 v[78:81], v[130:133], v[206:209], v[78:81]
	v_mfma_f32_16x16x32_bf16 v[74:77], v[150:153], v[206:209], v[74:77]
	v_mfma_f32_16x16x32_bf16 v[126:129], v[134:137], v[186:189], v[126:129]
	v_mfma_f32_16x16x32_bf16 v[122:125], v[154:157], v[186:189], v[122:125]
	v_mfma_f32_16x16x32_bf16 v[110:113], v[134:137], v[194:197], v[110:113]
	v_mfma_f32_16x16x32_bf16 v[106:109], v[154:157], v[194:197], v[106:109]
	v_mfma_f32_16x16x32_bf16 v[94:97], v[134:137], v[202:205], v[94:97]
	v_mfma_f32_16x16x32_bf16 v[90:93], v[154:157], v[202:205], v[90:93]
	v_mfma_f32_16x16x32_bf16 v[78:81], v[134:137], v[210:213], v[78:81]
	v_mfma_f32_16x16x32_bf16 v[74:77], v[154:157], v[210:213], v[74:77]
	s_setprio 0
	s_setprio 1
	v_mfma_f32_16x16x32_bf16 v[118:121], v[158:161], v[182:185], v[118:121]
	v_mfma_f32_16x16x32_bf16 v[114:117], v[174:177], v[182:185], v[114:117]
	v_mfma_f32_16x16x32_bf16 v[102:105], v[158:161], v[190:193], v[102:105]
	v_mfma_f32_16x16x32_bf16 v[98:101], v[174:177], v[190:193], v[98:101]
	v_mfma_f32_16x16x32_bf16 v[86:89], v[158:161], v[198:201], v[86:89]
	v_mfma_f32_16x16x32_bf16 v[82:85], v[174:177], v[198:201], v[82:85]
	v_mfma_f32_16x16x32_bf16 v[70:73], v[158:161], v[206:209], v[70:73]
	v_mfma_f32_16x16x32_bf16 v[66:69], v[174:177], v[206:209], v[66:69]
	v_mfma_f32_16x16x32_bf16 v[118:121], v[162:165], v[186:189], v[118:121]
	v_mfma_f32_16x16x32_bf16 v[114:117], v[178:181], v[186:189], v[114:117]
	v_mfma_f32_16x16x32_bf16 v[102:105], v[162:165], v[194:197], v[102:105]
	v_mfma_f32_16x16x32_bf16 v[98:101], v[178:181], v[194:197], v[98:101]
	v_mfma_f32_16x16x32_bf16 v[86:89], v[162:165], v[202:205], v[86:89]
	v_mfma_f32_16x16x32_bf16 v[82:85], v[178:181], v[202:205], v[82:85]
	v_mfma_f32_16x16x32_bf16 v[70:73], v[162:165], v[210:213], v[70:73]
	v_mfma_f32_16x16x32_bf16 v[66:69], v[178:181], v[210:213], v[66:69]
	s_barrier
	s_setprio 0
	s_add_i32 s26, s55, s34
	v_lshl_add_u64 v[166:167], v[166:167], 0, s[14:15]
	s_mov_b32 m0, s26
	ds_read_b128 v[182:185], v171 offset:49152
	ds_read_b128 v[186:189], v171 offset:50176
	ds_read_b128 v[190:193], v171 offset:51200
	ds_read_b128 v[194:197], v171 offset:52224
	ds_read_b128 v[198:201], v171 offset:53248
	ds_read_b128 v[202:205], v171 offset:54272
	ds_read_b128 v[206:209], v171 offset:55296
	ds_read_b128 v[210:213], v171 offset:56320
	global_load_lds_dwordx4 v[166:167], off
	s_add_i32 m0, s26, 0x2000
	s_add_u32 s6, s6, 0x80080
	v_lshl_add_u64 v[166:167], v[214:215], 0, s[14:15]
	s_addc_u32 s7, s7, 0
	s_add_i32 s26, s56, s34
	global_load_lds_dwordx4 v[166:167], off
	v_lshl_add_u64 v[166:167], s[6:7], 0, v[140:141]
	s_mov_b32 m0, s26
	s_nop 0
	global_load_lds_dwordx4 v[166:167], off
	v_lshl_add_u64 v[166:167], s[6:7], 0, v[138:139]
	s_add_i32 m0, s26, 0x2000
	s_nop 0
	global_load_lds_dwordx4 v[166:167], off
	v_lshl_add_u64 v[166:167], v[216:217], 0, s[14:15]
	s_mov_b32 m0, s43
	s_nop 0
	global_load_lds_dwordx4 v[166:167], off
	v_lshl_add_u64 v[166:167], v[218:219], 0, s[14:15]
	s_mov_b32 m0, s44
	s_nop 0
	global_load_lds_dwordx4 v[166:167], off
	s_waitcnt vmcnt(8)
	s_waitcnt lgkmcnt(0)
	s_barrier
	s_setprio 1
	v_mfma_f32_16x16x32_bf16 v[62:65], v[130:133], v[182:185], v[62:65]
	v_mfma_f32_16x16x32_bf16 v[58:61], v[150:153], v[182:185], v[58:61]
	v_mfma_f32_16x16x32_bf16 v[46:49], v[130:133], v[190:193], v[46:49]
	v_mfma_f32_16x16x32_bf16 v[42:45], v[150:153], v[190:193], v[42:45]
	v_mfma_f32_16x16x32_bf16 v[30:33], v[130:133], v[198:201], v[30:33]
	v_mfma_f32_16x16x32_bf16 v[26:29], v[150:153], v[198:201], v[26:29]
	v_mfma_f32_16x16x32_bf16 v[14:17], v[130:133], v[206:209], v[14:17]
	v_mfma_f32_16x16x32_bf16 v[10:13], v[150:153], v[206:209], v[10:13]
	v_mfma_f32_16x16x32_bf16 v[62:65], v[134:137], v[186:189], v[62:65]
	v_mfma_f32_16x16x32_bf16 v[58:61], v[154:157], v[186:189], v[58:61]
	v_mfma_f32_16x16x32_bf16 v[46:49], v[134:137], v[194:197], v[46:49]
	v_mfma_f32_16x16x32_bf16 v[42:45], v[154:157], v[194:197], v[42:45]
	v_mfma_f32_16x16x32_bf16 v[30:33], v[134:137], v[202:205], v[30:33]
	v_mfma_f32_16x16x32_bf16 v[26:29], v[154:157], v[202:205], v[26:29]
	v_mfma_f32_16x16x32_bf16 v[14:17], v[134:137], v[210:213], v[14:17]
	v_mfma_f32_16x16x32_bf16 v[10:13], v[154:157], v[210:213], v[10:13]
	s_setprio 0
	s_setprio 1
	v_mfma_f32_16x16x32_bf16 v[54:57], v[158:161], v[182:185], v[54:57]
	v_mfma_f32_16x16x32_bf16 v[50:53], v[174:177], v[182:185], v[50:53]
	v_mfma_f32_16x16x32_bf16 v[38:41], v[158:161], v[190:193], v[38:41]
	v_mfma_f32_16x16x32_bf16 v[34:37], v[174:177], v[190:193], v[34:37]
	v_mfma_f32_16x16x32_bf16 v[22:25], v[158:161], v[198:201], v[22:25]
	v_mfma_f32_16x16x32_bf16 v[18:21], v[174:177], v[198:201], v[18:21]
	v_mfma_f32_16x16x32_bf16 v[6:9], v[158:161], v[206:209], v[6:9]
	v_mfma_f32_16x16x32_bf16 v[2:5], v[174:177], v[206:209], v[2:5]
	v_mfma_f32_16x16x32_bf16 v[54:57], v[162:165], v[186:189], v[54:57]
	v_mfma_f32_16x16x32_bf16 v[50:53], v[178:181], v[186:189], v[50:53]
	v_mfma_f32_16x16x32_bf16 v[38:41], v[162:165], v[194:197], v[38:41]
	v_mfma_f32_16x16x32_bf16 v[34:37], v[178:181], v[194:197], v[34:37]
	v_mfma_f32_16x16x32_bf16 v[22:25], v[162:165], v[202:205], v[22:25]
	v_mfma_f32_16x16x32_bf16 v[18:21], v[178:181], v[202:205], v[18:21]
	v_mfma_f32_16x16x32_bf16 v[6:9], v[162:165], v[210:213], v[6:9]
	v_mfma_f32_16x16x32_bf16 v[2:5], v[178:181], v[210:213], v[2:5]
	s_barrier
	s_setprio 0
	s_add_i32 s54, s54, 2
	s_add_u32 s0, s0, 0x100
	s_addc_u32 s1, s1, 0
	s_add_u32 s31, s31, 0x100
	s_addc_u32 s53, s53, 0
	s_cmp_gt_u32 s54, 29
	s_cbranch_scc0 .LBB0_1199
	s_and_b64 vcc, exec, s[16:17]
	s_cbranch_vccz .LBB0_1202
	s_barrier

.LBB0_1855:
	ds_read_b128 v[142:145], v148
	ds_read_b128 v[152:155], v148 offset:1024
	ds_read_b128 v[156:159], v148 offset:2048
	ds_read_b128 v[160:163], v148 offset:3072
	ds_read_b128 v[164:167], v149
	ds_read_b128 v[168:171], v149 offset:1024
	ds_read_b128 v[172:175], v149 offset:2048
	ds_read_b128 v[176:179], v149 offset:3072
	s_add_u32 s26, s24, 0x100
	s_addc_u32 s27, s25, 0
	s_cmp_eq_u32 s55, 60
	s_cselect_b32 s31, s19, s27
	s_cselect_b32 s30, s51, s26
	s_cselect_b32 s29, s17, s54
	s_cselect_b32 s28, s52, s53
	v_lshl_add_u64 v[212:213], s[24:25], 0, v[134:135]
	s_add_i32 m0, s5, 0xc000
	ds_read_b128 v[180:183], v150
	ds_read_b128 v[184:187], v150 offset:1024
	ds_read_b128 v[188:191], v150 offset:2048
	ds_read_b128 v[192:195], v150 offset:3072
	ds_read_b128 v[196:199], v150 offset:4096
	ds_read_b128 v[200:203], v150 offset:5120
	ds_read_b128 v[204:207], v150 offset:6144
	ds_read_b128 v[208:211], v150 offset:7168
	global_load_lds_dwordx4 v[212:213], off
	v_lshl_add_u64 v[212:213], s[24:25], 0, v[136:137]
	s_add_i32 m0, s5, 0xe000
	s_nop 0
	global_load_lds_dwordx4 v[212:213], off
	s_waitcnt vmcnt(8)
	s_waitcnt lgkmcnt(0)
	s_barrier
	s_setprio 1
	v_mfma_f32_16x16x32_bf16 v[126:129], v[142:145], v[180:183], v[126:129]
	v_mfma_f32_16x16x32_bf16 v[122:125], v[156:159], v[180:183], v[122:125]
	v_mfma_f32_16x16x32_bf16 v[110:113], v[142:145], v[188:191], v[110:113]
	v_mfma_f32_16x16x32_bf16 v[106:109], v[156:159], v[188:191], v[106:109]
	v_mfma_f32_16x16x32_bf16 v[94:97], v[142:145], v[196:199], v[94:97]
	v_mfma_f32_16x16x32_bf16 v[90:93], v[156:159], v[196:199], v[90:93]
	v_mfma_f32_16x16x32_bf16 v[78:81], v[142:145], v[204:207], v[78:81]
	v_mfma_f32_16x16x32_bf16 v[74:77], v[156:159], v[204:207], v[74:77]
	v_mfma_f32_16x16x32_bf16 v[126:129], v[152:155], v[184:187], v[126:129]
	v_mfma_f32_16x16x32_bf16 v[122:125], v[160:163], v[184:187], v[122:125]
	v_mfma_f32_16x16x32_bf16 v[110:113], v[152:155], v[192:195], v[110:113]
	v_mfma_f32_16x16x32_bf16 v[106:109], v[160:163], v[192:195], v[106:109]
	v_mfma_f32_16x16x32_bf16 v[94:97], v[152:155], v[200:203], v[94:97]
	v_mfma_f32_16x16x32_bf16 v[90:93], v[160:163], v[200:203], v[90:93]
	v_mfma_f32_16x16x32_bf16 v[78:81], v[152:155], v[208:211], v[78:81]
	v_mfma_f32_16x16x32_bf16 v[74:77], v[160:163], v[208:211], v[74:77]
	s_setprio 0
	s_setprio 1
	v_mfma_f32_16x16x32_bf16 v[118:121], v[164:167], v[180:183], v[118:121]
	v_mfma_f32_16x16x32_bf16 v[114:117], v[172:175], v[180:183], v[114:117]
	v_mfma_f32_16x16x32_bf16 v[102:105], v[164:167], v[188:191], v[102:105]
	v_mfma_f32_16x16x32_bf16 v[98:101], v[172:175], v[188:191], v[98:101]
	v_mfma_f32_16x16x32_bf16 v[86:89], v[164:167], v[196:199], v[86:89]
	v_mfma_f32_16x16x32_bf16 v[82:85], v[172:175], v[196:199], v[82:85]
	v_mfma_f32_16x16x32_bf16 v[70:73], v[164:167], v[204:207], v[70:73]
	v_mfma_f32_16x16x32_bf16 v[66:69], v[172:175], v[204:207], v[66:69]
	v_mfma_f32_16x16x32_bf16 v[118:121], v[168:171], v[184:187], v[118:121]
	v_mfma_f32_16x16x32_bf16 v[114:117], v[176:179], v[184:187], v[114:117]
	v_mfma_f32_16x16x32_bf16 v[102:105], v[168:171], v[192:195], v[102:105]
	v_mfma_f32_16x16x32_bf16 v[98:101], v[176:179], v[192:195], v[98:101]
	v_mfma_f32_16x16x32_bf16 v[86:89], v[168:171], v[200:203], v[86:89]
	v_mfma_f32_16x16x32_bf16 v[82:85], v[176:179], v[200:203], v[82:85]
	v_mfma_f32_16x16x32_bf16 v[70:73], v[168:171], v[208:211], v[70:73]
	v_mfma_f32_16x16x32_bf16 v[66:69], v[176:179], v[208:211], v[66:69]
	s_barrier
	s_setprio 0
	s_add_i32 s24, s48, s37
	v_lshl_add_u64 v[212:213], s[28:29], 0, v[130:131]
	s_mov_b32 m0, s24
	ds_read_b128 v[180:183], v150 offset:16384
	ds_read_b128 v[184:187], v150 offset:17408
	ds_read_b128 v[188:191], v150 offset:18432
	ds_read_b128 v[192:195], v150 offset:19456
	ds_read_b128 v[196:199], v150 offset:20480
	ds_read_b128 v[200:203], v150 offset:21504
	ds_read_b128 v[204:207], v150 offset:22528
	ds_read_b128 v[208:211], v150 offset:23552
	global_load_lds_dwordx4 v[212:213], off
	s_add_i32 m0, s24, 0x2000
	s_add_u32 s24, s28, 0x100000
	v_lshl_add_u64 v[214:215], s[28:29], 0, v[132:133]
	s_addc_u32 s25, s29, 0
	s_add_i32 s56, s49, s37
	global_load_lds_dwordx4 v[214:215], off
	v_lshl_add_u64 v[216:217], s[24:25], 0, v[130:131]
	s_mov_b32 m0, s56
	v_lshl_add_u64 v[218:219], s[30:31], 0, v[132:133]
	global_load_lds_dwordx4 v[216:217], off
	v_lshl_add_u64 v[216:217], s[24:25], 0, v[132:133]
	s_add_i32 m0, s56, 0x2000
	s_nop 0
	global_load_lds_dwordx4 v[216:217], off
	v_lshl_add_u64 v[216:217], s[30:31], 0, v[130:131]
	s_mov_b32 m0, s5
	s_nop 0
	global_load_lds_dwordx4 v[216:217], off
	s_mov_b32 m0, s38
	s_nop 0
	global_load_lds_dwordx4 v[218:219], off
	s_waitcnt vmcnt(8)
	s_waitcnt lgkmcnt(0)
	s_barrier
	s_setprio 1
	v_mfma_f32_16x16x32_bf16 v[62:65], v[142:145], v[180:183], v[62:65]
	v_mfma_f32_16x16x32_bf16 v[58:61], v[156:159], v[180:183], v[58:61]
	v_mfma_f32_16x16x32_bf16 v[46:49], v[142:145], v[188:191], v[46:49]
	v_mfma_f32_16x16x32_bf16 v[42:45], v[156:159], v[188:191], v[42:45]
	v_mfma_f32_16x16x32_bf16 v[30:33], v[142:145], v[196:199], v[30:33]
	v_mfma_f32_16x16x32_bf16 v[26:29], v[156:159], v[196:199], v[26:29]
	v_mfma_f32_16x16x32_bf16 v[14:17], v[142:145], v[204:207], v[14:17]
	v_mfma_f32_16x16x32_bf16 v[10:13], v[156:159], v[204:207], v[10:13]
	v_mfma_f32_16x16x32_bf16 v[62:65], v[152:155], v[184:187], v[62:65]
	v_mfma_f32_16x16x32_bf16 v[58:61], v[160:163], v[184:187], v[58:61]
	v_mfma_f32_16x16x32_bf16 v[46:49], v[152:155], v[192:195], v[46:49]
	v_mfma_f32_16x16x32_bf16 v[42:45], v[160:163], v[192:195], v[42:45]
	v_mfma_f32_16x16x32_bf16 v[30:33], v[152:155], v[200:203], v[30:33]
	v_mfma_f32_16x16x32_bf16 v[26:29], v[160:163], v[200:203], v[26:29]
	v_mfma_f32_16x16x32_bf16 v[14:17], v[152:155], v[208:211], v[14:17]
	v_mfma_f32_16x16x32_bf16 v[10:13], v[160:163], v[208:211], v[10:13]
	s_setprio 0
	s_setprio 1
	v_mfma_f32_16x16x32_bf16 v[54:57], v[164:167], v[180:183], v[54:57]
	v_mfma_f32_16x16x32_bf16 v[50:53], v[172:175], v[180:183], v[50:53]
	v_mfma_f32_16x16x32_bf16 v[38:41], v[164:167], v[188:191], v[38:41]
	v_mfma_f32_16x16x32_bf16 v[34:37], v[172:175], v[188:191], v[34:37]
	v_mfma_f32_16x16x32_bf16 v[22:25], v[164:167], v[196:199], v[22:25]
	v_mfma_f32_16x16x32_bf16 v[18:21], v[172:175], v[196:199], v[18:21]
	v_mfma_f32_16x16x32_bf16 v[6:9], v[164:167], v[204:207], v[6:9]
	v_mfma_f32_16x16x32_bf16 v[2:5], v[172:175], v[204:207], v[2:5]
	v_mfma_f32_16x16x32_bf16 v[54:57], v[168:171], v[184:187], v[54:57]
	v_mfma_f32_16x16x32_bf16 v[50:53], v[176:179], v[184:187], v[50:53]
	v_mfma_f32_16x16x32_bf16 v[38:41], v[168:171], v[192:195], v[38:41]
	v_mfma_f32_16x16x32_bf16 v[34:37], v[176:179], v[192:195], v[34:37]
	v_mfma_f32_16x16x32_bf16 v[22:25], v[168:171], v[200:203], v[22:25]
	v_mfma_f32_16x16x32_bf16 v[18:21], v[176:179], v[200:203], v[18:21]
	v_mfma_f32_16x16x32_bf16 v[6:9], v[168:171], v[208:211], v[6:9]
	v_mfma_f32_16x16x32_bf16 v[2:5], v[176:179], v[208:211], v[2:5]
	s_barrier
	s_setprio 0
	s_add_i32 s56, 0, 0x18000
	s_add_i32 s57, 0, 0x1c000
	v_add_u32_e32 v160, s56, v147
	v_add_u32_e32 v176, s57, v147
	ds_read_b128 v[142:145], v160
	ds_read_b128 v[152:155], v160 offset:1024
	ds_read_b128 v[156:159], v160 offset:2048
	ds_read_b128 v[160:163], v160 offset:3072
	ds_read_b128 v[164:167], v176
	ds_read_b128 v[168:171], v176 offset:1024
	ds_read_b128 v[172:175], v176 offset:2048
	ds_read_b128 v[176:179], v176 offset:3072
	s_add_u32 s24, s30, 0x100000
	s_addc_u32 s25, s31, 0
	s_mov_b32 m0, s39
	v_lshl_add_u64 v[220:221], s[24:25], 0, v[130:131]
	ds_read_b128 v[180:183], v150 offset:32768
	ds_read_b128 v[184:187], v150 offset:33792
	ds_read_b128 v[188:191], v150 offset:34816
	ds_read_b128 v[192:195], v150 offset:35840
	ds_read_b128 v[196:199], v150 offset:36864
	ds_read_b128 v[200:203], v150 offset:37888
	ds_read_b128 v[204:207], v150 offset:38912
	ds_read_b128 v[208:211], v150 offset:39936
	global_load_lds_dwordx4 v[220:221], off
	v_lshl_add_u64 v[220:221], s[24:25], 0, v[132:133]
	s_mov_b32 m0, s40
	s_nop 0
	global_load_lds_dwordx4 v[220:221], off
	s_waitcnt vmcnt(8)
	s_waitcnt lgkmcnt(0)
	s_barrier
	s_setprio 1
	v_mfma_f32_16x16x32_bf16 v[126:129], v[142:145], v[180:183], v[126:129]
	v_mfma_f32_16x16x32_bf16 v[122:125], v[156:159], v[180:183], v[122:125]
	v_mfma_f32_16x16x32_bf16 v[110:113], v[142:145], v[188:191], v[110:113]
	v_mfma_f32_16x16x32_bf16 v[106:109], v[156:159], v[188:191], v[106:109]
	v_mfma_f32_16x16x32_bf16 v[94:97], v[142:145], v[196:199], v[94:97]
	v_mfma_f32_16x16x32_bf16 v[90:93], v[156:159], v[196:199], v[90:93]
	v_mfma_f32_16x16x32_bf16 v[78:81], v[142:145], v[204:207], v[78:81]
	v_mfma_f32_16x16x32_bf16 v[74:77], v[156:159], v[204:207], v[74:77]
	v_mfma_f32_16x16x32_bf16 v[126:129], v[152:155], v[184:187], v[126:129]
	v_mfma_f32_16x16x32_bf16 v[122:125], v[160:163], v[184:187], v[122:125]
	v_mfma_f32_16x16x32_bf16 v[110:113], v[152:155], v[192:195], v[110:113]
	v_mfma_f32_16x16x32_bf16 v[106:109], v[160:163], v[192:195], v[106:109]
	v_mfma_f32_16x16x32_bf16 v[94:97], v[152:155], v[200:203], v[94:97]
	v_mfma_f32_16x16x32_bf16 v[90:93], v[160:163], v[200:203], v[90:93]
	v_mfma_f32_16x16x32_bf16 v[78:81], v[152:155], v[208:211], v[78:81]
	v_mfma_f32_16x16x32_bf16 v[74:77], v[160:163], v[208:211], v[74:77]
	s_setprio 0
	s_setprio 1
	v_mfma_f32_16x16x32_bf16 v[118:121], v[164:167], v[180:183], v[118:121]
	v_mfma_f32_16x16x32_bf16 v[114:117], v[172:175], v[180:183], v[114:117]
	v_mfma_f32_16x16x32_bf16 v[102:105], v[164:167], v[188:191], v[102:105]
	v_mfma_f32_16x16x32_bf16 v[98:101], v[172:175], v[188:191], v[98:101]
	v_mfma_f32_16x16x32_bf16 v[86:89], v[164:167], v[196:199], v[86:89]
	v_mfma_f32_16x16x32_bf16 v[82:85], v[172:175], v[196:199], v[82:85]
	v_mfma_f32_16x16x32_bf16 v[70:73], v[164:167], v[204:207], v[70:73]
	v_mfma_f32_16x16x32_bf16 v[66:69], v[172:175], v[204:207], v[66:69]
	v_mfma_f32_16x16x32_bf16 v[118:121], v[168:171], v[184:187], v[118:121]
	v_mfma_f32_16x16x32_bf16 v[114:117], v[176:179], v[184:187], v[114:117]
	v_mfma_f32_16x16x32_bf16 v[102:105], v[168:171], v[192:195], v[102:105]
	v_mfma_f32_16x16x32_bf16 v[98:101], v[176:179], v[192:195], v[98:101]
	v_mfma_f32_16x16x32_bf16 v[86:89], v[168:171], v[200:203], v[86:89]
	v_mfma_f32_16x16x32_bf16 v[82:85], v[176:179], v[200:203], v[82:85]
	v_mfma_f32_16x16x32_bf16 v[70:73], v[168:171], v[208:211], v[70:73]
	v_mfma_f32_16x16x32_bf16 v[66:69], v[176:179], v[208:211], v[66:69]
	s_barrier
	s_setprio 0
	s_add_i32 s24, s56, s37
	v_lshl_add_u64 v[212:213], v[212:213], 0, s[12:13]
	s_mov_b32 m0, s24
	ds_read_b128 v[180:183], v150 offset:49152
	ds_read_b128 v[184:187], v150 offset:50176
	ds_read_b128 v[188:191], v150 offset:51200
	ds_read_b128 v[192:195], v150 offset:52224
	ds_read_b128 v[196:199], v150 offset:53248
	ds_read_b128 v[200:203], v150 offset:54272
	ds_read_b128 v[204:207], v150 offset:55296
	ds_read_b128 v[208:211], v150 offset:56320
	global_load_lds_dwordx4 v[212:213], off
	s_add_i32 m0, s24, 0x2000
	s_add_u32 s24, s28, 0x100080
	v_lshl_add_u64 v[212:213], v[214:215], 0, s[12:13]
	s_addc_u32 s25, s29, 0
	s_add_i32 s28, s57, s37
	global_load_lds_dwordx4 v[212:213], off
	v_lshl_add_u64 v[212:213], s[24:25], 0, v[130:131]
	s_mov_b32 m0, s28
	s_nop 0
	global_load_lds_dwordx4 v[212:213], off
	v_lshl_add_u64 v[212:213], s[24:25], 0, v[132:133]
	s_add_i32 m0, s28, 0x2000
	s_nop 0
	global_load_lds_dwordx4 v[212:213], off
	v_lshl_add_u64 v[212:213], v[216:217], 0, s[12:13]
	s_mov_b32 m0, s44
	s_nop 0
	global_load_lds_dwordx4 v[212:213], off
	v_lshl_add_u64 v[212:213], v[218:219], 0, s[12:13]
	s_mov_b32 m0, s45
	s_nop 0
	global_load_lds_dwordx4 v[212:213], off
	s_waitcnt vmcnt(8)
	s_waitcnt lgkmcnt(0)
	s_barrier
	s_setprio 1
	v_mfma_f32_16x16x32_bf16 v[62:65], v[142:145], v[180:183], v[62:65]
	v_mfma_f32_16x16x32_bf16 v[58:61], v[156:159], v[180:183], v[58:61]
	v_mfma_f32_16x16x32_bf16 v[46:49], v[142:145], v[188:191], v[46:49]
	v_mfma_f32_16x16x32_bf16 v[42:45], v[156:159], v[188:191], v[42:45]
	v_mfma_f32_16x16x32_bf16 v[30:33], v[142:145], v[196:199], v[30:33]
	v_mfma_f32_16x16x32_bf16 v[26:29], v[156:159], v[196:199], v[26:29]
	v_mfma_f32_16x16x32_bf16 v[14:17], v[142:145], v[204:207], v[14:17]
	v_mfma_f32_16x16x32_bf16 v[10:13], v[156:159], v[204:207], v[10:13]
	v_mfma_f32_16x16x32_bf16 v[62:65], v[152:155], v[184:187], v[62:65]
	v_mfma_f32_16x16x32_bf16 v[58:61], v[160:163], v[184:187], v[58:61]
	v_mfma_f32_16x16x32_bf16 v[46:49], v[152:155], v[192:195], v[46:49]
	v_mfma_f32_16x16x32_bf16 v[42:45], v[160:163], v[192:195], v[42:45]
	v_mfma_f32_16x16x32_bf16 v[30:33], v[152:155], v[200:203], v[30:33]
	v_mfma_f32_16x16x32_bf16 v[26:29], v[160:163], v[200:203], v[26:29]
	v_mfma_f32_16x16x32_bf16 v[14:17], v[152:155], v[208:211], v[14:17]
	v_mfma_f32_16x16x32_bf16 v[10:13], v[160:163], v[208:211], v[10:13]
	s_setprio 0
	s_setprio 1
	v_mfma_f32_16x16x32_bf16 v[54:57], v[164:167], v[180:183], v[54:57]
	v_mfma_f32_16x16x32_bf16 v[50:53], v[172:175], v[180:183], v[50:53]
	v_mfma_f32_16x16x32_bf16 v[38:41], v[164:167], v[188:191], v[38:41]
	v_mfma_f32_16x16x32_bf16 v[34:37], v[172:175], v[188:191], v[34:37]
	v_mfma_f32_16x16x32_bf16 v[22:25], v[164:167], v[196:199], v[22:25]
	v_mfma_f32_16x16x32_bf16 v[18:21], v[172:175], v[196:199], v[18:21]
	v_mfma_f32_16x16x32_bf16 v[6:9], v[164:167], v[204:207], v[6:9]
	v_mfma_f32_16x16x32_bf16 v[2:5], v[172:175], v[204:207], v[2:5]
	v_mfma_f32_16x16x32_bf16 v[54:57], v[168:171], v[184:187], v[54:57]
	v_mfma_f32_16x16x32_bf16 v[50:53], v[176:179], v[184:187], v[50:53]
	v_mfma_f32_16x16x32_bf16 v[38:41], v[168:171], v[192:195], v[38:41]
	v_mfma_f32_16x16x32_bf16 v[34:37], v[176:179], v[192:195], v[34:37]
	v_mfma_f32_16x16x32_bf16 v[22:25], v[168:171], v[200:203], v[22:25]
	v_mfma_f32_16x16x32_bf16 v[18:21], v[176:179], v[200:203], v[18:21]
	v_mfma_f32_16x16x32_bf16 v[6:9], v[168:171], v[208:211], v[6:9]
	v_mfma_f32_16x16x32_bf16 v[2:5], v[176:179], v[208:211], v[2:5]
	s_barrier
	s_setprio 0
	s_add_i32 s55, s55, 2
	s_add_u32 s53, s53, 0x100
	s_addc_u32 s54, s54, 0
	s_cmp_gt_u32 s55, 61
	s_mov_b64 s[24:25], s[26:27]
	s_cbranch_scc0 .LBB0_1855
	s_and_b64 vcc, exec, s[14:15]
	s_cbranch_vccz .LBB0_1858
	s_barrier

.LBB0_1942:
	s_waitcnt lgkmcnt(0)
	s_add_u32 s26, s8, 0xfff80080
	s_addc_u32 s27, s9, -1
	s_cmp_eq_u32 s53, 28
	s_cselect_b32 s29, s7, s27
	s_cselect_b32 s28, s21, s26
	s_cselect_b32 s27, s19, s52
	s_cselect_b32 s26, s50, s51
	v_lshl_add_u64 v[216:217], s[8:9], 0, v[190:191]
	s_add_i32 m0, s35, 0xc000
	s_nop 0
	global_load_lds_dwordx4 v[216:217], off
	v_lshl_add_u64 v[216:217], s[8:9], 0, v[192:193]
	s_add_i32 m0, s35, 0xe000
	s_nop 0
	global_load_lds_dwordx4 v[216:217], off
	ds_read_b128 v[130:133], v200
	ds_read_b128 v[134:137], v200 offset:1024
	ds_read_b128 v[138:141], v200 offset:2048
	ds_read_b128 v[142:145], v200 offset:3072
	ds_read_b128 v[146:149], v201
	ds_read_b128 v[150:153], v201 offset:1024
	ds_read_b128 v[154:157], v201 offset:2048
	ds_read_b128 v[158:161], v201 offset:3072
	ds_read_b128 v[162:165], v202
	ds_read_b128 v[166:169], v202 offset:1024
	ds_read_b128 v[170:173], v202 offset:2048
	ds_read_b128 v[174:177], v202 offset:3072
	ds_read_b128 v[178:181], v202 offset:4096
	ds_read_b128 v[204:207], v202 offset:5120
	ds_read_b128 v[208:211], v202 offset:6144
	ds_read_b128 v[212:215], v202 offset:7168
	s_waitcnt vmcnt(8)
	s_waitcnt lgkmcnt(0)
	s_barrier
	s_setprio 1
	v_mfma_f32_16x16x32_bf16 v[126:129], v[130:133], v[162:165], v[126:129]
	v_mfma_f32_16x16x32_bf16 v[122:125], v[138:141], v[162:165], v[122:125]
	v_mfma_f32_16x16x32_bf16 v[118:121], v[130:133], v[170:173], v[118:121]
	v_mfma_f32_16x16x32_bf16 v[110:113], v[138:141], v[170:173], v[110:113]
	v_mfma_f32_16x16x32_bf16 v[102:105], v[130:133], v[178:181], v[102:105]
	v_mfma_f32_16x16x32_bf16 v[94:97], v[138:141], v[178:181], v[94:97]
	v_mfma_f32_16x16x32_bf16 v[86:89], v[130:133], v[208:211], v[86:89]
	v_mfma_f32_16x16x32_bf16 v[78:81], v[138:141], v[208:211], v[78:81]
	v_mfma_f32_16x16x32_bf16 v[126:129], v[134:137], v[166:169], v[126:129]
	v_mfma_f32_16x16x32_bf16 v[122:125], v[142:145], v[166:169], v[122:125]
	v_mfma_f32_16x16x32_bf16 v[118:121], v[134:137], v[174:177], v[118:121]
	v_mfma_f32_16x16x32_bf16 v[110:113], v[142:145], v[174:177], v[110:113]
	v_mfma_f32_16x16x32_bf16 v[102:105], v[134:137], v[204:207], v[102:105]
	v_mfma_f32_16x16x32_bf16 v[94:97], v[142:145], v[204:207], v[94:97]
	v_mfma_f32_16x16x32_bf16 v[86:89], v[134:137], v[212:215], v[86:89]
	v_mfma_f32_16x16x32_bf16 v[78:81], v[142:145], v[212:215], v[78:81]
	s_setprio 0
	s_setprio 1
	v_mfma_f32_16x16x32_bf16 v[114:117], v[146:149], v[162:165], v[114:117]
	v_mfma_f32_16x16x32_bf16 v[106:109], v[154:157], v[162:165], v[106:109]
	v_mfma_f32_16x16x32_bf16 v[98:101], v[146:149], v[170:173], v[98:101]
	v_mfma_f32_16x16x32_bf16 v[90:93], v[154:157], v[170:173], v[90:93]
	v_mfma_f32_16x16x32_bf16 v[82:85], v[146:149], v[178:181], v[82:85]
	v_mfma_f32_16x16x32_bf16 v[74:77], v[154:157], v[178:181], v[74:77]
	v_mfma_f32_16x16x32_bf16 v[70:73], v[146:149], v[208:211], v[70:73]
	v_mfma_f32_16x16x32_bf16 v[66:69], v[154:157], v[208:211], v[66:69]
	v_mfma_f32_16x16x32_bf16 v[114:117], v[150:153], v[166:169], v[114:117]
	v_mfma_f32_16x16x32_bf16 v[106:109], v[158:161], v[166:169], v[106:109]
	v_mfma_f32_16x16x32_bf16 v[98:101], v[150:153], v[174:177], v[98:101]
	v_mfma_f32_16x16x32_bf16 v[90:93], v[158:161], v[174:177], v[90:93]
	v_mfma_f32_16x16x32_bf16 v[82:85], v[150:153], v[204:207], v[82:85]
	v_mfma_f32_16x16x32_bf16 v[74:77], v[158:161], v[204:207], v[74:77]
	v_mfma_f32_16x16x32_bf16 v[70:73], v[150:153], v[212:215], v[70:73]
	v_mfma_f32_16x16x32_bf16 v[66:69], v[158:161], v[212:215], v[66:69]
	s_barrier
	s_setprio 0
	s_add_i32 s54, s45, s31
	v_lshl_add_u64 v[216:217], s[26:27], 0, v[186:187]
	s_mov_b32 m0, s54
	s_nop 0
	global_load_lds_dwordx4 v[216:217], off
	s_add_i32 m0, s54, 0x2000
	s_add_u32 s54, s26, 0x80000
	v_lshl_add_u64 v[218:219], s[26:27], 0, v[182:183]
	s_addc_u32 s55, s27, 0
	s_add_i32 s56, s46, s31
	global_load_lds_dwordx4 v[218:219], off
	v_lshl_add_u64 v[220:221], s[54:55], 0, v[186:187]
	s_mov_b32 m0, s56
	v_lshl_add_u64 v[222:223], s[28:29], 0, v[184:185]
	global_load_lds_dwordx4 v[220:221], off
	v_lshl_add_u64 v[220:221], s[54:55], 0, v[182:183]
	s_add_i32 m0, s56, 0x2000
	s_nop 0
	global_load_lds_dwordx4 v[220:221], off
	v_lshl_add_u64 v[220:221], s[28:29], 0, v[188:189]
	s_mov_b32 m0, s35
	s_nop 0
	global_load_lds_dwordx4 v[220:221], off
	s_mov_b32 m0, s36
	s_nop 0
	global_load_lds_dwordx4 v[222:223], off
	ds_read_b128 v[162:165], v202 offset:16384
	ds_read_b128 v[166:169], v202 offset:17408
	ds_read_b128 v[170:173], v202 offset:18432
	ds_read_b128 v[174:177], v202 offset:19456
	ds_read_b128 v[178:181], v202 offset:20480
	ds_read_b128 v[204:207], v202 offset:21504
	ds_read_b128 v[208:211], v202 offset:22528
	ds_read_b128 v[212:215], v202 offset:23552
	s_waitcnt vmcnt(8)
	s_waitcnt lgkmcnt(0)
	s_barrier
	s_setprio 1
	v_mfma_f32_16x16x32_bf16 v[62:65], v[130:133], v[162:165], v[62:65]
	v_mfma_f32_16x16x32_bf16 v[58:61], v[138:141], v[162:165], v[58:61]
	v_mfma_f32_16x16x32_bf16 v[54:57], v[130:133], v[170:173], v[54:57]
	v_mfma_f32_16x16x32_bf16 v[46:49], v[138:141], v[170:173], v[46:49]
	v_mfma_f32_16x16x32_bf16 v[38:41], v[130:133], v[178:181], v[38:41]
	v_mfma_f32_16x16x32_bf16 v[30:33], v[138:141], v[178:181], v[30:33]
	v_mfma_f32_16x16x32_bf16 v[22:25], v[130:133], v[208:211], v[22:25]
	v_mfma_f32_16x16x32_bf16 v[14:17], v[138:141], v[208:211], v[14:17]
	v_mfma_f32_16x16x32_bf16 v[62:65], v[134:137], v[166:169], v[62:65]
	v_mfma_f32_16x16x32_bf16 v[58:61], v[142:145], v[166:169], v[58:61]
	v_mfma_f32_16x16x32_bf16 v[54:57], v[134:137], v[174:177], v[54:57]
	v_mfma_f32_16x16x32_bf16 v[46:49], v[142:145], v[174:177], v[46:49]
	v_mfma_f32_16x16x32_bf16 v[38:41], v[134:137], v[204:207], v[38:41]
	v_mfma_f32_16x16x32_bf16 v[30:33], v[142:145], v[204:207], v[30:33]
	v_mfma_f32_16x16x32_bf16 v[22:25], v[134:137], v[212:215], v[22:25]
	v_mfma_f32_16x16x32_bf16 v[14:17], v[142:145], v[212:215], v[14:17]
	s_setprio 0
	s_setprio 1
	v_mfma_f32_16x16x32_bf16 v[50:53], v[146:149], v[162:165], v[50:53]
	v_mfma_f32_16x16x32_bf16 v[42:45], v[154:157], v[162:165], v[42:45]
	v_mfma_f32_16x16x32_bf16 v[34:37], v[146:149], v[170:173], v[34:37]
	v_mfma_f32_16x16x32_bf16 v[26:29], v[154:157], v[170:173], v[26:29]
	v_mfma_f32_16x16x32_bf16 v[18:21], v[146:149], v[178:181], v[18:21]
	v_mfma_f32_16x16x32_bf16 v[10:13], v[154:157], v[178:181], v[10:13]
	v_mfma_f32_16x16x32_bf16 v[6:9], v[146:149], v[208:211], v[6:9]
	v_mfma_f32_16x16x32_bf16 v[2:5], v[154:157], v[208:211], v[2:5]
	v_mfma_f32_16x16x32_bf16 v[50:53], v[150:153], v[166:169], v[50:53]
	v_mfma_f32_16x16x32_bf16 v[42:45], v[158:161], v[166:169], v[42:45]
	v_mfma_f32_16x16x32_bf16 v[34:37], v[150:153], v[174:177], v[34:37]
	v_mfma_f32_16x16x32_bf16 v[26:29], v[158:161], v[174:177], v[26:29]
	v_mfma_f32_16x16x32_bf16 v[18:21], v[150:153], v[204:207], v[18:21]
	v_mfma_f32_16x16x32_bf16 v[10:13], v[158:161], v[204:207], v[10:13]
	v_mfma_f32_16x16x32_bf16 v[6:9], v[150:153], v[212:215], v[6:9]
	v_mfma_f32_16x16x32_bf16 v[2:5], v[158:161], v[212:215], v[2:5]
	s_barrier
	s_setprio 0
	s_add_i32 s54, 0, 0x18000
	s_add_i32 s55, 0, 0x1c000
	v_add_u32_e32 v142, s54, v199
	v_add_u32_e32 v158, s55, v199
	s_add_u32 s28, s28, 0x80000
	s_addc_u32 s29, s29, 0
	s_mov_b32 m0, s37
	v_lshl_add_u64 v[224:225], s[28:29], 0, v[188:189]
	global_load_lds_dwordx4 v[224:225], off
	v_lshl_add_u64 v[224:225], s[28:29], 0, v[184:185]
	s_mov_b32 m0, s38
	s_nop 0
	global_load_lds_dwordx4 v[224:225], off
	ds_read_b128 v[130:133], v142
	ds_read_b128 v[134:137], v142 offset:1024
	ds_read_b128 v[138:141], v142 offset:2048
	ds_read_b128 v[142:145], v142 offset:3072
	ds_read_b128 v[146:149], v158
	ds_read_b128 v[150:153], v158 offset:1024
	ds_read_b128 v[154:157], v158 offset:2048
	ds_read_b128 v[158:161], v158 offset:3072
	ds_read_b128 v[162:165], v202 offset:32768
	ds_read_b128 v[166:169], v202 offset:33792
	ds_read_b128 v[170:173], v202 offset:34816
	ds_read_b128 v[174:177], v202 offset:35840
	ds_read_b128 v[178:181], v202 offset:36864
	ds_read_b128 v[204:207], v202 offset:37888
	ds_read_b128 v[208:211], v202 offset:38912
	ds_read_b128 v[212:215], v202 offset:39936
	s_waitcnt vmcnt(8)
	s_waitcnt lgkmcnt(0)
	s_barrier
	s_setprio 1
	v_mfma_f32_16x16x32_bf16 v[126:129], v[130:133], v[162:165], v[126:129]
	v_mfma_f32_16x16x32_bf16 v[122:125], v[138:141], v[162:165], v[122:125]
	v_mfma_f32_16x16x32_bf16 v[118:121], v[130:133], v[170:173], v[118:121]
	v_mfma_f32_16x16x32_bf16 v[110:113], v[138:141], v[170:173], v[110:113]
	v_mfma_f32_16x16x32_bf16 v[102:105], v[130:133], v[178:181], v[102:105]
	v_mfma_f32_16x16x32_bf16 v[94:97], v[138:141], v[178:181], v[94:97]
	v_mfma_f32_16x16x32_bf16 v[86:89], v[130:133], v[208:211], v[86:89]
	v_mfma_f32_16x16x32_bf16 v[78:81], v[138:141], v[208:211], v[78:81]
	v_mfma_f32_16x16x32_bf16 v[126:129], v[134:137], v[166:169], v[126:129]
	v_mfma_f32_16x16x32_bf16 v[122:125], v[142:145], v[166:169], v[122:125]
	v_mfma_f32_16x16x32_bf16 v[118:121], v[134:137], v[174:177], v[118:121]
	v_mfma_f32_16x16x32_bf16 v[110:113], v[142:145], v[174:177], v[110:113]
	v_mfma_f32_16x16x32_bf16 v[102:105], v[134:137], v[204:207], v[102:105]
	v_mfma_f32_16x16x32_bf16 v[94:97], v[142:145], v[204:207], v[94:97]
	v_mfma_f32_16x16x32_bf16 v[86:89], v[134:137], v[212:215], v[86:89]
	v_mfma_f32_16x16x32_bf16 v[78:81], v[142:145], v[212:215], v[78:81]
	s_setprio 0
	s_setprio 1
	v_mfma_f32_16x16x32_bf16 v[114:117], v[146:149], v[162:165], v[114:117]
	v_mfma_f32_16x16x32_bf16 v[106:109], v[154:157], v[162:165], v[106:109]
	v_mfma_f32_16x16x32_bf16 v[98:101], v[146:149], v[170:173], v[98:101]
	v_mfma_f32_16x16x32_bf16 v[90:93], v[154:157], v[170:173], v[90:93]
	v_mfma_f32_16x16x32_bf16 v[82:85], v[146:149], v[178:181], v[82:85]
	v_mfma_f32_16x16x32_bf16 v[74:77], v[154:157], v[178:181], v[74:77]
	v_mfma_f32_16x16x32_bf16 v[70:73], v[146:149], v[208:211], v[70:73]
	v_mfma_f32_16x16x32_bf16 v[66:69], v[154:157], v[208:211], v[66:69]
	v_mfma_f32_16x16x32_bf16 v[114:117], v[150:153], v[166:169], v[114:117]
	v_mfma_f32_16x16x32_bf16 v[106:109], v[158:161], v[166:169], v[106:109]
	v_mfma_f32_16x16x32_bf16 v[98:101], v[150:153], v[174:177], v[98:101]
	v_mfma_f32_16x16x32_bf16 v[90:93], v[158:161], v[174:177], v[90:93]
	v_mfma_f32_16x16x32_bf16 v[82:85], v[150:153], v[204:207], v[82:85]
	v_mfma_f32_16x16x32_bf16 v[74:77], v[158:161], v[204:207], v[74:77]
	v_mfma_f32_16x16x32_bf16 v[70:73], v[150:153], v[212:215], v[70:73]
	v_mfma_f32_16x16x32_bf16 v[66:69], v[158:161], v[212:215], v[66:69]
	s_barrier
	s_setprio 0
	s_add_i32 s28, s54, s31
	v_lshl_add_u64 v[216:217], v[216:217], 0, s[12:13]
	s_mov_b32 m0, s28
	s_nop 0
	global_load_lds_dwordx4 v[216:217], off
	s_add_i32 m0, s28, 0x2000
	s_add_u32 s26, s26, 0x80080
	v_lshl_add_u64 v[216:217], v[218:219], 0, s[12:13]
	s_addc_u32 s27, s27, 0
	s_add_i32 s28, s55, s31
	global_load_lds_dwordx4 v[216:217], off
	v_lshl_add_u64 v[216:217], s[26:27], 0, v[186:187]
	s_mov_b32 m0, s28
	s_nop 0
	global_load_lds_dwordx4 v[216:217], off
	v_lshl_add_u64 v[216:217], s[26:27], 0, v[182:183]
	s_add_i32 m0, s28, 0x2000
	s_nop 0
	global_load_lds_dwordx4 v[216:217], off
	v_lshl_add_u64 v[216:217], v[220:221], 0, s[12:13]
	s_mov_b32 m0, s42
	s_nop 0
	global_load_lds_dwordx4 v[216:217], off
	v_lshl_add_u64 v[216:217], v[222:223], 0, s[12:13]
	s_mov_b32 m0, s43
	s_nop 0
	global_load_lds_dwordx4 v[216:217], off
	ds_read_b128 v[162:165], v202 offset:49152
	ds_read_b128 v[166:169], v202 offset:50176
	ds_read_b128 v[170:173], v202 offset:51200
	ds_read_b128 v[174:177], v202 offset:52224
	ds_read_b128 v[178:181], v202 offset:53248
	ds_read_b128 v[204:207], v202 offset:54272
	ds_read_b128 v[208:211], v202 offset:55296
	ds_read_b128 v[212:215], v202 offset:56320
	s_waitcnt vmcnt(8)
	s_waitcnt lgkmcnt(0)
	s_barrier
	s_setprio 1
	v_mfma_f32_16x16x32_bf16 v[62:65], v[130:133], v[162:165], v[62:65]
	v_mfma_f32_16x16x32_bf16 v[58:61], v[138:141], v[162:165], v[58:61]
	v_mfma_f32_16x16x32_bf16 v[54:57], v[130:133], v[170:173], v[54:57]
	v_mfma_f32_16x16x32_bf16 v[46:49], v[138:141], v[170:173], v[46:49]
	v_mfma_f32_16x16x32_bf16 v[38:41], v[130:133], v[178:181], v[38:41]
	v_mfma_f32_16x16x32_bf16 v[30:33], v[138:141], v[178:181], v[30:33]
	v_mfma_f32_16x16x32_bf16 v[22:25], v[130:133], v[208:211], v[22:25]
	v_mfma_f32_16x16x32_bf16 v[14:17], v[138:141], v[208:211], v[14:17]
	v_mfma_f32_16x16x32_bf16 v[62:65], v[134:137], v[166:169], v[62:65]
	v_mfma_f32_16x16x32_bf16 v[58:61], v[142:145], v[166:169], v[58:61]
	v_mfma_f32_16x16x32_bf16 v[54:57], v[134:137], v[174:177], v[54:57]
	v_mfma_f32_16x16x32_bf16 v[46:49], v[142:145], v[174:177], v[46:49]
	v_mfma_f32_16x16x32_bf16 v[38:41], v[134:137], v[204:207], v[38:41]
	v_mfma_f32_16x16x32_bf16 v[30:33], v[142:145], v[204:207], v[30:33]
	v_mfma_f32_16x16x32_bf16 v[22:25], v[134:137], v[212:215], v[22:25]
	v_mfma_f32_16x16x32_bf16 v[14:17], v[142:145], v[212:215], v[14:17]
	s_setprio 0
	s_setprio 1
	v_mfma_f32_16x16x32_bf16 v[50:53], v[146:149], v[162:165], v[50:53]
	v_mfma_f32_16x16x32_bf16 v[42:45], v[154:157], v[162:165], v[42:45]
	v_mfma_f32_16x16x32_bf16 v[34:37], v[146:149], v[170:173], v[34:37]
	v_mfma_f32_16x16x32_bf16 v[26:29], v[154:157], v[170:173], v[26:29]
	v_mfma_f32_16x16x32_bf16 v[18:21], v[146:149], v[178:181], v[18:21]
	v_mfma_f32_16x16x32_bf16 v[10:13], v[154:157], v[178:181], v[10:13]
	v_mfma_f32_16x16x32_bf16 v[6:9], v[146:149], v[208:211], v[6:9]
	v_mfma_f32_16x16x32_bf16 v[2:5], v[154:157], v[208:211], v[2:5]
	v_mfma_f32_16x16x32_bf16 v[50:53], v[150:153], v[166:169], v[50:53]
	v_mfma_f32_16x16x32_bf16 v[42:45], v[158:161], v[166:169], v[42:45]
	v_mfma_f32_16x16x32_bf16 v[34:37], v[150:153], v[174:177], v[34:37]
	v_mfma_f32_16x16x32_bf16 v[26:29], v[158:161], v[174:177], v[26:29]
	v_mfma_f32_16x16x32_bf16 v[18:21], v[150:153], v[204:207], v[18:21]
	v_mfma_f32_16x16x32_bf16 v[10:13], v[158:161], v[204:207], v[10:13]
	v_mfma_f32_16x16x32_bf16 v[6:9], v[150:153], v[212:215], v[6:9]
	v_mfma_f32_16x16x32_bf16 v[2:5], v[158:161], v[212:215], v[2:5]
	s_barrier
	s_setprio 0
	s_add_i32 s53, s53, 2
	s_add_u32 s8, s8, 0x100
	s_addc_u32 s9, s9, 0
	s_add_u32 s51, s51, 0x100
	s_addc_u32 s52, s52, 0
	s_cmp_gt_u32 s53, 29
	s_cbranch_scc0 .LBB0_1942
	s_and_b64 vcc, exec, s[14:15]
	s_cbranch_vccz .LBB0_1945
	s_barrier

.LBB0_2118:
	ds_read_b128 v[142:145], v148
	ds_read_b128 v[152:155], v148 offset:1024
	ds_read_b128 v[156:159], v148 offset:2048
	ds_read_b128 v[160:163], v148 offset:3072
	ds_read_b128 v[164:167], v149
	ds_read_b128 v[168:171], v149 offset:1024
	ds_read_b128 v[172:175], v149 offset:2048
	ds_read_b128 v[176:179], v149 offset:3072
	s_add_u32 s20, s18, 0x100
	s_addc_u32 s21, s19, 0
	s_cmpk_eq_i32 s49, 0x54
	s_cselect_b32 s25, s7, s21
	s_cselect_b32 s24, s6, s20
	s_cselect_b32 s23, s17, s48
	s_cselect_b32 s22, s16, s47
	v_lshl_add_u64 v[212:213], s[18:19], 0, v[134:135]
	s_add_i32 m0, s30, 0xc000
	ds_read_b128 v[180:183], v150
	ds_read_b128 v[184:187], v150 offset:1024
	ds_read_b128 v[188:191], v150 offset:2048
	ds_read_b128 v[192:195], v150 offset:3072
	ds_read_b128 v[196:199], v150 offset:4096
	ds_read_b128 v[200:203], v150 offset:5120
	ds_read_b128 v[204:207], v150 offset:6144
	ds_read_b128 v[208:211], v150 offset:7168
	global_load_lds_dwordx4 v[212:213], off
	v_lshl_add_u64 v[212:213], s[18:19], 0, v[136:137]
	s_add_i32 m0, s30, 0xe000
	s_nop 0
	global_load_lds_dwordx4 v[212:213], off
	s_waitcnt vmcnt(8)
	s_waitcnt lgkmcnt(0)
	s_barrier
	s_setprio 1
	v_mfma_f32_16x16x32_bf16 v[126:129], v[142:145], v[180:183], v[126:129]
	v_mfma_f32_16x16x32_bf16 v[122:125], v[156:159], v[180:183], v[122:125]
	v_mfma_f32_16x16x32_bf16 v[110:113], v[142:145], v[188:191], v[110:113]
	v_mfma_f32_16x16x32_bf16 v[106:109], v[156:159], v[188:191], v[106:109]
	v_mfma_f32_16x16x32_bf16 v[94:97], v[142:145], v[196:199], v[94:97]
	v_mfma_f32_16x16x32_bf16 v[90:93], v[156:159], v[196:199], v[90:93]
	v_mfma_f32_16x16x32_bf16 v[78:81], v[142:145], v[204:207], v[78:81]
	v_mfma_f32_16x16x32_bf16 v[74:77], v[156:159], v[204:207], v[74:77]
	v_mfma_f32_16x16x32_bf16 v[126:129], v[152:155], v[184:187], v[126:129]
	v_mfma_f32_16x16x32_bf16 v[122:125], v[160:163], v[184:187], v[122:125]
	v_mfma_f32_16x16x32_bf16 v[110:113], v[152:155], v[192:195], v[110:113]
	v_mfma_f32_16x16x32_bf16 v[106:109], v[160:163], v[192:195], v[106:109]
	v_mfma_f32_16x16x32_bf16 v[94:97], v[152:155], v[200:203], v[94:97]
	v_mfma_f32_16x16x32_bf16 v[90:93], v[160:163], v[200:203], v[90:93]
	v_mfma_f32_16x16x32_bf16 v[78:81], v[152:155], v[208:211], v[78:81]
	v_mfma_f32_16x16x32_bf16 v[74:77], v[160:163], v[208:211], v[74:77]
	s_setprio 0
	s_setprio 1
	v_mfma_f32_16x16x32_bf16 v[118:121], v[164:167], v[180:183], v[118:121]
	v_mfma_f32_16x16x32_bf16 v[114:117], v[172:175], v[180:183], v[114:117]
	v_mfma_f32_16x16x32_bf16 v[102:105], v[164:167], v[188:191], v[102:105]
	v_mfma_f32_16x16x32_bf16 v[98:101], v[172:175], v[188:191], v[98:101]
	v_mfma_f32_16x16x32_bf16 v[86:89], v[164:167], v[196:199], v[86:89]
	v_mfma_f32_16x16x32_bf16 v[82:85], v[172:175], v[196:199], v[82:85]
	v_mfma_f32_16x16x32_bf16 v[70:73], v[164:167], v[204:207], v[70:73]
	v_mfma_f32_16x16x32_bf16 v[66:69], v[172:175], v[204:207], v[66:69]
	v_mfma_f32_16x16x32_bf16 v[118:121], v[168:171], v[184:187], v[118:121]
	v_mfma_f32_16x16x32_bf16 v[114:117], v[176:179], v[184:187], v[114:117]
	v_mfma_f32_16x16x32_bf16 v[102:105], v[168:171], v[192:195], v[102:105]
	v_mfma_f32_16x16x32_bf16 v[98:101], v[176:179], v[192:195], v[98:101]
	v_mfma_f32_16x16x32_bf16 v[86:89], v[168:171], v[200:203], v[86:89]
	v_mfma_f32_16x16x32_bf16 v[82:85], v[176:179], v[200:203], v[82:85]
	v_mfma_f32_16x16x32_bf16 v[70:73], v[168:171], v[208:211], v[70:73]
	v_mfma_f32_16x16x32_bf16 v[66:69], v[176:179], v[208:211], v[66:69]
	s_barrier
	s_setprio 0
	s_add_i32 s18, s42, s29
	v_lshl_add_u64 v[212:213], s[22:23], 0, v[130:131]
	s_mov_b32 m0, s18
	ds_read_b128 v[180:183], v150 offset:16384
	ds_read_b128 v[184:187], v150 offset:17408
	ds_read_b128 v[188:191], v150 offset:18432
	ds_read_b128 v[192:195], v150 offset:19456
	ds_read_b128 v[196:199], v150 offset:20480
	ds_read_b128 v[200:203], v150 offset:21504
	ds_read_b128 v[204:207], v150 offset:22528
	ds_read_b128 v[208:211], v150 offset:23552
	global_load_lds_dwordx4 v[212:213], off
	s_add_i32 m0, s18, 0x2000
	s_add_u32 s18, s22, 0x160000
	v_lshl_add_u64 v[214:215], s[22:23], 0, v[132:133]
	s_addc_u32 s19, s23, 0
	s_add_i32 s50, s43, s29
	global_load_lds_dwordx4 v[214:215], off
	v_lshl_add_u64 v[216:217], s[18:19], 0, v[130:131]
	s_mov_b32 m0, s50
	v_lshl_add_u64 v[218:219], s[24:25], 0, v[132:133]
	global_load_lds_dwordx4 v[216:217], off
	v_lshl_add_u64 v[216:217], s[18:19], 0, v[132:133]
	s_add_i32 m0, s50, 0x2000
	s_nop 0
	global_load_lds_dwordx4 v[216:217], off
	v_lshl_add_u64 v[216:217], s[24:25], 0, v[130:131]
	s_mov_b32 m0, s30
	s_nop 0
	global_load_lds_dwordx4 v[216:217], off
	s_mov_b32 m0, s31
	s_nop 0
	global_load_lds_dwordx4 v[218:219], off
	s_waitcnt vmcnt(8)
	s_waitcnt lgkmcnt(0)
	s_barrier
	s_setprio 1
	v_mfma_f32_16x16x32_bf16 v[62:65], v[142:145], v[180:183], v[62:65]
	v_mfma_f32_16x16x32_bf16 v[58:61], v[156:159], v[180:183], v[58:61]
	v_mfma_f32_16x16x32_bf16 v[46:49], v[142:145], v[188:191], v[46:49]
	v_mfma_f32_16x16x32_bf16 v[42:45], v[156:159], v[188:191], v[42:45]
	v_mfma_f32_16x16x32_bf16 v[30:33], v[142:145], v[196:199], v[30:33]
	v_mfma_f32_16x16x32_bf16 v[26:29], v[156:159], v[196:199], v[26:29]
	v_mfma_f32_16x16x32_bf16 v[14:17], v[142:145], v[204:207], v[14:17]
	v_mfma_f32_16x16x32_bf16 v[10:13], v[156:159], v[204:207], v[10:13]
	v_mfma_f32_16x16x32_bf16 v[62:65], v[152:155], v[184:187], v[62:65]
	v_mfma_f32_16x16x32_bf16 v[58:61], v[160:163], v[184:187], v[58:61]
	v_mfma_f32_16x16x32_bf16 v[46:49], v[152:155], v[192:195], v[46:49]
	v_mfma_f32_16x16x32_bf16 v[42:45], v[160:163], v[192:195], v[42:45]
	v_mfma_f32_16x16x32_bf16 v[30:33], v[152:155], v[200:203], v[30:33]
	v_mfma_f32_16x16x32_bf16 v[26:29], v[160:163], v[200:203], v[26:29]
	v_mfma_f32_16x16x32_bf16 v[14:17], v[152:155], v[208:211], v[14:17]
	v_mfma_f32_16x16x32_bf16 v[10:13], v[160:163], v[208:211], v[10:13]
	s_setprio 0
	s_setprio 1
	v_mfma_f32_16x16x32_bf16 v[54:57], v[164:167], v[180:183], v[54:57]
	v_mfma_f32_16x16x32_bf16 v[50:53], v[172:175], v[180:183], v[50:53]
	v_mfma_f32_16x16x32_bf16 v[38:41], v[164:167], v[188:191], v[38:41]
	v_mfma_f32_16x16x32_bf16 v[34:37], v[172:175], v[188:191], v[34:37]
	v_mfma_f32_16x16x32_bf16 v[22:25], v[164:167], v[196:199], v[22:25]
	v_mfma_f32_16x16x32_bf16 v[18:21], v[172:175], v[196:199], v[18:21]
	v_mfma_f32_16x16x32_bf16 v[6:9], v[164:167], v[204:207], v[6:9]
	v_mfma_f32_16x16x32_bf16 v[2:5], v[172:175], v[204:207], v[2:5]
	v_mfma_f32_16x16x32_bf16 v[54:57], v[168:171], v[184:187], v[54:57]
	v_mfma_f32_16x16x32_bf16 v[50:53], v[176:179], v[184:187], v[50:53]
	v_mfma_f32_16x16x32_bf16 v[38:41], v[168:171], v[192:195], v[38:41]
	v_mfma_f32_16x16x32_bf16 v[34:37], v[176:179], v[192:195], v[34:37]
	v_mfma_f32_16x16x32_bf16 v[22:25], v[168:171], v[200:203], v[22:25]
	v_mfma_f32_16x16x32_bf16 v[18:21], v[176:179], v[200:203], v[18:21]
	v_mfma_f32_16x16x32_bf16 v[6:9], v[168:171], v[208:211], v[6:9]
	v_mfma_f32_16x16x32_bf16 v[2:5], v[176:179], v[208:211], v[2:5]
	s_barrier
	s_setprio 0
	s_add_i32 s50, 0, 0x18000
	s_add_i32 s51, 0, 0x1c000
	v_add_u32_e32 v160, s50, v147
	v_add_u32_e32 v176, s51, v147
	ds_read_b128 v[142:145], v160
	ds_read_b128 v[152:155], v160 offset:1024
	ds_read_b128 v[156:159], v160 offset:2048
	ds_read_b128 v[160:163], v160 offset:3072
	ds_read_b128 v[164:167], v176
	ds_read_b128 v[168:171], v176 offset:1024
	ds_read_b128 v[172:175], v176 offset:2048
	ds_read_b128 v[176:179], v176 offset:3072
	s_add_u32 s18, s24, 0x160000
	s_addc_u32 s19, s25, 0
	s_mov_b32 m0, s33
	v_lshl_add_u64 v[220:221], s[18:19], 0, v[130:131]
	ds_read_b128 v[180:183], v150 offset:32768
	ds_read_b128 v[184:187], v150 offset:33792
	ds_read_b128 v[188:191], v150 offset:34816
	ds_read_b128 v[192:195], v150 offset:35840
	ds_read_b128 v[196:199], v150 offset:36864
	ds_read_b128 v[200:203], v150 offset:37888
	ds_read_b128 v[204:207], v150 offset:38912
	ds_read_b128 v[208:211], v150 offset:39936
	global_load_lds_dwordx4 v[220:221], off
	v_lshl_add_u64 v[220:221], s[18:19], 0, v[132:133]
	s_mov_b32 m0, s34
	s_nop 0
	global_load_lds_dwordx4 v[220:221], off
	s_waitcnt vmcnt(8)
	s_waitcnt lgkmcnt(0)
	s_barrier
	s_setprio 1
	v_mfma_f32_16x16x32_bf16 v[126:129], v[142:145], v[180:183], v[126:129]
	v_mfma_f32_16x16x32_bf16 v[122:125], v[156:159], v[180:183], v[122:125]
	v_mfma_f32_16x16x32_bf16 v[110:113], v[142:145], v[188:191], v[110:113]
	v_mfma_f32_16x16x32_bf16 v[106:109], v[156:159], v[188:191], v[106:109]
	v_mfma_f32_16x16x32_bf16 v[94:97], v[142:145], v[196:199], v[94:97]
	v_mfma_f32_16x16x32_bf16 v[90:93], v[156:159], v[196:199], v[90:93]
	v_mfma_f32_16x16x32_bf16 v[78:81], v[142:145], v[204:207], v[78:81]
	v_mfma_f32_16x16x32_bf16 v[74:77], v[156:159], v[204:207], v[74:77]
	v_mfma_f32_16x16x32_bf16 v[126:129], v[152:155], v[184:187], v[126:129]
	v_mfma_f32_16x16x32_bf16 v[122:125], v[160:163], v[184:187], v[122:125]
	v_mfma_f32_16x16x32_bf16 v[110:113], v[152:155], v[192:195], v[110:113]
	v_mfma_f32_16x16x32_bf16 v[106:109], v[160:163], v[192:195], v[106:109]
	v_mfma_f32_16x16x32_bf16 v[94:97], v[152:155], v[200:203], v[94:97]
	v_mfma_f32_16x16x32_bf16 v[90:93], v[160:163], v[200:203], v[90:93]
	v_mfma_f32_16x16x32_bf16 v[78:81], v[152:155], v[208:211], v[78:81]
	v_mfma_f32_16x16x32_bf16 v[74:77], v[160:163], v[208:211], v[74:77]
	s_setprio 0
	s_setprio 1
	v_mfma_f32_16x16x32_bf16 v[118:121], v[164:167], v[180:183], v[118:121]
	v_mfma_f32_16x16x32_bf16 v[114:117], v[172:175], v[180:183], v[114:117]
	v_mfma_f32_16x16x32_bf16 v[102:105], v[164:167], v[188:191], v[102:105]
	v_mfma_f32_16x16x32_bf16 v[98:101], v[172:175], v[188:191], v[98:101]
	v_mfma_f32_16x16x32_bf16 v[86:89], v[164:167], v[196:199], v[86:89]
	v_mfma_f32_16x16x32_bf16 v[82:85], v[172:175], v[196:199], v[82:85]
	v_mfma_f32_16x16x32_bf16 v[70:73], v[164:167], v[204:207], v[70:73]
	v_mfma_f32_16x16x32_bf16 v[66:69], v[172:175], v[204:207], v[66:69]
	v_mfma_f32_16x16x32_bf16 v[118:121], v[168:171], v[184:187], v[118:121]
	v_mfma_f32_16x16x32_bf16 v[114:117], v[176:179], v[184:187], v[114:117]
	v_mfma_f32_16x16x32_bf16 v[102:105], v[168:171], v[192:195], v[102:105]
	v_mfma_f32_16x16x32_bf16 v[98:101], v[176:179], v[192:195], v[98:101]
	v_mfma_f32_16x16x32_bf16 v[86:89], v[168:171], v[200:203], v[86:89]
	v_mfma_f32_16x16x32_bf16 v[82:85], v[176:179], v[200:203], v[82:85]
	v_mfma_f32_16x16x32_bf16 v[70:73], v[168:171], v[208:211], v[70:73]
	v_mfma_f32_16x16x32_bf16 v[66:69], v[176:179], v[208:211], v[66:69]
	s_barrier
	s_setprio 0
	s_add_i32 s18, s50, s29
	v_lshl_add_u64 v[212:213], v[212:213], 0, s[12:13]
	s_mov_b32 m0, s18
	ds_read_b128 v[180:183], v150 offset:49152
	ds_read_b128 v[184:187], v150 offset:50176
	ds_read_b128 v[188:191], v150 offset:51200
	ds_read_b128 v[192:195], v150 offset:52224
	ds_read_b128 v[196:199], v150 offset:53248
	ds_read_b128 v[200:203], v150 offset:54272
	ds_read_b128 v[204:207], v150 offset:55296
	ds_read_b128 v[208:211], v150 offset:56320
	global_load_lds_dwordx4 v[212:213], off
	s_add_i32 m0, s18, 0x2000
	s_add_u32 s18, s22, 0x160080
	v_lshl_add_u64 v[212:213], v[214:215], 0, s[12:13]
	s_addc_u32 s19, s23, 0
	s_add_i32 s22, s51, s29
	global_load_lds_dwordx4 v[212:213], off
	v_lshl_add_u64 v[212:213], s[18:19], 0, v[130:131]
	s_mov_b32 m0, s22
	s_nop 0
	global_load_lds_dwordx4 v[212:213], off
	v_lshl_add_u64 v[212:213], s[18:19], 0, v[132:133]
	s_add_i32 m0, s22, 0x2000
	s_nop 0
	global_load_lds_dwordx4 v[212:213], off
	v_lshl_add_u64 v[212:213], v[216:217], 0, s[12:13]
	s_mov_b32 m0, s38
	s_nop 0
	global_load_lds_dwordx4 v[212:213], off
	v_lshl_add_u64 v[212:213], v[218:219], 0, s[12:13]
	s_mov_b32 m0, s39
	s_nop 0
	global_load_lds_dwordx4 v[212:213], off
	s_waitcnt vmcnt(8)
	s_waitcnt lgkmcnt(0)
	s_barrier
	s_setprio 1
	v_mfma_f32_16x16x32_bf16 v[62:65], v[142:145], v[180:183], v[62:65]
	v_mfma_f32_16x16x32_bf16 v[58:61], v[156:159], v[180:183], v[58:61]
	v_mfma_f32_16x16x32_bf16 v[46:49], v[142:145], v[188:191], v[46:49]
	v_mfma_f32_16x16x32_bf16 v[42:45], v[156:159], v[188:191], v[42:45]
	v_mfma_f32_16x16x32_bf16 v[30:33], v[142:145], v[196:199], v[30:33]
	v_mfma_f32_16x16x32_bf16 v[26:29], v[156:159], v[196:199], v[26:29]
	v_mfma_f32_16x16x32_bf16 v[14:17], v[142:145], v[204:207], v[14:17]
	v_mfma_f32_16x16x32_bf16 v[10:13], v[156:159], v[204:207], v[10:13]
	v_mfma_f32_16x16x32_bf16 v[62:65], v[152:155], v[184:187], v[62:65]
	v_mfma_f32_16x16x32_bf16 v[58:61], v[160:163], v[184:187], v[58:61]
	v_mfma_f32_16x16x32_bf16 v[46:49], v[152:155], v[192:195], v[46:49]
	v_mfma_f32_16x16x32_bf16 v[42:45], v[160:163], v[192:195], v[42:45]
	v_mfma_f32_16x16x32_bf16 v[30:33], v[152:155], v[200:203], v[30:33]
	v_mfma_f32_16x16x32_bf16 v[26:29], v[160:163], v[200:203], v[26:29]
	v_mfma_f32_16x16x32_bf16 v[14:17], v[152:155], v[208:211], v[14:17]
	v_mfma_f32_16x16x32_bf16 v[10:13], v[160:163], v[208:211], v[10:13]
	s_setprio 0
	s_setprio 1
	v_mfma_f32_16x16x32_bf16 v[54:57], v[164:167], v[180:183], v[54:57]
	v_mfma_f32_16x16x32_bf16 v[50:53], v[172:175], v[180:183], v[50:53]
	v_mfma_f32_16x16x32_bf16 v[38:41], v[164:167], v[188:191], v[38:41]
	v_mfma_f32_16x16x32_bf16 v[34:37], v[172:175], v[188:191], v[34:37]
	v_mfma_f32_16x16x32_bf16 v[22:25], v[164:167], v[196:199], v[22:25]
	v_mfma_f32_16x16x32_bf16 v[18:21], v[172:175], v[196:199], v[18:21]
	v_mfma_f32_16x16x32_bf16 v[6:9], v[164:167], v[204:207], v[6:9]
	v_mfma_f32_16x16x32_bf16 v[2:5], v[172:175], v[204:207], v[2:5]
	v_mfma_f32_16x16x32_bf16 v[54:57], v[168:171], v[184:187], v[54:57]
	v_mfma_f32_16x16x32_bf16 v[50:53], v[176:179], v[184:187], v[50:53]
	v_mfma_f32_16x16x32_bf16 v[38:41], v[168:171], v[192:195], v[38:41]
	v_mfma_f32_16x16x32_bf16 v[34:37], v[176:179], v[192:195], v[34:37]
	v_mfma_f32_16x16x32_bf16 v[22:25], v[168:171], v[200:203], v[22:25]
	v_mfma_f32_16x16x32_bf16 v[18:21], v[176:179], v[200:203], v[18:21]
	v_mfma_f32_16x16x32_bf16 v[6:9], v[168:171], v[208:211], v[6:9]
	v_mfma_f32_16x16x32_bf16 v[2:5], v[176:179], v[208:211], v[2:5]
	s_barrier
	s_setprio 0
	s_add_i32 s49, s49, 2
	s_add_u32 s47, s47, 0x100
	s_addc_u32 s48, s48, 0
	s_cmpk_gt_u32 s49, 0x55
	s_mov_b64 s[18:19], s[20:21]
	s_cbranch_scc0 .LBB0_2118
	s_and_b64 vcc, exec, s[14:15]
	s_cbranch_vccz .LBB0_2121
	s_barrier

.LBB0_2207:
	ds_read_b128 v[130:133], v197
	ds_read_b128 v[134:137], v197 offset:1024
	ds_read_b128 v[138:141], v197 offset:2048
	ds_read_b128 v[142:145], v197 offset:3072
	ds_read_b128 v[146:149], v198
	ds_read_b128 v[150:153], v198 offset:1024
	ds_read_b128 v[154:157], v198 offset:2048
	ds_read_b128 v[158:161], v198 offset:3072
	s_add_u32 s28, s10, 0xfff80080
	s_addc_u32 s29, s11, -1
	s_cmp_eq_u32 s36, 28
	s_cselect_b32 s31, s7, s29
	s_cselect_b32 s30, s9, s28
	s_cselect_b32 s29, s21, s35
	s_cselect_b32 s28, s23, s34
	v_lshl_add_u64 v[194:195], s[10:11], 0, v[184:185]
	s_add_i32 m0, s39, 0xc000
	ds_read_b128 v[162:165], v199
	ds_read_b128 v[166:169], v199 offset:1024
	ds_read_b128 v[170:173], v199 offset:2048
	ds_read_b128 v[174:177], v199 offset:3072
	ds_read_b128 v[202:205], v199 offset:4096
	ds_read_b128 v[206:209], v199 offset:5120
	ds_read_b128 v[210:213], v199 offset:6144
	ds_read_b128 v[214:217], v199 offset:7168
	global_load_lds_dwordx4 v[194:195], off
	v_lshl_add_u64 v[194:195], s[10:11], 0, v[186:187]
	s_add_i32 m0, s39, 0xe000
	s_nop 0
	global_load_lds_dwordx4 v[194:195], off
	s_waitcnt vmcnt(8)
	s_waitcnt lgkmcnt(0)
	s_barrier
	s_setprio 1
	v_mfma_f32_16x16x32_bf16 v[126:129], v[130:133], v[162:165], v[126:129]
	v_mfma_f32_16x16x32_bf16 v[122:125], v[138:141], v[162:165], v[122:125]
	v_mfma_f32_16x16x32_bf16 v[110:113], v[130:133], v[170:173], v[110:113]
	v_mfma_f32_16x16x32_bf16 v[106:109], v[138:141], v[170:173], v[106:109]
	v_mfma_f32_16x16x32_bf16 v[94:97], v[130:133], v[202:205], v[94:97]
	v_mfma_f32_16x16x32_bf16 v[90:93], v[138:141], v[202:205], v[90:93]
	v_mfma_f32_16x16x32_bf16 v[78:81], v[130:133], v[210:213], v[78:81]
	v_mfma_f32_16x16x32_bf16 v[74:77], v[138:141], v[210:213], v[74:77]
	v_mfma_f32_16x16x32_bf16 v[126:129], v[134:137], v[166:169], v[126:129]
	v_mfma_f32_16x16x32_bf16 v[122:125], v[142:145], v[166:169], v[122:125]
	v_mfma_f32_16x16x32_bf16 v[110:113], v[134:137], v[174:177], v[110:113]
	v_mfma_f32_16x16x32_bf16 v[106:109], v[142:145], v[174:177], v[106:109]
	v_mfma_f32_16x16x32_bf16 v[94:97], v[134:137], v[206:209], v[94:97]
	v_mfma_f32_16x16x32_bf16 v[90:93], v[142:145], v[206:209], v[90:93]
	v_mfma_f32_16x16x32_bf16 v[78:81], v[134:137], v[214:217], v[78:81]
	v_mfma_f32_16x16x32_bf16 v[74:77], v[142:145], v[214:217], v[74:77]
	s_setprio 0
	s_setprio 1
	v_mfma_f32_16x16x32_bf16 v[118:121], v[146:149], v[162:165], v[118:121]
	v_mfma_f32_16x16x32_bf16 v[114:117], v[154:157], v[162:165], v[114:117]
	v_mfma_f32_16x16x32_bf16 v[102:105], v[146:149], v[170:173], v[102:105]
	v_mfma_f32_16x16x32_bf16 v[98:101], v[154:157], v[170:173], v[98:101]
	v_mfma_f32_16x16x32_bf16 v[86:89], v[146:149], v[202:205], v[86:89]
	v_mfma_f32_16x16x32_bf16 v[82:85], v[154:157], v[202:205], v[82:85]
	v_mfma_f32_16x16x32_bf16 v[70:73], v[146:149], v[210:213], v[70:73]
	v_mfma_f32_16x16x32_bf16 v[66:69], v[154:157], v[210:213], v[66:69]
	v_mfma_f32_16x16x32_bf16 v[118:121], v[150:153], v[166:169], v[118:121]
	v_mfma_f32_16x16x32_bf16 v[114:117], v[158:161], v[166:169], v[114:117]
	v_mfma_f32_16x16x32_bf16 v[102:105], v[150:153], v[174:177], v[102:105]
	v_mfma_f32_16x16x32_bf16 v[98:101], v[158:161], v[174:177], v[98:101]
	v_mfma_f32_16x16x32_bf16 v[86:89], v[150:153], v[206:209], v[86:89]
	v_mfma_f32_16x16x32_bf16 v[82:85], v[158:161], v[206:209], v[82:85]
	v_mfma_f32_16x16x32_bf16 v[70:73], v[150:153], v[214:217], v[70:73]
	v_mfma_f32_16x16x32_bf16 v[66:69], v[158:161], v[214:217], v[66:69]
	s_barrier
	s_setprio 0
	s_add_i32 s37, s52, s38
	v_lshl_add_u64 v[194:195], s[28:29], 0, v[178:179]
	s_mov_b32 m0, s37
	ds_read_b128 v[162:165], v199 offset:16384
	ds_read_b128 v[166:169], v199 offset:17408
	ds_read_b128 v[170:173], v199 offset:18432
	ds_read_b128 v[174:177], v199 offset:19456
	ds_read_b128 v[202:205], v199 offset:20480
	ds_read_b128 v[206:209], v199 offset:21504
	ds_read_b128 v[210:213], v199 offset:22528
	ds_read_b128 v[214:217], v199 offset:23552
	global_load_lds_dwordx4 v[194:195], off
	s_add_i32 m0, s37, 0x2000
	s_add_u32 s56, s28, 0x80000
	v_lshl_add_u64 v[218:219], s[28:29], 0, v[180:181]
	s_addc_u32 s57, s29, 0
	s_add_i32 s37, s53, s38
	global_load_lds_dwordx4 v[218:219], off
	v_lshl_add_u64 v[220:221], s[56:57], 0, v[178:179]
	s_mov_b32 m0, s37
	v_lshl_add_u64 v[222:223], s[30:31], 0, v[180:181]
	global_load_lds_dwordx4 v[220:221], off
	v_lshl_add_u64 v[220:221], s[56:57], 0, v[180:181]
	s_add_i32 m0, s37, 0x2000
	s_nop 0
	global_load_lds_dwordx4 v[220:221], off
	v_lshl_add_u64 v[220:221], s[30:31], 0, v[178:179]
	s_mov_b32 m0, s39
	s_nop 0
	global_load_lds_dwordx4 v[220:221], off
	s_mov_b32 m0, s40
	s_nop 0
	global_load_lds_dwordx4 v[222:223], off
	s_waitcnt vmcnt(8)
	s_waitcnt lgkmcnt(0)
	s_barrier
	s_setprio 1
	v_mfma_f32_16x16x32_bf16 v[62:65], v[130:133], v[162:165], v[62:65]
	v_mfma_f32_16x16x32_bf16 v[58:61], v[138:141], v[162:165], v[58:61]
	v_mfma_f32_16x16x32_bf16 v[46:49], v[130:133], v[170:173], v[46:49]
	v_mfma_f32_16x16x32_bf16 v[42:45], v[138:141], v[170:173], v[42:45]
	v_mfma_f32_16x16x32_bf16 v[30:33], v[130:133], v[202:205], v[30:33]
	v_mfma_f32_16x16x32_bf16 v[26:29], v[138:141], v[202:205], v[26:29]
	v_mfma_f32_16x16x32_bf16 v[14:17], v[130:133], v[210:213], v[14:17]
	v_mfma_f32_16x16x32_bf16 v[10:13], v[138:141], v[210:213], v[10:13]
	v_mfma_f32_16x16x32_bf16 v[62:65], v[134:137], v[166:169], v[62:65]
	v_mfma_f32_16x16x32_bf16 v[58:61], v[142:145], v[166:169], v[58:61]
	v_mfma_f32_16x16x32_bf16 v[46:49], v[134:137], v[174:177], v[46:49]
	v_mfma_f32_16x16x32_bf16 v[42:45], v[142:145], v[174:177], v[42:45]
	v_mfma_f32_16x16x32_bf16 v[30:33], v[134:137], v[206:209], v[30:33]
	v_mfma_f32_16x16x32_bf16 v[26:29], v[142:145], v[206:209], v[26:29]
	v_mfma_f32_16x16x32_bf16 v[14:17], v[134:137], v[214:217], v[14:17]
	v_mfma_f32_16x16x32_bf16 v[10:13], v[142:145], v[214:217], v[10:13]
	s_setprio 0
	s_setprio 1
	v_mfma_f32_16x16x32_bf16 v[54:57], v[146:149], v[162:165], v[54:57]
	v_mfma_f32_16x16x32_bf16 v[50:53], v[154:157], v[162:165], v[50:53]
	v_mfma_f32_16x16x32_bf16 v[38:41], v[146:149], v[170:173], v[38:41]
	v_mfma_f32_16x16x32_bf16 v[34:37], v[154:157], v[170:173], v[34:37]
	v_mfma_f32_16x16x32_bf16 v[22:25], v[146:149], v[202:205], v[22:25]
	v_mfma_f32_16x16x32_bf16 v[18:21], v[154:157], v[202:205], v[18:21]
	v_mfma_f32_16x16x32_bf16 v[6:9], v[146:149], v[210:213], v[6:9]
	v_mfma_f32_16x16x32_bf16 v[2:5], v[154:157], v[210:213], v[2:5]
	v_mfma_f32_16x16x32_bf16 v[54:57], v[150:153], v[166:169], v[54:57]
	v_mfma_f32_16x16x32_bf16 v[50:53], v[158:161], v[166:169], v[50:53]
	v_mfma_f32_16x16x32_bf16 v[38:41], v[150:153], v[174:177], v[38:41]
	v_mfma_f32_16x16x32_bf16 v[34:37], v[158:161], v[174:177], v[34:37]
	v_mfma_f32_16x16x32_bf16 v[22:25], v[150:153], v[206:209], v[22:25]
	v_mfma_f32_16x16x32_bf16 v[18:21], v[158:161], v[206:209], v[18:21]
	v_mfma_f32_16x16x32_bf16 v[6:9], v[150:153], v[214:217], v[6:9]
	v_mfma_f32_16x16x32_bf16 v[2:5], v[158:161], v[214:217], v[2:5]
	s_barrier
	s_setprio 0
	s_add_i32 s37, 0, 0x18000
	s_add_i32 s56, 0, 0x1c000
	v_add_u32_e32 v142, s37, v196
	v_add_u32_e32 v158, s56, v196
	ds_read_b128 v[130:133], v142
	ds_read_b128 v[134:137], v142 offset:1024
	ds_read_b128 v[138:141], v142 offset:2048
	ds_read_b128 v[142:145], v142 offset:3072
	ds_read_b128 v[146:149], v158
	ds_read_b128 v[150:153], v158 offset:1024
	ds_read_b128 v[154:157], v158 offset:2048
	ds_read_b128 v[158:161], v158 offset:3072
	s_add_u32 s30, s30, 0x80000
	s_addc_u32 s31, s31, 0
	s_mov_b32 m0, s41
	v_lshl_add_u64 v[224:225], s[30:31], 0, v[178:179]
	ds_read_b128 v[162:165], v199 offset:32768
	ds_read_b128 v[166:169], v199 offset:33792
	ds_read_b128 v[170:173], v199 offset:34816
	ds_read_b128 v[174:177], v199 offset:35840
	ds_read_b128 v[202:205], v199 offset:36864
	ds_read_b128 v[206:209], v199 offset:37888
	ds_read_b128 v[210:213], v199 offset:38912
	ds_read_b128 v[214:217], v199 offset:39936
	global_load_lds_dwordx4 v[224:225], off
	v_lshl_add_u64 v[224:225], s[30:31], 0, v[180:181]
	s_mov_b32 m0, s42
	s_nop 0
	global_load_lds_dwordx4 v[224:225], off
	s_waitcnt vmcnt(8)
	s_waitcnt lgkmcnt(0)
	s_barrier
	s_setprio 1
	v_mfma_f32_16x16x32_bf16 v[126:129], v[130:133], v[162:165], v[126:129]
	v_mfma_f32_16x16x32_bf16 v[122:125], v[138:141], v[162:165], v[122:125]
	v_mfma_f32_16x16x32_bf16 v[110:113], v[130:133], v[170:173], v[110:113]
	v_mfma_f32_16x16x32_bf16 v[106:109], v[138:141], v[170:173], v[106:109]
	v_mfma_f32_16x16x32_bf16 v[94:97], v[130:133], v[202:205], v[94:97]
	v_mfma_f32_16x16x32_bf16 v[90:93], v[138:141], v[202:205], v[90:93]
	v_mfma_f32_16x16x32_bf16 v[78:81], v[130:133], v[210:213], v[78:81]
	v_mfma_f32_16x16x32_bf16 v[74:77], v[138:141], v[210:213], v[74:77]
	v_mfma_f32_16x16x32_bf16 v[126:129], v[134:137], v[166:169], v[126:129]
	v_mfma_f32_16x16x32_bf16 v[122:125], v[142:145], v[166:169], v[122:125]
	v_mfma_f32_16x16x32_bf16 v[110:113], v[134:137], v[174:177], v[110:113]
	v_mfma_f32_16x16x32_bf16 v[106:109], v[142:145], v[174:177], v[106:109]
	v_mfma_f32_16x16x32_bf16 v[94:97], v[134:137], v[206:209], v[94:97]
	v_mfma_f32_16x16x32_bf16 v[90:93], v[142:145], v[206:209], v[90:93]
	v_mfma_f32_16x16x32_bf16 v[78:81], v[134:137], v[214:217], v[78:81]
	v_mfma_f32_16x16x32_bf16 v[74:77], v[142:145], v[214:217], v[74:77]
	s_setprio 0
	s_setprio 1
	v_mfma_f32_16x16x32_bf16 v[118:121], v[146:149], v[162:165], v[118:121]
	v_mfma_f32_16x16x32_bf16 v[114:117], v[154:157], v[162:165], v[114:117]
	v_mfma_f32_16x16x32_bf16 v[102:105], v[146:149], v[170:173], v[102:105]
	v_mfma_f32_16x16x32_bf16 v[98:101], v[154:157], v[170:173], v[98:101]
	v_mfma_f32_16x16x32_bf16 v[86:89], v[146:149], v[202:205], v[86:89]
	v_mfma_f32_16x16x32_bf16 v[82:85], v[154:157], v[202:205], v[82:85]
	v_mfma_f32_16x16x32_bf16 v[70:73], v[146:149], v[210:213], v[70:73]
	v_mfma_f32_16x16x32_bf16 v[66:69], v[154:157], v[210:213], v[66:69]
	v_mfma_f32_16x16x32_bf16 v[118:121], v[150:153], v[166:169], v[118:121]
	v_mfma_f32_16x16x32_bf16 v[114:117], v[158:161], v[166:169], v[114:117]
	v_mfma_f32_16x16x32_bf16 v[102:105], v[150:153], v[174:177], v[102:105]
	v_mfma_f32_16x16x32_bf16 v[98:101], v[158:161], v[174:177], v[98:101]
	v_mfma_f32_16x16x32_bf16 v[86:89], v[150:153], v[206:209], v[86:89]
	v_mfma_f32_16x16x32_bf16 v[82:85], v[158:161], v[206:209], v[82:85]
	v_mfma_f32_16x16x32_bf16 v[70:73], v[150:153], v[214:217], v[70:73]
	v_mfma_f32_16x16x32_bf16 v[66:69], v[158:161], v[214:217], v[66:69]
	s_barrier
	s_setprio 0
	s_add_i32 s30, s37, s38
	v_lshl_add_u64 v[194:195], v[194:195], 0, s[14:15]
	s_mov_b32 m0, s30
	ds_read_b128 v[162:165], v199 offset:49152
	ds_read_b128 v[166:169], v199 offset:50176
	ds_read_b128 v[170:173], v199 offset:51200
	ds_read_b128 v[174:177], v199 offset:52224
	ds_read_b128 v[202:205], v199 offset:53248
	ds_read_b128 v[206:209], v199 offset:54272
	ds_read_b128 v[210:213], v199 offset:55296
	ds_read_b128 v[214:217], v199 offset:56320
	global_load_lds_dwordx4 v[194:195], off
	s_add_i32 m0, s30, 0x2000
	s_add_u32 s28, s28, 0x80080
	v_lshl_add_u64 v[194:195], v[218:219], 0, s[14:15]
	s_addc_u32 s29, s29, 0
	s_add_i32 s30, s56, s38
	global_load_lds_dwordx4 v[194:195], off
	v_lshl_add_u64 v[194:195], s[28:29], 0, v[178:179]
	s_mov_b32 m0, s30
	s_nop 0
	global_load_lds_dwordx4 v[194:195], off
	v_lshl_add_u64 v[194:195], s[28:29], 0, v[180:181]
	s_add_i32 m0, s30, 0x2000
	s_nop 0
	global_load_lds_dwordx4 v[194:195], off
	v_lshl_add_u64 v[194:195], v[220:221], 0, s[14:15]
	s_mov_b32 m0, s46
	s_nop 0
	global_load_lds_dwordx4 v[194:195], off
	v_lshl_add_u64 v[194:195], v[222:223], 0, s[14:15]
	s_mov_b32 m0, s47
	s_nop 0
	global_load_lds_dwordx4 v[194:195], off
	s_waitcnt vmcnt(8)
	s_waitcnt lgkmcnt(0)
	s_barrier
	s_setprio 1
	v_mfma_f32_16x16x32_bf16 v[62:65], v[130:133], v[162:165], v[62:65]
	v_mfma_f32_16x16x32_bf16 v[58:61], v[138:141], v[162:165], v[58:61]
	v_mfma_f32_16x16x32_bf16 v[46:49], v[130:133], v[170:173], v[46:49]
	v_mfma_f32_16x16x32_bf16 v[42:45], v[138:141], v[170:173], v[42:45]
	v_mfma_f32_16x16x32_bf16 v[30:33], v[130:133], v[202:205], v[30:33]
	v_mfma_f32_16x16x32_bf16 v[26:29], v[138:141], v[202:205], v[26:29]
	v_mfma_f32_16x16x32_bf16 v[14:17], v[130:133], v[210:213], v[14:17]
	v_mfma_f32_16x16x32_bf16 v[10:13], v[138:141], v[210:213], v[10:13]
	v_mfma_f32_16x16x32_bf16 v[62:65], v[134:137], v[166:169], v[62:65]
	v_mfma_f32_16x16x32_bf16 v[58:61], v[142:145], v[166:169], v[58:61]
	v_mfma_f32_16x16x32_bf16 v[46:49], v[134:137], v[174:177], v[46:49]
	v_mfma_f32_16x16x32_bf16 v[42:45], v[142:145], v[174:177], v[42:45]
	v_mfma_f32_16x16x32_bf16 v[30:33], v[134:137], v[206:209], v[30:33]
	v_mfma_f32_16x16x32_bf16 v[26:29], v[142:145], v[206:209], v[26:29]
	v_mfma_f32_16x16x32_bf16 v[14:17], v[134:137], v[214:217], v[14:17]
	v_mfma_f32_16x16x32_bf16 v[10:13], v[142:145], v[214:217], v[10:13]
	s_setprio 0
	s_setprio 1
	v_mfma_f32_16x16x32_bf16 v[54:57], v[146:149], v[162:165], v[54:57]
	v_mfma_f32_16x16x32_bf16 v[50:53], v[154:157], v[162:165], v[50:53]
	v_mfma_f32_16x16x32_bf16 v[38:41], v[146:149], v[170:173], v[38:41]
	v_mfma_f32_16x16x32_bf16 v[34:37], v[154:157], v[170:173], v[34:37]
	v_mfma_f32_16x16x32_bf16 v[22:25], v[146:149], v[202:205], v[22:25]
	v_mfma_f32_16x16x32_bf16 v[18:21], v[154:157], v[202:205], v[18:21]
	v_mfma_f32_16x16x32_bf16 v[6:9], v[146:149], v[210:213], v[6:9]
	v_mfma_f32_16x16x32_bf16 v[2:5], v[154:157], v[210:213], v[2:5]
	v_mfma_f32_16x16x32_bf16 v[54:57], v[150:153], v[166:169], v[54:57]
	v_mfma_f32_16x16x32_bf16 v[50:53], v[158:161], v[166:169], v[50:53]
	v_mfma_f32_16x16x32_bf16 v[38:41], v[150:153], v[174:177], v[38:41]
	v_mfma_f32_16x16x32_bf16 v[34:37], v[158:161], v[174:177], v[34:37]
	v_mfma_f32_16x16x32_bf16 v[22:25], v[150:153], v[206:209], v[22:25]
	v_mfma_f32_16x16x32_bf16 v[18:21], v[158:161], v[206:209], v[18:21]
	v_mfma_f32_16x16x32_bf16 v[6:9], v[150:153], v[214:217], v[6:9]
	v_mfma_f32_16x16x32_bf16 v[2:5], v[158:161], v[214:217], v[2:5]
	s_barrier
	s_setprio 0
	s_add_i32 s36, s36, 2
	s_add_u32 s10, s10, 0x100
	s_addc_u32 s11, s11, 0
	s_add_u32 s34, s34, 0x100
	s_addc_u32 s35, s35, 0
	s_cmp_gt_u32 s36, 29
	s_cbranch_scc0 .LBB0_2207
	s_and_b64 vcc, exec, s[16:17]
	s_cbranch_vccz .LBB0_2210
	s_barrier

.LBB0_2412:
	ds_read_b128 v[138:141], v144
	ds_read_b128 v[150:153], v144 offset:1024
	ds_read_b128 v[154:157], v144 offset:2048
	ds_read_b128 v[158:161], v144 offset:3072
	ds_read_b128 v[162:165], v145
	ds_read_b128 v[166:169], v145 offset:1024
	ds_read_b128 v[170:173], v145 offset:2048
	ds_read_b128 v[174:177], v145 offset:3072
	s_add_u32 s24, s22, 0x100
	s_addc_u32 s25, s23, 0
	s_add_u32 s26, s54, s22
	s_addc_u32 s27, s55, s23
	s_cmp_eq_u32 s56, 28
	s_cselect_b32 s28, 0, s24
	s_cselect_b32 s29, 0, s25
	s_cselect_b32 s26, s19, s26
	s_cselect_b32 s27, s10, s27
	s_add_u32 s28, s8, s28
	s_addc_u32 s29, s9, s29
	s_mov_b32 m0, s42
	v_lshl_add_u64 v[210:211], v[134:135], 0, s[22:23]
	ds_read_b128 v[178:181], v146
	ds_read_b128 v[182:185], v146 offset:1024
	ds_read_b128 v[186:189], v146 offset:2048
	ds_read_b128 v[190:193], v146 offset:3072
	ds_read_b128 v[194:197], v146 offset:4096
	ds_read_b128 v[198:201], v146 offset:5120
	ds_read_b128 v[202:205], v146 offset:6144
	ds_read_b128 v[206:209], v146 offset:7168
	global_load_lds_dwordx4 v[210:211], off
	v_lshl_add_u64 v[210:211], v[136:137], 0, s[22:23]
	s_mov_b32 m0, s43
	s_nop 0
	global_load_lds_dwordx4 v[210:211], off
	s_waitcnt vmcnt(8)
	s_waitcnt lgkmcnt(0)
	s_barrier
	s_setprio 1
	v_mfma_f32_16x16x32_bf16 v[126:129], v[138:141], v[178:181], v[126:129]
	v_mfma_f32_16x16x32_bf16 v[122:125], v[154:157], v[178:181], v[122:125]
	v_mfma_f32_16x16x32_bf16 v[110:113], v[138:141], v[186:189], v[110:113]
	v_mfma_f32_16x16x32_bf16 v[106:109], v[154:157], v[186:189], v[106:109]
	v_mfma_f32_16x16x32_bf16 v[94:97], v[138:141], v[194:197], v[94:97]
	v_mfma_f32_16x16x32_bf16 v[90:93], v[154:157], v[194:197], v[90:93]
	v_mfma_f32_16x16x32_bf16 v[78:81], v[138:141], v[202:205], v[78:81]
	v_mfma_f32_16x16x32_bf16 v[74:77], v[154:157], v[202:205], v[74:77]
	v_mfma_f32_16x16x32_bf16 v[126:129], v[150:153], v[182:185], v[126:129]
	v_mfma_f32_16x16x32_bf16 v[122:125], v[158:161], v[182:185], v[122:125]
	v_mfma_f32_16x16x32_bf16 v[110:113], v[150:153], v[190:193], v[110:113]
	v_mfma_f32_16x16x32_bf16 v[106:109], v[158:161], v[190:193], v[106:109]
	v_mfma_f32_16x16x32_bf16 v[94:97], v[150:153], v[198:201], v[94:97]
	v_mfma_f32_16x16x32_bf16 v[90:93], v[158:161], v[198:201], v[90:93]
	v_mfma_f32_16x16x32_bf16 v[78:81], v[150:153], v[206:209], v[78:81]
	v_mfma_f32_16x16x32_bf16 v[74:77], v[158:161], v[206:209], v[74:77]
	s_setprio 0
	s_setprio 1
	v_mfma_f32_16x16x32_bf16 v[118:121], v[162:165], v[178:181], v[118:121]
	v_mfma_f32_16x16x32_bf16 v[114:117], v[170:173], v[178:181], v[114:117]
	v_mfma_f32_16x16x32_bf16 v[102:105], v[162:165], v[186:189], v[102:105]
	v_mfma_f32_16x16x32_bf16 v[98:101], v[170:173], v[186:189], v[98:101]
	v_mfma_f32_16x16x32_bf16 v[86:89], v[162:165], v[194:197], v[86:89]
	v_mfma_f32_16x16x32_bf16 v[82:85], v[170:173], v[194:197], v[82:85]
	v_mfma_f32_16x16x32_bf16 v[70:73], v[162:165], v[202:205], v[70:73]
	v_mfma_f32_16x16x32_bf16 v[66:69], v[170:173], v[202:205], v[66:69]
	v_mfma_f32_16x16x32_bf16 v[118:121], v[166:169], v[182:185], v[118:121]
	v_mfma_f32_16x16x32_bf16 v[114:117], v[174:177], v[182:185], v[114:117]
	v_mfma_f32_16x16x32_bf16 v[102:105], v[166:169], v[190:193], v[102:105]
	v_mfma_f32_16x16x32_bf16 v[98:101], v[174:177], v[190:193], v[98:101]
	v_mfma_f32_16x16x32_bf16 v[86:89], v[166:169], v[198:201], v[86:89]
	v_mfma_f32_16x16x32_bf16 v[82:85], v[174:177], v[198:201], v[82:85]
	v_mfma_f32_16x16x32_bf16 v[70:73], v[166:169], v[206:209], v[70:73]
	v_mfma_f32_16x16x32_bf16 v[66:69], v[174:177], v[206:209], v[66:69]
	s_barrier
	s_setprio 0
	s_mov_b32 m0, s44
	v_lshl_add_u64 v[210:211], s[26:27], 0, v[132:133]
	s_add_u32 s22, s26, 0x80000
	ds_read_b128 v[178:181], v146 offset:16384
	ds_read_b128 v[182:185], v146 offset:17408
	ds_read_b128 v[186:189], v146 offset:18432
	ds_read_b128 v[190:193], v146 offset:19456
	ds_read_b128 v[194:197], v146 offset:20480
	ds_read_b128 v[198:201], v146 offset:21504
	ds_read_b128 v[202:205], v146 offset:22528
	ds_read_b128 v[206:209], v146 offset:23552
	global_load_lds_dwordx4 v[210:211], off
	v_lshl_add_u64 v[212:213], s[26:27], 0, v[130:131]
	s_mov_b32 m0, s45
	s_addc_u32 s23, s27, 0
	global_load_lds_dwordx4 v[212:213], off
	v_lshl_add_u64 v[214:215], s[22:23], 0, v[132:133]
	s_mov_b32 m0, s46
	v_lshl_add_u64 v[216:217], s[28:29], 0, v[130:131]
	global_load_lds_dwordx4 v[214:215], off
	v_lshl_add_u64 v[214:215], s[22:23], 0, v[130:131]
	s_mov_b32 m0, s47
	s_nop 0
	global_load_lds_dwordx4 v[214:215], off
	v_lshl_add_u64 v[214:215], s[28:29], 0, v[132:133]
	s_mov_b32 m0, s33
	s_nop 0
	global_load_lds_dwordx4 v[214:215], off
	s_mov_b32 m0, s34
	s_nop 0
	global_load_lds_dwordx4 v[216:217], off
	s_waitcnt vmcnt(8)
	s_waitcnt lgkmcnt(0)
	s_barrier
	s_setprio 1
	v_mfma_f32_16x16x32_bf16 v[62:65], v[138:141], v[178:181], v[62:65]
	v_mfma_f32_16x16x32_bf16 v[58:61], v[154:157], v[178:181], v[58:61]
	v_mfma_f32_16x16x32_bf16 v[46:49], v[138:141], v[186:189], v[46:49]
	v_mfma_f32_16x16x32_bf16 v[42:45], v[154:157], v[186:189], v[42:45]
	v_mfma_f32_16x16x32_bf16 v[30:33], v[138:141], v[194:197], v[30:33]
	v_mfma_f32_16x16x32_bf16 v[26:29], v[154:157], v[194:197], v[26:29]
	v_mfma_f32_16x16x32_bf16 v[14:17], v[138:141], v[202:205], v[14:17]
	v_mfma_f32_16x16x32_bf16 v[10:13], v[154:157], v[202:205], v[10:13]
	v_mfma_f32_16x16x32_bf16 v[62:65], v[150:153], v[182:185], v[62:65]
	v_mfma_f32_16x16x32_bf16 v[58:61], v[158:161], v[182:185], v[58:61]
	v_mfma_f32_16x16x32_bf16 v[46:49], v[150:153], v[190:193], v[46:49]
	v_mfma_f32_16x16x32_bf16 v[42:45], v[158:161], v[190:193], v[42:45]
	v_mfma_f32_16x16x32_bf16 v[30:33], v[150:153], v[198:201], v[30:33]
	v_mfma_f32_16x16x32_bf16 v[26:29], v[158:161], v[198:201], v[26:29]
	v_mfma_f32_16x16x32_bf16 v[14:17], v[150:153], v[206:209], v[14:17]
	v_mfma_f32_16x16x32_bf16 v[10:13], v[158:161], v[206:209], v[10:13]
	s_setprio 0
	s_setprio 1
	v_mfma_f32_16x16x32_bf16 v[54:57], v[162:165], v[178:181], v[54:57]
	v_mfma_f32_16x16x32_bf16 v[50:53], v[170:173], v[178:181], v[50:53]
	v_mfma_f32_16x16x32_bf16 v[38:41], v[162:165], v[186:189], v[38:41]
	v_mfma_f32_16x16x32_bf16 v[34:37], v[170:173], v[186:189], v[34:37]
	v_mfma_f32_16x16x32_bf16 v[22:25], v[162:165], v[194:197], v[22:25]
	v_mfma_f32_16x16x32_bf16 v[18:21], v[170:173], v[194:197], v[18:21]
	v_mfma_f32_16x16x32_bf16 v[6:9], v[162:165], v[202:205], v[6:9]
	v_mfma_f32_16x16x32_bf16 v[2:5], v[170:173], v[202:205], v[2:5]
	v_mfma_f32_16x16x32_bf16 v[54:57], v[166:169], v[182:185], v[54:57]
	v_mfma_f32_16x16x32_bf16 v[50:53], v[174:177], v[182:185], v[50:53]
	v_mfma_f32_16x16x32_bf16 v[38:41], v[166:169], v[190:193], v[38:41]
	v_mfma_f32_16x16x32_bf16 v[34:37], v[174:177], v[190:193], v[34:37]
	v_mfma_f32_16x16x32_bf16 v[22:25], v[166:169], v[198:201], v[22:25]
	v_mfma_f32_16x16x32_bf16 v[18:21], v[174:177], v[198:201], v[18:21]
	v_mfma_f32_16x16x32_bf16 v[6:9], v[166:169], v[206:209], v[6:9]
	v_mfma_f32_16x16x32_bf16 v[2:5], v[174:177], v[206:209], v[2:5]
	s_barrier
	s_setprio 0
	ds_read_b128 v[138:141], v147
	ds_read_b128 v[150:153], v147 offset:1024
	ds_read_b128 v[154:157], v147 offset:2048
	ds_read_b128 v[158:161], v147 offset:3072
	ds_read_b128 v[162:165], v148
	ds_read_b128 v[166:169], v148 offset:1024
	ds_read_b128 v[170:173], v148 offset:2048
	ds_read_b128 v[174:177], v148 offset:3072
	s_add_u32 s22, s28, 0x80000
	s_addc_u32 s23, s29, 0
	s_mov_b32 m0, s35
	v_lshl_add_u64 v[218:219], s[22:23], 0, v[132:133]
	ds_read_b128 v[178:181], v146 offset:32768
	ds_read_b128 v[182:185], v146 offset:33792
	ds_read_b128 v[186:189], v146 offset:34816
	ds_read_b128 v[190:193], v146 offset:35840
	ds_read_b128 v[194:197], v146 offset:36864
	ds_read_b128 v[198:201], v146 offset:37888
	ds_read_b128 v[202:205], v146 offset:38912
	ds_read_b128 v[206:209], v146 offset:39936
	global_load_lds_dwordx4 v[218:219], off
	v_lshl_add_u64 v[218:219], s[22:23], 0, v[130:131]
	s_mov_b32 m0, s36
	s_nop 0
	global_load_lds_dwordx4 v[218:219], off
	s_waitcnt vmcnt(8)
	s_waitcnt lgkmcnt(0)
	s_barrier
	s_setprio 1
	v_mfma_f32_16x16x32_bf16 v[126:129], v[138:141], v[178:181], v[126:129]
	v_mfma_f32_16x16x32_bf16 v[122:125], v[154:157], v[178:181], v[122:125]
	v_mfma_f32_16x16x32_bf16 v[110:113], v[138:141], v[186:189], v[110:113]
	v_mfma_f32_16x16x32_bf16 v[106:109], v[154:157], v[186:189], v[106:109]
	v_mfma_f32_16x16x32_bf16 v[94:97], v[138:141], v[194:197], v[94:97]
	v_mfma_f32_16x16x32_bf16 v[90:93], v[154:157], v[194:197], v[90:93]
	v_mfma_f32_16x16x32_bf16 v[78:81], v[138:141], v[202:205], v[78:81]
	v_mfma_f32_16x16x32_bf16 v[74:77], v[154:157], v[202:205], v[74:77]
	v_mfma_f32_16x16x32_bf16 v[126:129], v[150:153], v[182:185], v[126:129]
	v_mfma_f32_16x16x32_bf16 v[122:125], v[158:161], v[182:185], v[122:125]
	v_mfma_f32_16x16x32_bf16 v[110:113], v[150:153], v[190:193], v[110:113]
	v_mfma_f32_16x16x32_bf16 v[106:109], v[158:161], v[190:193], v[106:109]
	v_mfma_f32_16x16x32_bf16 v[94:97], v[150:153], v[198:201], v[94:97]
	v_mfma_f32_16x16x32_bf16 v[90:93], v[158:161], v[198:201], v[90:93]
	v_mfma_f32_16x16x32_bf16 v[78:81], v[150:153], v[206:209], v[78:81]
	v_mfma_f32_16x16x32_bf16 v[74:77], v[158:161], v[206:209], v[74:77]
	s_setprio 0
	s_setprio 1
	v_mfma_f32_16x16x32_bf16 v[118:121], v[162:165], v[178:181], v[118:121]
	v_mfma_f32_16x16x32_bf16 v[114:117], v[170:173], v[178:181], v[114:117]
	v_mfma_f32_16x16x32_bf16 v[102:105], v[162:165], v[186:189], v[102:105]
	v_mfma_f32_16x16x32_bf16 v[98:101], v[170:173], v[186:189], v[98:101]
	v_mfma_f32_16x16x32_bf16 v[86:89], v[162:165], v[194:197], v[86:89]
	v_mfma_f32_16x16x32_bf16 v[82:85], v[170:173], v[194:197], v[82:85]
	v_mfma_f32_16x16x32_bf16 v[70:73], v[162:165], v[202:205], v[70:73]
	v_mfma_f32_16x16x32_bf16 v[66:69], v[170:173], v[202:205], v[66:69]
	v_mfma_f32_16x16x32_bf16 v[118:121], v[166:169], v[182:185], v[118:121]
	v_mfma_f32_16x16x32_bf16 v[114:117], v[174:177], v[182:185], v[114:117]
	v_mfma_f32_16x16x32_bf16 v[102:105], v[166:169], v[190:193], v[102:105]
	v_mfma_f32_16x16x32_bf16 v[98:101], v[174:177], v[190:193], v[98:101]
	v_mfma_f32_16x16x32_bf16 v[86:89], v[166:169], v[198:201], v[86:89]
	v_mfma_f32_16x16x32_bf16 v[82:85], v[174:177], v[198:201], v[82:85]
	v_mfma_f32_16x16x32_bf16 v[70:73], v[166:169], v[206:209], v[70:73]
	v_mfma_f32_16x16x32_bf16 v[66:69], v[174:177], v[206:209], v[66:69]
	s_barrier
	s_setprio 0
	s_mov_b32 m0, s48
	v_lshl_add_u64 v[210:211], v[210:211], 0, s[14:15]
	s_add_u32 s22, s26, 0x80080
	ds_read_b128 v[178:181], v146 offset:49152
	ds_read_b128 v[182:185], v146 offset:50176
	ds_read_b128 v[186:189], v146 offset:51200
	ds_read_b128 v[190:193], v146 offset:52224
	ds_read_b128 v[194:197], v146 offset:53248
	ds_read_b128 v[198:201], v146 offset:54272
	ds_read_b128 v[202:205], v146 offset:55296
	ds_read_b128 v[206:209], v146 offset:56320
	global_load_lds_dwordx4 v[210:211], off
	v_lshl_add_u64 v[210:211], v[212:213], 0, s[14:15]
	s_mov_b32 m0, s49
	s_addc_u32 s23, s27, 0
	global_load_lds_dwordx4 v[210:211], off
	v_lshl_add_u64 v[210:211], s[22:23], 0, v[132:133]
	s_mov_b32 m0, s50
	s_nop 0
	global_load_lds_dwordx4 v[210:211], off
	v_lshl_add_u64 v[210:211], s[22:23], 0, v[130:131]
	s_mov_b32 m0, s51
	s_nop 0
	global_load_lds_dwordx4 v[210:211], off
	v_lshl_add_u64 v[210:211], v[214:215], 0, s[14:15]
	s_mov_b32 m0, s39
	s_nop 0
	global_load_lds_dwordx4 v[210:211], off
	v_lshl_add_u64 v[210:211], v[216:217], 0, s[14:15]
	s_mov_b32 m0, s40
	s_nop 0
	global_load_lds_dwordx4 v[210:211], off
	s_waitcnt vmcnt(8)
	s_waitcnt lgkmcnt(0)
	s_barrier
	s_setprio 1
	v_mfma_f32_16x16x32_bf16 v[62:65], v[138:141], v[178:181], v[62:65]
	v_mfma_f32_16x16x32_bf16 v[58:61], v[154:157], v[178:181], v[58:61]
	v_mfma_f32_16x16x32_bf16 v[46:49], v[138:141], v[186:189], v[46:49]
	v_mfma_f32_16x16x32_bf16 v[42:45], v[154:157], v[186:189], v[42:45]
	v_mfma_f32_16x16x32_bf16 v[30:33], v[138:141], v[194:197], v[30:33]
	v_mfma_f32_16x16x32_bf16 v[26:29], v[154:157], v[194:197], v[26:29]
	v_mfma_f32_16x16x32_bf16 v[14:17], v[138:141], v[202:205], v[14:17]
	v_mfma_f32_16x16x32_bf16 v[10:13], v[154:157], v[202:205], v[10:13]
	v_mfma_f32_16x16x32_bf16 v[62:65], v[150:153], v[182:185], v[62:65]
	v_mfma_f32_16x16x32_bf16 v[58:61], v[158:161], v[182:185], v[58:61]
	v_mfma_f32_16x16x32_bf16 v[46:49], v[150:153], v[190:193], v[46:49]
	v_mfma_f32_16x16x32_bf16 v[42:45], v[158:161], v[190:193], v[42:45]
	v_mfma_f32_16x16x32_bf16 v[30:33], v[150:153], v[198:201], v[30:33]
	v_mfma_f32_16x16x32_bf16 v[26:29], v[158:161], v[198:201], v[26:29]
	v_mfma_f32_16x16x32_bf16 v[14:17], v[150:153], v[206:209], v[14:17]
	v_mfma_f32_16x16x32_bf16 v[10:13], v[158:161], v[206:209], v[10:13]
	s_setprio 0
	s_setprio 1
	v_mfma_f32_16x16x32_bf16 v[54:57], v[162:165], v[178:181], v[54:57]
	v_mfma_f32_16x16x32_bf16 v[50:53], v[170:173], v[178:181], v[50:53]
	v_mfma_f32_16x16x32_bf16 v[38:41], v[162:165], v[186:189], v[38:41]
	v_mfma_f32_16x16x32_bf16 v[34:37], v[170:173], v[186:189], v[34:37]
	v_mfma_f32_16x16x32_bf16 v[22:25], v[162:165], v[194:197], v[22:25]
	v_mfma_f32_16x16x32_bf16 v[18:21], v[170:173], v[194:197], v[18:21]
	v_mfma_f32_16x16x32_bf16 v[6:9], v[162:165], v[202:205], v[6:9]
	v_mfma_f32_16x16x32_bf16 v[2:5], v[170:173], v[202:205], v[2:5]
	v_mfma_f32_16x16x32_bf16 v[54:57], v[166:169], v[182:185], v[54:57]
	v_mfma_f32_16x16x32_bf16 v[50:53], v[174:177], v[182:185], v[50:53]
	v_mfma_f32_16x16x32_bf16 v[38:41], v[166:169], v[190:193], v[38:41]
	v_mfma_f32_16x16x32_bf16 v[34:37], v[174:177], v[190:193], v[34:37]
	v_mfma_f32_16x16x32_bf16 v[22:25], v[166:169], v[198:201], v[22:25]
	v_mfma_f32_16x16x32_bf16 v[18:21], v[174:177], v[198:201], v[18:21]
	v_mfma_f32_16x16x32_bf16 v[6:9], v[166:169], v[206:209], v[6:9]
	v_mfma_f32_16x16x32_bf16 v[2:5], v[174:177], v[206:209], v[2:5]
	s_barrier
	s_setprio 0
	s_add_i32 s56, s56, 2
	s_cmp_gt_u32 s56, 29
	s_mov_b64 s[22:23], s[24:25]
	s_cbranch_scc0 .LBB0_2412
	s_and_b64 vcc, exec, s[16:17]
	s_cbranch_vccz .LBB0_2415
	s_barrier

.LBB0_2492:
	ds_read_b128 v[130:133], v159
	ds_read_b128 v[134:137], v159 offset:1024
	ds_read_b128 v[164:167], v159 offset:2048
	ds_read_b128 v[168:171], v159 offset:3072
	ds_read_b128 v[172:175], v161
	ds_read_b128 v[182:185], v161 offset:1024
	ds_read_b128 v[186:189], v161 offset:2048
	ds_read_b128 v[190:193], v161 offset:3072
	s_add_u32 s22, s0, 0xfff80080
	s_addc_u32 s23, s1, -1
	s_cmp_eq_u32 s48, 28
	s_cselect_b32 s25, s9, s23
	s_cselect_b32 s24, s8, s22
	s_cselect_b32 s23, s44, s47
	s_cselect_b32 s22, s45, s46
	v_lshl_add_u64 v[154:155], s[0:1], 0, v[146:147]
	s_add_i32 m0, s28, 0xc000
	ds_read_b128 v[194:197], v163
	ds_read_b128 v[198:201], v163 offset:1024
	ds_read_b128 v[202:205], v163 offset:2048
	ds_read_b128 v[206:209], v163 offset:3072
	ds_read_b128 v[210:213], v163 offset:4096
	ds_read_b128 v[214:217], v163 offset:5120
	ds_read_b128 v[218:221], v163 offset:6144
	ds_read_b128 v[222:225], v163 offset:7168
	global_load_lds_dwordx4 v[154:155], off
	v_lshl_add_u64 v[154:155], s[0:1], 0, v[148:149]
	s_add_i32 m0, s28, 0xe000
	s_nop 0
	global_load_lds_dwordx4 v[154:155], off
	s_waitcnt vmcnt(8)
	s_waitcnt lgkmcnt(0)
	s_barrier
	s_setprio 1
	v_mfma_f32_16x16x32_bf16 v[126:129], v[130:133], v[194:197], v[126:129]
	v_mfma_f32_16x16x32_bf16 v[122:125], v[164:167], v[194:197], v[122:125]
	v_mfma_f32_16x16x32_bf16 v[118:121], v[130:133], v[202:205], v[118:121]
	v_mfma_f32_16x16x32_bf16 v[110:113], v[164:167], v[202:205], v[110:113]
	v_mfma_f32_16x16x32_bf16 v[102:105], v[130:133], v[210:213], v[102:105]
	v_mfma_f32_16x16x32_bf16 v[94:97], v[164:167], v[210:213], v[94:97]
	v_mfma_f32_16x16x32_bf16 v[86:89], v[130:133], v[218:221], v[86:89]
	v_mfma_f32_16x16x32_bf16 v[78:81], v[164:167], v[218:221], v[78:81]
	v_mfma_f32_16x16x32_bf16 v[126:129], v[134:137], v[198:201], v[126:129]
	v_mfma_f32_16x16x32_bf16 v[122:125], v[168:171], v[198:201], v[122:125]
	v_mfma_f32_16x16x32_bf16 v[118:121], v[134:137], v[206:209], v[118:121]
	v_mfma_f32_16x16x32_bf16 v[110:113], v[168:171], v[206:209], v[110:113]
	v_mfma_f32_16x16x32_bf16 v[102:105], v[134:137], v[214:217], v[102:105]
	v_mfma_f32_16x16x32_bf16 v[94:97], v[168:171], v[214:217], v[94:97]
	v_mfma_f32_16x16x32_bf16 v[86:89], v[134:137], v[222:225], v[86:89]
	v_mfma_f32_16x16x32_bf16 v[78:81], v[168:171], v[222:225], v[78:81]
	s_setprio 0
	s_setprio 1
	v_mfma_f32_16x16x32_bf16 v[114:117], v[172:175], v[194:197], v[114:117]
	v_mfma_f32_16x16x32_bf16 v[106:109], v[186:189], v[194:197], v[106:109]
	v_mfma_f32_16x16x32_bf16 v[98:101], v[172:175], v[202:205], v[98:101]
	v_mfma_f32_16x16x32_bf16 v[90:93], v[186:189], v[202:205], v[90:93]
	v_mfma_f32_16x16x32_bf16 v[82:85], v[172:175], v[210:213], v[82:85]
	v_mfma_f32_16x16x32_bf16 v[74:77], v[186:189], v[210:213], v[74:77]
	v_mfma_f32_16x16x32_bf16 v[70:73], v[172:175], v[218:221], v[70:73]
	v_mfma_f32_16x16x32_bf16 v[66:69], v[186:189], v[218:221], v[66:69]
	v_mfma_f32_16x16x32_bf16 v[114:117], v[182:185], v[198:201], v[114:117]
	v_mfma_f32_16x16x32_bf16 v[106:109], v[190:193], v[198:201], v[106:109]
	v_mfma_f32_16x16x32_bf16 v[98:101], v[182:185], v[206:209], v[98:101]
	v_mfma_f32_16x16x32_bf16 v[90:93], v[190:193], v[206:209], v[90:93]
	v_mfma_f32_16x16x32_bf16 v[82:85], v[182:185], v[214:217], v[82:85]
	v_mfma_f32_16x16x32_bf16 v[74:77], v[190:193], v[214:217], v[74:77]
	v_mfma_f32_16x16x32_bf16 v[70:73], v[182:185], v[222:225], v[70:73]
	v_mfma_f32_16x16x32_bf16 v[66:69], v[190:193], v[222:225], v[66:69]
	s_barrier
	s_setprio 0
	s_add_i32 s49, s64, s27
	v_lshl_add_u64 v[154:155], s[22:23], 0, v[142:143]
	s_mov_b32 m0, s49
	ds_read_b128 v[194:197], v163 offset:16384
	ds_read_b128 v[198:201], v163 offset:17408
	ds_read_b128 v[202:205], v163 offset:18432
	ds_read_b128 v[206:209], v163 offset:19456
	ds_read_b128 v[210:213], v163 offset:20480
	ds_read_b128 v[214:217], v163 offset:21504
	ds_read_b128 v[218:221], v163 offset:22528
	ds_read_b128 v[222:225], v163 offset:23552
	global_load_lds_dwordx4 v[154:155], off
	s_add_i32 m0, s49, 0x2000
	s_add_u32 s50, s22, 0x80000
	v_lshl_add_u64 v[176:177], s[22:23], 0, v[138:139]
	s_addc_u32 s51, s23, 0
	s_add_i32 s49, s65, s27
	global_load_lds_dwordx4 v[176:177], off
	v_lshl_add_u64 v[226:227], s[50:51], 0, v[142:143]
	s_mov_b32 m0, s49
	v_lshl_add_u64 v[228:229], s[24:25], 0, v[140:141]
	global_load_lds_dwordx4 v[226:227], off
	v_lshl_add_u64 v[226:227], s[50:51], 0, v[138:139]
	s_add_i32 m0, s49, 0x2000
	s_nop 0
	global_load_lds_dwordx4 v[226:227], off
	v_lshl_add_u64 v[226:227], s[24:25], 0, v[144:145]
	s_mov_b32 m0, s28
	s_nop 0
	global_load_lds_dwordx4 v[226:227], off
	s_mov_b32 m0, s29
	s_nop 0
	global_load_lds_dwordx4 v[228:229], off
	s_waitcnt vmcnt(8)
	s_waitcnt lgkmcnt(0)
	s_barrier
	s_setprio 1
	v_mfma_f32_16x16x32_bf16 v[62:65], v[130:133], v[194:197], v[62:65]
	v_mfma_f32_16x16x32_bf16 v[58:61], v[164:167], v[194:197], v[58:61]
	v_mfma_f32_16x16x32_bf16 v[54:57], v[130:133], v[202:205], v[54:57]
	v_mfma_f32_16x16x32_bf16 v[46:49], v[164:167], v[202:205], v[46:49]
	v_mfma_f32_16x16x32_bf16 v[38:41], v[130:133], v[210:213], v[38:41]
	v_mfma_f32_16x16x32_bf16 v[30:33], v[164:167], v[210:213], v[30:33]
	v_mfma_f32_16x16x32_bf16 v[22:25], v[130:133], v[218:221], v[22:25]
	v_mfma_f32_16x16x32_bf16 v[14:17], v[164:167], v[218:221], v[14:17]
	v_mfma_f32_16x16x32_bf16 v[62:65], v[134:137], v[198:201], v[62:65]
	v_mfma_f32_16x16x32_bf16 v[58:61], v[168:171], v[198:201], v[58:61]
	v_mfma_f32_16x16x32_bf16 v[54:57], v[134:137], v[206:209], v[54:57]
	v_mfma_f32_16x16x32_bf16 v[46:49], v[168:171], v[206:209], v[46:49]
	v_mfma_f32_16x16x32_bf16 v[38:41], v[134:137], v[214:217], v[38:41]
	v_mfma_f32_16x16x32_bf16 v[30:33], v[168:171], v[214:217], v[30:33]
	v_mfma_f32_16x16x32_bf16 v[22:25], v[134:137], v[222:225], v[22:25]
	v_mfma_f32_16x16x32_bf16 v[14:17], v[168:171], v[222:225], v[14:17]
	s_setprio 0
	s_setprio 1
	v_mfma_f32_16x16x32_bf16 v[50:53], v[172:175], v[194:197], v[50:53]
	v_mfma_f32_16x16x32_bf16 v[42:45], v[186:189], v[194:197], v[42:45]
	v_mfma_f32_16x16x32_bf16 v[34:37], v[172:175], v[202:205], v[34:37]
	v_mfma_f32_16x16x32_bf16 v[26:29], v[186:189], v[202:205], v[26:29]
	v_mfma_f32_16x16x32_bf16 v[18:21], v[172:175], v[210:213], v[18:21]
	v_mfma_f32_16x16x32_bf16 v[10:13], v[186:189], v[210:213], v[10:13]
	v_mfma_f32_16x16x32_bf16 v[6:9], v[172:175], v[218:221], v[6:9]
	v_mfma_f32_16x16x32_bf16 v[2:5], v[186:189], v[218:221], v[2:5]
	v_mfma_f32_16x16x32_bf16 v[50:53], v[182:185], v[198:201], v[50:53]
	v_mfma_f32_16x16x32_bf16 v[42:45], v[190:193], v[198:201], v[42:45]
	v_mfma_f32_16x16x32_bf16 v[34:37], v[182:185], v[206:209], v[34:37]
	v_mfma_f32_16x16x32_bf16 v[26:29], v[190:193], v[206:209], v[26:29]
	v_mfma_f32_16x16x32_bf16 v[18:21], v[182:185], v[214:217], v[18:21]
	v_mfma_f32_16x16x32_bf16 v[10:13], v[190:193], v[214:217], v[10:13]
	v_mfma_f32_16x16x32_bf16 v[6:9], v[182:185], v[222:225], v[6:9]
	v_mfma_f32_16x16x32_bf16 v[2:5], v[190:193], v[222:225], v[2:5]
	s_barrier
	s_setprio 0
	v_add_u32_e32 v150, s66, v157
	ds_read_b128 v[130:133], v150
	ds_read_b128 v[134:137], v150 offset:1024
	ds_read_b128 v[164:167], v150 offset:2048
	ds_read_b128 v[168:171], v150 offset:3072
	v_add_u32_e32 v150, s67, v157
	ds_read_b128 v[172:175], v150
	ds_read_b128 v[182:185], v150 offset:1024
	ds_read_b128 v[186:189], v150 offset:2048
	ds_read_b128 v[190:193], v150 offset:3072
	s_add_u32 s24, s24, 0x80000
	s_addc_u32 s25, s25, 0
	s_mov_b32 m0, s30
	v_lshl_add_u64 v[230:231], s[24:25], 0, v[144:145]
	ds_read_b128 v[194:197], v163 offset:32768
	ds_read_b128 v[198:201], v163 offset:33792
	ds_read_b128 v[202:205], v163 offset:34816
	ds_read_b128 v[206:209], v163 offset:35840
	ds_read_b128 v[210:213], v163 offset:36864
	ds_read_b128 v[214:217], v163 offset:37888
	ds_read_b128 v[218:221], v163 offset:38912
	ds_read_b128 v[222:225], v163 offset:39936
	global_load_lds_dwordx4 v[230:231], off
	v_lshl_add_u64 v[230:231], s[24:25], 0, v[140:141]
	s_mov_b32 m0, s31
	s_nop 0
	global_load_lds_dwordx4 v[230:231], off
	s_waitcnt vmcnt(8)
	s_waitcnt lgkmcnt(0)
	s_barrier
	s_setprio 1
	v_mfma_f32_16x16x32_bf16 v[126:129], v[130:133], v[194:197], v[126:129]
	v_mfma_f32_16x16x32_bf16 v[122:125], v[164:167], v[194:197], v[122:125]
	v_mfma_f32_16x16x32_bf16 v[118:121], v[130:133], v[202:205], v[118:121]
	v_mfma_f32_16x16x32_bf16 v[110:113], v[164:167], v[202:205], v[110:113]
	v_mfma_f32_16x16x32_bf16 v[102:105], v[130:133], v[210:213], v[102:105]
	v_mfma_f32_16x16x32_bf16 v[94:97], v[164:167], v[210:213], v[94:97]
	v_mfma_f32_16x16x32_bf16 v[86:89], v[130:133], v[218:221], v[86:89]
	v_mfma_f32_16x16x32_bf16 v[78:81], v[164:167], v[218:221], v[78:81]
	v_mfma_f32_16x16x32_bf16 v[126:129], v[134:137], v[198:201], v[126:129]
	v_mfma_f32_16x16x32_bf16 v[122:125], v[168:171], v[198:201], v[122:125]
	v_mfma_f32_16x16x32_bf16 v[118:121], v[134:137], v[206:209], v[118:121]
	v_mfma_f32_16x16x32_bf16 v[110:113], v[168:171], v[206:209], v[110:113]
	v_mfma_f32_16x16x32_bf16 v[102:105], v[134:137], v[214:217], v[102:105]
	v_mfma_f32_16x16x32_bf16 v[94:97], v[168:171], v[214:217], v[94:97]
	v_mfma_f32_16x16x32_bf16 v[86:89], v[134:137], v[222:225], v[86:89]
	v_mfma_f32_16x16x32_bf16 v[78:81], v[168:171], v[222:225], v[78:81]
	s_setprio 0
	s_setprio 1
	v_mfma_f32_16x16x32_bf16 v[114:117], v[172:175], v[194:197], v[114:117]
	v_mfma_f32_16x16x32_bf16 v[106:109], v[186:189], v[194:197], v[106:109]
	v_mfma_f32_16x16x32_bf16 v[98:101], v[172:175], v[202:205], v[98:101]
	v_mfma_f32_16x16x32_bf16 v[90:93], v[186:189], v[202:205], v[90:93]
	v_mfma_f32_16x16x32_bf16 v[82:85], v[172:175], v[210:213], v[82:85]
	v_mfma_f32_16x16x32_bf16 v[74:77], v[186:189], v[210:213], v[74:77]
	v_mfma_f32_16x16x32_bf16 v[70:73], v[172:175], v[218:221], v[70:73]
	v_mfma_f32_16x16x32_bf16 v[66:69], v[186:189], v[218:221], v[66:69]
	v_mfma_f32_16x16x32_bf16 v[114:117], v[182:185], v[198:201], v[114:117]
	v_mfma_f32_16x16x32_bf16 v[106:109], v[190:193], v[198:201], v[106:109]
	v_mfma_f32_16x16x32_bf16 v[98:101], v[182:185], v[206:209], v[98:101]
	v_mfma_f32_16x16x32_bf16 v[90:93], v[190:193], v[206:209], v[90:93]
	v_mfma_f32_16x16x32_bf16 v[82:85], v[182:185], v[214:217], v[82:85]
	v_mfma_f32_16x16x32_bf16 v[74:77], v[190:193], v[214:217], v[74:77]
	v_mfma_f32_16x16x32_bf16 v[70:73], v[182:185], v[222:225], v[70:73]
	v_mfma_f32_16x16x32_bf16 v[66:69], v[190:193], v[222:225], v[66:69]
	s_barrier
	s_setprio 0
	s_add_i32 s24, s66, s27
	v_lshl_add_u64 v[154:155], v[154:155], 0, s[12:13]
	s_mov_b32 m0, s24
	ds_read_b128 v[194:197], v163 offset:49152
	ds_read_b128 v[198:201], v163 offset:50176
	ds_read_b128 v[202:205], v163 offset:51200
	ds_read_b128 v[206:209], v163 offset:52224
	ds_read_b128 v[210:213], v163 offset:53248
	ds_read_b128 v[214:217], v163 offset:54272
	ds_read_b128 v[218:221], v163 offset:55296
	ds_read_b128 v[222:225], v163 offset:56320
	global_load_lds_dwordx4 v[154:155], off
	s_add_i32 m0, s24, 0x2000
	s_add_u32 s22, s22, 0x80080
	v_lshl_add_u64 v[154:155], v[176:177], 0, s[12:13]
	s_addc_u32 s23, s23, 0
	s_add_i32 s24, s67, s27
	global_load_lds_dwordx4 v[154:155], off
	v_lshl_add_u64 v[154:155], s[22:23], 0, v[142:143]
	s_mov_b32 m0, s24
	s_nop 0
	global_load_lds_dwordx4 v[154:155], off
	v_lshl_add_u64 v[154:155], s[22:23], 0, v[138:139]
	s_add_i32 m0, s24, 0x2000
	s_nop 0
	global_load_lds_dwordx4 v[154:155], off
	v_lshl_add_u64 v[154:155], v[226:227], 0, s[12:13]
	s_mov_b32 m0, s35
	s_nop 0
	global_load_lds_dwordx4 v[154:155], off
	v_lshl_add_u64 v[154:155], v[228:229], 0, s[12:13]
	s_mov_b32 m0, s36
	s_nop 0
	global_load_lds_dwordx4 v[154:155], off
	s_waitcnt vmcnt(8)
	s_waitcnt lgkmcnt(0)
	s_barrier
	s_setprio 1
	v_mfma_f32_16x16x32_bf16 v[62:65], v[130:133], v[194:197], v[62:65]
	v_mfma_f32_16x16x32_bf16 v[58:61], v[164:167], v[194:197], v[58:61]
	v_mfma_f32_16x16x32_bf16 v[54:57], v[130:133], v[202:205], v[54:57]
	v_mfma_f32_16x16x32_bf16 v[46:49], v[164:167], v[202:205], v[46:49]
	v_mfma_f32_16x16x32_bf16 v[38:41], v[130:133], v[210:213], v[38:41]
	v_mfma_f32_16x16x32_bf16 v[30:33], v[164:167], v[210:213], v[30:33]
	v_mfma_f32_16x16x32_bf16 v[22:25], v[130:133], v[218:221], v[22:25]
	v_mfma_f32_16x16x32_bf16 v[14:17], v[164:167], v[218:221], v[14:17]
	v_mfma_f32_16x16x32_bf16 v[62:65], v[134:137], v[198:201], v[62:65]
	v_mfma_f32_16x16x32_bf16 v[58:61], v[168:171], v[198:201], v[58:61]
	v_mfma_f32_16x16x32_bf16 v[54:57], v[134:137], v[206:209], v[54:57]
	v_mfma_f32_16x16x32_bf16 v[46:49], v[168:171], v[206:209], v[46:49]
	v_mfma_f32_16x16x32_bf16 v[38:41], v[134:137], v[214:217], v[38:41]
	v_mfma_f32_16x16x32_bf16 v[30:33], v[168:171], v[214:217], v[30:33]
	v_mfma_f32_16x16x32_bf16 v[22:25], v[134:137], v[222:225], v[22:25]
	v_mfma_f32_16x16x32_bf16 v[14:17], v[168:171], v[222:225], v[14:17]
	s_setprio 0
	s_setprio 1
	v_mfma_f32_16x16x32_bf16 v[50:53], v[172:175], v[194:197], v[50:53]
	v_mfma_f32_16x16x32_bf16 v[42:45], v[186:189], v[194:197], v[42:45]
	v_mfma_f32_16x16x32_bf16 v[34:37], v[172:175], v[202:205], v[34:37]
	v_mfma_f32_16x16x32_bf16 v[26:29], v[186:189], v[202:205], v[26:29]
	v_mfma_f32_16x16x32_bf16 v[18:21], v[172:175], v[210:213], v[18:21]
	v_mfma_f32_16x16x32_bf16 v[10:13], v[186:189], v[210:213], v[10:13]
	v_mfma_f32_16x16x32_bf16 v[6:9], v[172:175], v[218:221], v[6:9]
	v_mfma_f32_16x16x32_bf16 v[2:5], v[186:189], v[218:221], v[2:5]
	v_mfma_f32_16x16x32_bf16 v[50:53], v[182:185], v[198:201], v[50:53]
	v_mfma_f32_16x16x32_bf16 v[42:45], v[190:193], v[198:201], v[42:45]
	v_mfma_f32_16x16x32_bf16 v[34:37], v[182:185], v[206:209], v[34:37]
	v_mfma_f32_16x16x32_bf16 v[26:29], v[190:193], v[206:209], v[26:29]
	v_mfma_f32_16x16x32_bf16 v[18:21], v[182:185], v[214:217], v[18:21]
	v_mfma_f32_16x16x32_bf16 v[10:13], v[190:193], v[214:217], v[10:13]
	v_mfma_f32_16x16x32_bf16 v[6:9], v[182:185], v[222:225], v[6:9]
	v_mfma_f32_16x16x32_bf16 v[2:5], v[190:193], v[222:225], v[2:5]
	s_barrier
	s_setprio 0
	s_add_i32 s48, s48, 2
	s_add_u32 s0, s0, 0x100
	s_addc_u32 s1, s1, 0
	s_add_u32 s46, s46, 0x100
	s_addc_u32 s47, s47, 0
	s_cmp_gt_u32 s48, 29
	s_cbranch_scc0 .LBB0_2492
	s_and_b64 vcc, exec, s[14:15]
	s_cbranch_vccz .LBB0_2495
	s_barrier

.LBB0_2644:
	ds_read_b128 v[138:141], v144
	ds_read_b128 v[150:153], v144 offset:1024
	ds_read_b128 v[154:157], v144 offset:2048
	ds_read_b128 v[158:161], v144 offset:3072
	ds_read_b128 v[162:165], v145
	ds_read_b128 v[166:169], v145 offset:1024
	ds_read_b128 v[170:173], v145 offset:2048
	ds_read_b128 v[174:177], v145 offset:3072
	s_add_u32 s20, s18, 0x100
	s_addc_u32 s21, s19, 0
	s_add_u32 s22, s4, s18
	s_addc_u32 s23, s52, s19
	s_cmpk_eq_i32 s53, 0x54
	s_cselect_b32 s24, 0, s20
	s_cselect_b32 s25, 0, s21
	s_cselect_b32 s22, s14, s22
	s_cselect_b32 s23, s15, s23
	s_add_u32 s24, s0, s24
	s_addc_u32 s25, s1, s25
	s_mov_b32 m0, s39
	v_lshl_add_u64 v[214:215], v[134:135], 0, s[18:19]
	ds_read_b128 v[182:185], v146
	ds_read_b128 v[186:189], v146 offset:1024
	ds_read_b128 v[190:193], v146 offset:2048
	ds_read_b128 v[194:197], v146 offset:3072
	ds_read_b128 v[198:201], v146 offset:4096
	ds_read_b128 v[202:205], v146 offset:5120
	ds_read_b128 v[206:209], v146 offset:6144
	ds_read_b128 v[210:213], v146 offset:7168
	global_load_lds_dwordx4 v[214:215], off
	v_lshl_add_u64 v[214:215], v[136:137], 0, s[18:19]
	s_mov_b32 m0, s41
	s_nop 0
	global_load_lds_dwordx4 v[214:215], off
	s_waitcnt vmcnt(8)
	s_waitcnt lgkmcnt(0)
	s_barrier
	s_setprio 1
	v_mfma_f32_16x16x32_bf16 v[126:129], v[138:141], v[182:185], v[126:129]
	v_mfma_f32_16x16x32_bf16 v[122:125], v[154:157], v[182:185], v[122:125]
	v_mfma_f32_16x16x32_bf16 v[110:113], v[138:141], v[190:193], v[110:113]
	v_mfma_f32_16x16x32_bf16 v[106:109], v[154:157], v[190:193], v[106:109]
	v_mfma_f32_16x16x32_bf16 v[94:97], v[138:141], v[198:201], v[94:97]
	v_mfma_f32_16x16x32_bf16 v[90:93], v[154:157], v[198:201], v[90:93]
	v_mfma_f32_16x16x32_bf16 v[78:81], v[138:141], v[206:209], v[78:81]
	v_mfma_f32_16x16x32_bf16 v[74:77], v[154:157], v[206:209], v[74:77]
	v_mfma_f32_16x16x32_bf16 v[126:129], v[150:153], v[186:189], v[126:129]
	v_mfma_f32_16x16x32_bf16 v[122:125], v[158:161], v[186:189], v[122:125]
	v_mfma_f32_16x16x32_bf16 v[110:113], v[150:153], v[194:197], v[110:113]
	v_mfma_f32_16x16x32_bf16 v[106:109], v[158:161], v[194:197], v[106:109]
	v_mfma_f32_16x16x32_bf16 v[94:97], v[150:153], v[202:205], v[94:97]
	v_mfma_f32_16x16x32_bf16 v[90:93], v[158:161], v[202:205], v[90:93]
	v_mfma_f32_16x16x32_bf16 v[78:81], v[150:153], v[210:213], v[78:81]
	v_mfma_f32_16x16x32_bf16 v[74:77], v[158:161], v[210:213], v[74:77]
	s_setprio 0
	s_setprio 1
	v_mfma_f32_16x16x32_bf16 v[118:121], v[162:165], v[182:185], v[118:121]
	v_mfma_f32_16x16x32_bf16 v[114:117], v[170:173], v[182:185], v[114:117]
	v_mfma_f32_16x16x32_bf16 v[102:105], v[162:165], v[190:193], v[102:105]
	v_mfma_f32_16x16x32_bf16 v[98:101], v[170:173], v[190:193], v[98:101]
	v_mfma_f32_16x16x32_bf16 v[86:89], v[162:165], v[198:201], v[86:89]
	v_mfma_f32_16x16x32_bf16 v[82:85], v[170:173], v[198:201], v[82:85]
	v_mfma_f32_16x16x32_bf16 v[70:73], v[162:165], v[206:209], v[70:73]
	v_mfma_f32_16x16x32_bf16 v[66:69], v[170:173], v[206:209], v[66:69]
	v_mfma_f32_16x16x32_bf16 v[118:121], v[166:169], v[186:189], v[118:121]
	v_mfma_f32_16x16x32_bf16 v[114:117], v[174:177], v[186:189], v[114:117]
	v_mfma_f32_16x16x32_bf16 v[102:105], v[166:169], v[194:197], v[102:105]
	v_mfma_f32_16x16x32_bf16 v[98:101], v[174:177], v[194:197], v[98:101]
	v_mfma_f32_16x16x32_bf16 v[86:89], v[166:169], v[202:205], v[86:89]
	v_mfma_f32_16x16x32_bf16 v[82:85], v[174:177], v[202:205], v[82:85]
	v_mfma_f32_16x16x32_bf16 v[70:73], v[166:169], v[210:213], v[70:73]
	v_mfma_f32_16x16x32_bf16 v[66:69], v[174:177], v[210:213], v[66:69]
	s_barrier
	s_setprio 0
	s_mov_b32 m0, s42
	v_lshl_add_u64 v[214:215], s[22:23], 0, v[132:133]
	s_add_u32 s18, s22, 0x160000
	ds_read_b128 v[182:185], v146 offset:16384
	ds_read_b128 v[186:189], v146 offset:17408
	ds_read_b128 v[190:193], v146 offset:18432
	ds_read_b128 v[194:197], v146 offset:19456
	ds_read_b128 v[198:201], v146 offset:20480
	ds_read_b128 v[202:205], v146 offset:21504
	ds_read_b128 v[206:209], v146 offset:22528
	ds_read_b128 v[210:213], v146 offset:23552
	global_load_lds_dwordx4 v[214:215], off
	v_lshl_add_u64 v[216:217], s[22:23], 0, v[130:131]
	s_mov_b32 m0, s43
	s_addc_u32 s19, s23, 0
	global_load_lds_dwordx4 v[216:217], off
	v_lshl_add_u64 v[218:219], s[18:19], 0, v[132:133]
	s_mov_b32 m0, s44
	v_lshl_add_u64 v[220:221], s[24:25], 0, v[130:131]
	global_load_lds_dwordx4 v[218:219], off
	v_lshl_add_u64 v[218:219], s[18:19], 0, v[130:131]
	s_mov_b32 m0, s45
	s_nop 0
	global_load_lds_dwordx4 v[218:219], off
	v_lshl_add_u64 v[218:219], s[24:25], 0, v[132:133]
	s_mov_b32 m0, s28
	s_nop 0
	global_load_lds_dwordx4 v[218:219], off
	s_mov_b32 m0, s29
	s_nop 0
	global_load_lds_dwordx4 v[220:221], off
	s_waitcnt vmcnt(8)
	s_waitcnt lgkmcnt(0)
	s_barrier
	s_setprio 1
	v_mfma_f32_16x16x32_bf16 v[62:65], v[138:141], v[182:185], v[62:65]
	v_mfma_f32_16x16x32_bf16 v[58:61], v[154:157], v[182:185], v[58:61]
	v_mfma_f32_16x16x32_bf16 v[46:49], v[138:141], v[190:193], v[46:49]
	v_mfma_f32_16x16x32_bf16 v[42:45], v[154:157], v[190:193], v[42:45]
	v_mfma_f32_16x16x32_bf16 v[30:33], v[138:141], v[198:201], v[30:33]
	v_mfma_f32_16x16x32_bf16 v[26:29], v[154:157], v[198:201], v[26:29]
	v_mfma_f32_16x16x32_bf16 v[14:17], v[138:141], v[206:209], v[14:17]
	v_mfma_f32_16x16x32_bf16 v[10:13], v[154:157], v[206:209], v[10:13]
	v_mfma_f32_16x16x32_bf16 v[62:65], v[150:153], v[186:189], v[62:65]
	v_mfma_f32_16x16x32_bf16 v[58:61], v[158:161], v[186:189], v[58:61]
	v_mfma_f32_16x16x32_bf16 v[46:49], v[150:153], v[194:197], v[46:49]
	v_mfma_f32_16x16x32_bf16 v[42:45], v[158:161], v[194:197], v[42:45]
	v_mfma_f32_16x16x32_bf16 v[30:33], v[150:153], v[202:205], v[30:33]
	v_mfma_f32_16x16x32_bf16 v[26:29], v[158:161], v[202:205], v[26:29]
	v_mfma_f32_16x16x32_bf16 v[14:17], v[150:153], v[210:213], v[14:17]
	v_mfma_f32_16x16x32_bf16 v[10:13], v[158:161], v[210:213], v[10:13]
	s_setprio 0
	s_setprio 1
	v_mfma_f32_16x16x32_bf16 v[54:57], v[162:165], v[182:185], v[54:57]
	v_mfma_f32_16x16x32_bf16 v[50:53], v[170:173], v[182:185], v[50:53]
	v_mfma_f32_16x16x32_bf16 v[38:41], v[162:165], v[190:193], v[38:41]
	v_mfma_f32_16x16x32_bf16 v[34:37], v[170:173], v[190:193], v[34:37]
	v_mfma_f32_16x16x32_bf16 v[22:25], v[162:165], v[198:201], v[22:25]
	v_mfma_f32_16x16x32_bf16 v[18:21], v[170:173], v[198:201], v[18:21]
	v_mfma_f32_16x16x32_bf16 v[6:9], v[162:165], v[206:209], v[6:9]
	v_mfma_f32_16x16x32_bf16 v[2:5], v[170:173], v[206:209], v[2:5]
	v_mfma_f32_16x16x32_bf16 v[54:57], v[166:169], v[186:189], v[54:57]
	v_mfma_f32_16x16x32_bf16 v[50:53], v[174:177], v[186:189], v[50:53]
	v_mfma_f32_16x16x32_bf16 v[38:41], v[166:169], v[194:197], v[38:41]
	v_mfma_f32_16x16x32_bf16 v[34:37], v[174:177], v[194:197], v[34:37]
	v_mfma_f32_16x16x32_bf16 v[22:25], v[166:169], v[202:205], v[22:25]
	v_mfma_f32_16x16x32_bf16 v[18:21], v[174:177], v[202:205], v[18:21]
	v_mfma_f32_16x16x32_bf16 v[6:9], v[166:169], v[210:213], v[6:9]
	v_mfma_f32_16x16x32_bf16 v[2:5], v[174:177], v[210:213], v[2:5]
	s_barrier
	s_setprio 0
	ds_read_b128 v[138:141], v147
	ds_read_b128 v[150:153], v147 offset:1024
	ds_read_b128 v[154:157], v147 offset:2048
	ds_read_b128 v[158:161], v147 offset:3072
	ds_read_b128 v[162:165], v148
	ds_read_b128 v[166:169], v148 offset:1024
	ds_read_b128 v[170:173], v148 offset:2048
	ds_read_b128 v[174:177], v148 offset:3072
	s_add_u32 s18, s24, 0x160000
	s_addc_u32 s19, s25, 0
	s_mov_b32 m0, s30
	v_lshl_add_u64 v[222:223], s[18:19], 0, v[132:133]
	ds_read_b128 v[182:185], v146 offset:32768
	ds_read_b128 v[186:189], v146 offset:33792
	ds_read_b128 v[190:193], v146 offset:34816
	ds_read_b128 v[194:197], v146 offset:35840
	ds_read_b128 v[198:201], v146 offset:36864
	ds_read_b128 v[202:205], v146 offset:37888
	ds_read_b128 v[206:209], v146 offset:38912
	ds_read_b128 v[210:213], v146 offset:39936
	global_load_lds_dwordx4 v[222:223], off
	v_lshl_add_u64 v[222:223], s[18:19], 0, v[130:131]
	s_mov_b32 m0, s31
	s_nop 0
	global_load_lds_dwordx4 v[222:223], off
	s_waitcnt vmcnt(8)
	s_waitcnt lgkmcnt(0)
	s_barrier
	s_setprio 1
	v_mfma_f32_16x16x32_bf16 v[126:129], v[138:141], v[182:185], v[126:129]
	v_mfma_f32_16x16x32_bf16 v[122:125], v[154:157], v[182:185], v[122:125]
	v_mfma_f32_16x16x32_bf16 v[110:113], v[138:141], v[190:193], v[110:113]
	v_mfma_f32_16x16x32_bf16 v[106:109], v[154:157], v[190:193], v[106:109]
	v_mfma_f32_16x16x32_bf16 v[94:97], v[138:141], v[198:201], v[94:97]
	v_mfma_f32_16x16x32_bf16 v[90:93], v[154:157], v[198:201], v[90:93]
	v_mfma_f32_16x16x32_bf16 v[78:81], v[138:141], v[206:209], v[78:81]
	v_mfma_f32_16x16x32_bf16 v[74:77], v[154:157], v[206:209], v[74:77]
	v_mfma_f32_16x16x32_bf16 v[126:129], v[150:153], v[186:189], v[126:129]
	v_mfma_f32_16x16x32_bf16 v[122:125], v[158:161], v[186:189], v[122:125]
	v_mfma_f32_16x16x32_bf16 v[110:113], v[150:153], v[194:197], v[110:113]
	v_mfma_f32_16x16x32_bf16 v[106:109], v[158:161], v[194:197], v[106:109]
	v_mfma_f32_16x16x32_bf16 v[94:97], v[150:153], v[202:205], v[94:97]
	v_mfma_f32_16x16x32_bf16 v[90:93], v[158:161], v[202:205], v[90:93]
	v_mfma_f32_16x16x32_bf16 v[78:81], v[150:153], v[210:213], v[78:81]
	v_mfma_f32_16x16x32_bf16 v[74:77], v[158:161], v[210:213], v[74:77]
	s_setprio 0
	s_setprio 1
	v_mfma_f32_16x16x32_bf16 v[118:121], v[162:165], v[182:185], v[118:121]
	v_mfma_f32_16x16x32_bf16 v[114:117], v[170:173], v[182:185], v[114:117]
	v_mfma_f32_16x16x32_bf16 v[102:105], v[162:165], v[190:193], v[102:105]
	v_mfma_f32_16x16x32_bf16 v[98:101], v[170:173], v[190:193], v[98:101]
	v_mfma_f32_16x16x32_bf16 v[86:89], v[162:165], v[198:201], v[86:89]
	v_mfma_f32_16x16x32_bf16 v[82:85], v[170:173], v[198:201], v[82:85]
	v_mfma_f32_16x16x32_bf16 v[70:73], v[162:165], v[206:209], v[70:73]
	v_mfma_f32_16x16x32_bf16 v[66:69], v[170:173], v[206:209], v[66:69]
	v_mfma_f32_16x16x32_bf16 v[118:121], v[166:169], v[186:189], v[118:121]
	v_mfma_f32_16x16x32_bf16 v[114:117], v[174:177], v[186:189], v[114:117]
	v_mfma_f32_16x16x32_bf16 v[102:105], v[166:169], v[194:197], v[102:105]
	v_mfma_f32_16x16x32_bf16 v[98:101], v[174:177], v[194:197], v[98:101]
	v_mfma_f32_16x16x32_bf16 v[86:89], v[166:169], v[202:205], v[86:89]
	v_mfma_f32_16x16x32_bf16 v[82:85], v[174:177], v[202:205], v[82:85]
	v_mfma_f32_16x16x32_bf16 v[70:73], v[166:169], v[210:213], v[70:73]
	v_mfma_f32_16x16x32_bf16 v[66:69], v[174:177], v[210:213], v[66:69]
	s_barrier
	s_setprio 0
	s_mov_b32 m0, s46
	v_lshl_add_u64 v[214:215], v[214:215], 0, s[10:11]
	s_add_u32 s18, s22, 0x160080
	ds_read_b128 v[182:185], v146 offset:49152
	ds_read_b128 v[186:189], v146 offset:50176
	ds_read_b128 v[190:193], v146 offset:51200
	ds_read_b128 v[194:197], v146 offset:52224
	ds_read_b128 v[198:201], v146 offset:53248
	ds_read_b128 v[202:205], v146 offset:54272
	ds_read_b128 v[206:209], v146 offset:55296
	ds_read_b128 v[210:213], v146 offset:56320
	global_load_lds_dwordx4 v[214:215], off
	v_lshl_add_u64 v[214:215], v[216:217], 0, s[10:11]
	s_mov_b32 m0, s47
	s_addc_u32 s19, s23, 0
	global_load_lds_dwordx4 v[214:215], off
	v_lshl_add_u64 v[214:215], s[18:19], 0, v[132:133]
	s_mov_b32 m0, s48
	s_nop 0
	global_load_lds_dwordx4 v[214:215], off
	v_lshl_add_u64 v[214:215], s[18:19], 0, v[130:131]
	s_mov_b32 m0, s49
	s_nop 0
	global_load_lds_dwordx4 v[214:215], off
	v_lshl_add_u64 v[214:215], v[218:219], 0, s[10:11]
	s_mov_b32 m0, s36
	s_nop 0
	global_load_lds_dwordx4 v[214:215], off
	v_lshl_add_u64 v[214:215], v[220:221], 0, s[10:11]
	s_mov_b32 m0, s37
	s_nop 0
	global_load_lds_dwordx4 v[214:215], off
	s_waitcnt vmcnt(8)
	s_waitcnt lgkmcnt(0)
	s_barrier
	s_setprio 1
	v_mfma_f32_16x16x32_bf16 v[62:65], v[138:141], v[182:185], v[62:65]
	v_mfma_f32_16x16x32_bf16 v[58:61], v[154:157], v[182:185], v[58:61]
	v_mfma_f32_16x16x32_bf16 v[46:49], v[138:141], v[190:193], v[46:49]
	v_mfma_f32_16x16x32_bf16 v[42:45], v[154:157], v[190:193], v[42:45]
	v_mfma_f32_16x16x32_bf16 v[30:33], v[138:141], v[198:201], v[30:33]
	v_mfma_f32_16x16x32_bf16 v[26:29], v[154:157], v[198:201], v[26:29]
	v_mfma_f32_16x16x32_bf16 v[14:17], v[138:141], v[206:209], v[14:17]
	v_mfma_f32_16x16x32_bf16 v[10:13], v[154:157], v[206:209], v[10:13]
	v_mfma_f32_16x16x32_bf16 v[62:65], v[150:153], v[186:189], v[62:65]
	v_mfma_f32_16x16x32_bf16 v[58:61], v[158:161], v[186:189], v[58:61]
	v_mfma_f32_16x16x32_bf16 v[46:49], v[150:153], v[194:197], v[46:49]
	v_mfma_f32_16x16x32_bf16 v[42:45], v[158:161], v[194:197], v[42:45]
	v_mfma_f32_16x16x32_bf16 v[30:33], v[150:153], v[202:205], v[30:33]
	v_mfma_f32_16x16x32_bf16 v[26:29], v[158:161], v[202:205], v[26:29]
	v_mfma_f32_16x16x32_bf16 v[14:17], v[150:153], v[210:213], v[14:17]
	v_mfma_f32_16x16x32_bf16 v[10:13], v[158:161], v[210:213], v[10:13]
	s_setprio 0
	s_setprio 1
	v_mfma_f32_16x16x32_bf16 v[54:57], v[162:165], v[182:185], v[54:57]
	v_mfma_f32_16x16x32_bf16 v[50:53], v[170:173], v[182:185], v[50:53]
	v_mfma_f32_16x16x32_bf16 v[38:41], v[162:165], v[190:193], v[38:41]
	v_mfma_f32_16x16x32_bf16 v[34:37], v[170:173], v[190:193], v[34:37]
	v_mfma_f32_16x16x32_bf16 v[22:25], v[162:165], v[198:201], v[22:25]
	v_mfma_f32_16x16x32_bf16 v[18:21], v[170:173], v[198:201], v[18:21]
	v_mfma_f32_16x16x32_bf16 v[6:9], v[162:165], v[206:209], v[6:9]
	v_mfma_f32_16x16x32_bf16 v[2:5], v[170:173], v[206:209], v[2:5]
	v_mfma_f32_16x16x32_bf16 v[54:57], v[166:169], v[186:189], v[54:57]
	v_mfma_f32_16x16x32_bf16 v[50:53], v[174:177], v[186:189], v[50:53]
	v_mfma_f32_16x16x32_bf16 v[38:41], v[166:169], v[194:197], v[38:41]
	v_mfma_f32_16x16x32_bf16 v[34:37], v[174:177], v[194:197], v[34:37]
	v_mfma_f32_16x16x32_bf16 v[22:25], v[166:169], v[202:205], v[22:25]
	v_mfma_f32_16x16x32_bf16 v[18:21], v[174:177], v[202:205], v[18:21]
	v_mfma_f32_16x16x32_bf16 v[6:9], v[166:169], v[210:213], v[6:9]
	v_mfma_f32_16x16x32_bf16 v[2:5], v[174:177], v[210:213], v[2:5]
	s_barrier
	s_setprio 0
	s_add_i32 s53, s53, 2
	s_cmpk_gt_u32 s53, 0x55
	s_mov_b64 s[18:19], s[20:21]
	s_cbranch_scc0 .LBB0_2644
	s_and_b64 vcc, exec, s[12:13]
	s_cbranch_vccz .LBB0_2647
	s_barrier

.LBB0_3114:
	ds_read_b128 v[142:145], v148
	ds_read_b128 v[152:155], v148 offset:1024
	ds_read_b128 v[156:159], v148 offset:2048
	ds_read_b128 v[160:163], v148 offset:3072
	ds_read_b128 v[164:167], v149
	ds_read_b128 v[168:171], v149 offset:1024
	ds_read_b128 v[172:175], v149 offset:2048
	ds_read_b128 v[176:179], v149 offset:3072
	s_add_u32 s26, s24, 0x100
	s_addc_u32 s27, s25, 0
	s_cmp_eq_u32 s55, 28
	s_cselect_b32 s31, s19, s27
	s_cselect_b32 s30, s51, s26
	s_cselect_b32 s29, s17, s54
	s_cselect_b32 s28, s52, s53
	v_lshl_add_u64 v[212:213], s[24:25], 0, v[134:135]
	s_add_i32 m0, s5, 0xc000
	ds_read_b128 v[180:183], v150
	ds_read_b128 v[184:187], v150 offset:1024
	ds_read_b128 v[188:191], v150 offset:2048
	ds_read_b128 v[192:195], v150 offset:3072
	ds_read_b128 v[196:199], v150 offset:4096
	ds_read_b128 v[200:203], v150 offset:5120
	ds_read_b128 v[204:207], v150 offset:6144
	ds_read_b128 v[208:211], v150 offset:7168
	global_load_lds_dwordx4 v[212:213], off
	v_lshl_add_u64 v[212:213], s[24:25], 0, v[136:137]
	s_add_i32 m0, s5, 0xe000
	s_nop 0
	global_load_lds_dwordx4 v[212:213], off
	s_waitcnt vmcnt(8)
	s_waitcnt lgkmcnt(0)
	s_barrier
	s_setprio 1
	v_mfma_f32_16x16x32_bf16 v[126:129], v[142:145], v[180:183], v[126:129]
	v_mfma_f32_16x16x32_bf16 v[122:125], v[156:159], v[180:183], v[122:125]
	v_mfma_f32_16x16x32_bf16 v[110:113], v[142:145], v[188:191], v[110:113]
	v_mfma_f32_16x16x32_bf16 v[106:109], v[156:159], v[188:191], v[106:109]
	v_mfma_f32_16x16x32_bf16 v[94:97], v[142:145], v[196:199], v[94:97]
	v_mfma_f32_16x16x32_bf16 v[90:93], v[156:159], v[196:199], v[90:93]
	v_mfma_f32_16x16x32_bf16 v[78:81], v[142:145], v[204:207], v[78:81]
	v_mfma_f32_16x16x32_bf16 v[74:77], v[156:159], v[204:207], v[74:77]
	v_mfma_f32_16x16x32_bf16 v[126:129], v[152:155], v[184:187], v[126:129]
	v_mfma_f32_16x16x32_bf16 v[122:125], v[160:163], v[184:187], v[122:125]
	v_mfma_f32_16x16x32_bf16 v[110:113], v[152:155], v[192:195], v[110:113]
	v_mfma_f32_16x16x32_bf16 v[106:109], v[160:163], v[192:195], v[106:109]
	v_mfma_f32_16x16x32_bf16 v[94:97], v[152:155], v[200:203], v[94:97]
	v_mfma_f32_16x16x32_bf16 v[90:93], v[160:163], v[200:203], v[90:93]
	v_mfma_f32_16x16x32_bf16 v[78:81], v[152:155], v[208:211], v[78:81]
	v_mfma_f32_16x16x32_bf16 v[74:77], v[160:163], v[208:211], v[74:77]
	s_setprio 0
	s_setprio 1
	v_mfma_f32_16x16x32_bf16 v[118:121], v[164:167], v[180:183], v[118:121]
	v_mfma_f32_16x16x32_bf16 v[114:117], v[172:175], v[180:183], v[114:117]
	v_mfma_f32_16x16x32_bf16 v[102:105], v[164:167], v[188:191], v[102:105]
	v_mfma_f32_16x16x32_bf16 v[98:101], v[172:175], v[188:191], v[98:101]
	v_mfma_f32_16x16x32_bf16 v[86:89], v[164:167], v[196:199], v[86:89]
	v_mfma_f32_16x16x32_bf16 v[82:85], v[172:175], v[196:199], v[82:85]
	v_mfma_f32_16x16x32_bf16 v[70:73], v[164:167], v[204:207], v[70:73]
	v_mfma_f32_16x16x32_bf16 v[66:69], v[172:175], v[204:207], v[66:69]
	v_mfma_f32_16x16x32_bf16 v[118:121], v[168:171], v[184:187], v[118:121]
	v_mfma_f32_16x16x32_bf16 v[114:117], v[176:179], v[184:187], v[114:117]
	v_mfma_f32_16x16x32_bf16 v[102:105], v[168:171], v[192:195], v[102:105]
	v_mfma_f32_16x16x32_bf16 v[98:101], v[176:179], v[192:195], v[98:101]
	v_mfma_f32_16x16x32_bf16 v[86:89], v[168:171], v[200:203], v[86:89]
	v_mfma_f32_16x16x32_bf16 v[82:85], v[176:179], v[200:203], v[82:85]
	v_mfma_f32_16x16x32_bf16 v[70:73], v[168:171], v[208:211], v[70:73]
	v_mfma_f32_16x16x32_bf16 v[66:69], v[176:179], v[208:211], v[66:69]
	s_barrier
	s_setprio 0
	s_add_i32 s24, s48, s37
	v_lshl_add_u64 v[212:213], s[28:29], 0, v[130:131]
	s_mov_b32 m0, s24
	ds_read_b128 v[180:183], v150 offset:16384
	ds_read_b128 v[184:187], v150 offset:17408
	ds_read_b128 v[188:191], v150 offset:18432
	ds_read_b128 v[192:195], v150 offset:19456
	ds_read_b128 v[196:199], v150 offset:20480
	ds_read_b128 v[200:203], v150 offset:21504
	ds_read_b128 v[204:207], v150 offset:22528
	ds_read_b128 v[208:211], v150 offset:23552
	global_load_lds_dwordx4 v[212:213], off
	s_add_i32 m0, s24, 0x2000
	s_add_u32 s24, s28, 0x80000
	v_lshl_add_u64 v[214:215], s[28:29], 0, v[132:133]
	s_addc_u32 s25, s29, 0
	s_add_i32 s56, s49, s37
	global_load_lds_dwordx4 v[214:215], off
	v_lshl_add_u64 v[216:217], s[24:25], 0, v[130:131]
	s_mov_b32 m0, s56
	v_lshl_add_u64 v[218:219], s[30:31], 0, v[132:133]
	global_load_lds_dwordx4 v[216:217], off
	v_lshl_add_u64 v[216:217], s[24:25], 0, v[132:133]
	s_add_i32 m0, s56, 0x2000
	s_nop 0
	global_load_lds_dwordx4 v[216:217], off
	v_lshl_add_u64 v[216:217], s[30:31], 0, v[130:131]
	s_mov_b32 m0, s5
	s_nop 0
	global_load_lds_dwordx4 v[216:217], off
	s_mov_b32 m0, s38
	s_nop 0
	global_load_lds_dwordx4 v[218:219], off
	s_waitcnt vmcnt(8)
	s_waitcnt lgkmcnt(0)
	s_barrier
	s_setprio 1
	v_mfma_f32_16x16x32_bf16 v[62:65], v[142:145], v[180:183], v[62:65]
	v_mfma_f32_16x16x32_bf16 v[58:61], v[156:159], v[180:183], v[58:61]
	v_mfma_f32_16x16x32_bf16 v[46:49], v[142:145], v[188:191], v[46:49]
	v_mfma_f32_16x16x32_bf16 v[42:45], v[156:159], v[188:191], v[42:45]
	v_mfma_f32_16x16x32_bf16 v[30:33], v[142:145], v[196:199], v[30:33]
	v_mfma_f32_16x16x32_bf16 v[26:29], v[156:159], v[196:199], v[26:29]
	v_mfma_f32_16x16x32_bf16 v[14:17], v[142:145], v[204:207], v[14:17]
	v_mfma_f32_16x16x32_bf16 v[10:13], v[156:159], v[204:207], v[10:13]
	v_mfma_f32_16x16x32_bf16 v[62:65], v[152:155], v[184:187], v[62:65]
	v_mfma_f32_16x16x32_bf16 v[58:61], v[160:163], v[184:187], v[58:61]
	v_mfma_f32_16x16x32_bf16 v[46:49], v[152:155], v[192:195], v[46:49]
	v_mfma_f32_16x16x32_bf16 v[42:45], v[160:163], v[192:195], v[42:45]
	v_mfma_f32_16x16x32_bf16 v[30:33], v[152:155], v[200:203], v[30:33]
	v_mfma_f32_16x16x32_bf16 v[26:29], v[160:163], v[200:203], v[26:29]
	v_mfma_f32_16x16x32_bf16 v[14:17], v[152:155], v[208:211], v[14:17]
	v_mfma_f32_16x16x32_bf16 v[10:13], v[160:163], v[208:211], v[10:13]
	s_setprio 0
	s_setprio 1
	v_mfma_f32_16x16x32_bf16 v[54:57], v[164:167], v[180:183], v[54:57]
	v_mfma_f32_16x16x32_bf16 v[50:53], v[172:175], v[180:183], v[50:53]
	v_mfma_f32_16x16x32_bf16 v[38:41], v[164:167], v[188:191], v[38:41]
	v_mfma_f32_16x16x32_bf16 v[34:37], v[172:175], v[188:191], v[34:37]
	v_mfma_f32_16x16x32_bf16 v[22:25], v[164:167], v[196:199], v[22:25]
	v_mfma_f32_16x16x32_bf16 v[18:21], v[172:175], v[196:199], v[18:21]
	v_mfma_f32_16x16x32_bf16 v[6:9], v[164:167], v[204:207], v[6:9]
	v_mfma_f32_16x16x32_bf16 v[2:5], v[172:175], v[204:207], v[2:5]
	v_mfma_f32_16x16x32_bf16 v[54:57], v[168:171], v[184:187], v[54:57]
	v_mfma_f32_16x16x32_bf16 v[50:53], v[176:179], v[184:187], v[50:53]
	v_mfma_f32_16x16x32_bf16 v[38:41], v[168:171], v[192:195], v[38:41]
	v_mfma_f32_16x16x32_bf16 v[34:37], v[176:179], v[192:195], v[34:37]
	v_mfma_f32_16x16x32_bf16 v[22:25], v[168:171], v[200:203], v[22:25]
	v_mfma_f32_16x16x32_bf16 v[18:21], v[176:179], v[200:203], v[18:21]
	v_mfma_f32_16x16x32_bf16 v[6:9], v[168:171], v[208:211], v[6:9]
	v_mfma_f32_16x16x32_bf16 v[2:5], v[176:179], v[208:211], v[2:5]
	s_barrier
	s_setprio 0
	s_add_i32 s56, 0, 0x18000
	s_add_i32 s57, 0, 0x1c000
	v_add_u32_e32 v160, s56, v147
	v_add_u32_e32 v176, s57, v147
	ds_read_b128 v[142:145], v160
	ds_read_b128 v[152:155], v160 offset:1024
	ds_read_b128 v[156:159], v160 offset:2048
	ds_read_b128 v[160:163], v160 offset:3072
	ds_read_b128 v[164:167], v176
	ds_read_b128 v[168:171], v176 offset:1024
	ds_read_b128 v[172:175], v176 offset:2048
	ds_read_b128 v[176:179], v176 offset:3072
	s_add_u32 s24, s30, 0x80000
	s_addc_u32 s25, s31, 0
	s_mov_b32 m0, s39
	v_lshl_add_u64 v[220:221], s[24:25], 0, v[130:131]
	ds_read_b128 v[180:183], v150 offset:32768
	ds_read_b128 v[184:187], v150 offset:33792
	ds_read_b128 v[188:191], v150 offset:34816
	ds_read_b128 v[192:195], v150 offset:35840
	ds_read_b128 v[196:199], v150 offset:36864
	ds_read_b128 v[200:203], v150 offset:37888
	ds_read_b128 v[204:207], v150 offset:38912
	ds_read_b128 v[208:211], v150 offset:39936
	global_load_lds_dwordx4 v[220:221], off
	v_lshl_add_u64 v[220:221], s[24:25], 0, v[132:133]
	s_mov_b32 m0, s40
	s_nop 0
	global_load_lds_dwordx4 v[220:221], off
	s_waitcnt vmcnt(8)
	s_waitcnt lgkmcnt(0)
	s_barrier
	s_setprio 1
	v_mfma_f32_16x16x32_bf16 v[126:129], v[142:145], v[180:183], v[126:129]
	v_mfma_f32_16x16x32_bf16 v[122:125], v[156:159], v[180:183], v[122:125]
	v_mfma_f32_16x16x32_bf16 v[110:113], v[142:145], v[188:191], v[110:113]
	v_mfma_f32_16x16x32_bf16 v[106:109], v[156:159], v[188:191], v[106:109]
	v_mfma_f32_16x16x32_bf16 v[94:97], v[142:145], v[196:199], v[94:97]
	v_mfma_f32_16x16x32_bf16 v[90:93], v[156:159], v[196:199], v[90:93]
	v_mfma_f32_16x16x32_bf16 v[78:81], v[142:145], v[204:207], v[78:81]
	v_mfma_f32_16x16x32_bf16 v[74:77], v[156:159], v[204:207], v[74:77]
	v_mfma_f32_16x16x32_bf16 v[126:129], v[152:155], v[184:187], v[126:129]
	v_mfma_f32_16x16x32_bf16 v[122:125], v[160:163], v[184:187], v[122:125]
	v_mfma_f32_16x16x32_bf16 v[110:113], v[152:155], v[192:195], v[110:113]
	v_mfma_f32_16x16x32_bf16 v[106:109], v[160:163], v[192:195], v[106:109]
	v_mfma_f32_16x16x32_bf16 v[94:97], v[152:155], v[200:203], v[94:97]
	v_mfma_f32_16x16x32_bf16 v[90:93], v[160:163], v[200:203], v[90:93]
	v_mfma_f32_16x16x32_bf16 v[78:81], v[152:155], v[208:211], v[78:81]
	v_mfma_f32_16x16x32_bf16 v[74:77], v[160:163], v[208:211], v[74:77]
	s_setprio 0
	s_setprio 1
	v_mfma_f32_16x16x32_bf16 v[118:121], v[164:167], v[180:183], v[118:121]
	v_mfma_f32_16x16x32_bf16 v[114:117], v[172:175], v[180:183], v[114:117]
	v_mfma_f32_16x16x32_bf16 v[102:105], v[164:167], v[188:191], v[102:105]
	v_mfma_f32_16x16x32_bf16 v[98:101], v[172:175], v[188:191], v[98:101]
	v_mfma_f32_16x16x32_bf16 v[86:89], v[164:167], v[196:199], v[86:89]
	v_mfma_f32_16x16x32_bf16 v[82:85], v[172:175], v[196:199], v[82:85]
	v_mfma_f32_16x16x32_bf16 v[70:73], v[164:167], v[204:207], v[70:73]
	v_mfma_f32_16x16x32_bf16 v[66:69], v[172:175], v[204:207], v[66:69]
	v_mfma_f32_16x16x32_bf16 v[118:121], v[168:171], v[184:187], v[118:121]
	v_mfma_f32_16x16x32_bf16 v[114:117], v[176:179], v[184:187], v[114:117]
	v_mfma_f32_16x16x32_bf16 v[102:105], v[168:171], v[192:195], v[102:105]
	v_mfma_f32_16x16x32_bf16 v[98:101], v[176:179], v[192:195], v[98:101]
	v_mfma_f32_16x16x32_bf16 v[86:89], v[168:171], v[200:203], v[86:89]
	v_mfma_f32_16x16x32_bf16 v[82:85], v[176:179], v[200:203], v[82:85]
	v_mfma_f32_16x16x32_bf16 v[70:73], v[168:171], v[208:211], v[70:73]
	v_mfma_f32_16x16x32_bf16 v[66:69], v[176:179], v[208:211], v[66:69]
	s_barrier
	s_setprio 0
	s_add_i32 s24, s56, s37
	v_lshl_add_u64 v[212:213], v[212:213], 0, s[12:13]
	s_mov_b32 m0, s24
	ds_read_b128 v[180:183], v150 offset:49152
	ds_read_b128 v[184:187], v150 offset:50176
	ds_read_b128 v[188:191], v150 offset:51200
	ds_read_b128 v[192:195], v150 offset:52224
	ds_read_b128 v[196:199], v150 offset:53248
	ds_read_b128 v[200:203], v150 offset:54272
	ds_read_b128 v[204:207], v150 offset:55296
	ds_read_b128 v[208:211], v150 offset:56320
	global_load_lds_dwordx4 v[212:213], off
	s_add_i32 m0, s24, 0x2000
	s_add_u32 s24, s28, 0x80080
	v_lshl_add_u64 v[212:213], v[214:215], 0, s[12:13]
	s_addc_u32 s25, s29, 0
	s_add_i32 s28, s57, s37
	global_load_lds_dwordx4 v[212:213], off
	v_lshl_add_u64 v[212:213], s[24:25], 0, v[130:131]
	s_mov_b32 m0, s28
	s_nop 0
	global_load_lds_dwordx4 v[212:213], off
	v_lshl_add_u64 v[212:213], s[24:25], 0, v[132:133]
	s_add_i32 m0, s28, 0x2000
	s_nop 0
	global_load_lds_dwordx4 v[212:213], off
	v_lshl_add_u64 v[212:213], v[216:217], 0, s[12:13]
	s_mov_b32 m0, s44
	s_nop 0
	global_load_lds_dwordx4 v[212:213], off
	v_lshl_add_u64 v[212:213], v[218:219], 0, s[12:13]
	s_mov_b32 m0, s45
	s_nop 0
	global_load_lds_dwordx4 v[212:213], off
	s_waitcnt vmcnt(8)
	s_waitcnt lgkmcnt(0)
	s_barrier
	s_setprio 1
	v_mfma_f32_16x16x32_bf16 v[62:65], v[142:145], v[180:183], v[62:65]
	v_mfma_f32_16x16x32_bf16 v[58:61], v[156:159], v[180:183], v[58:61]
	v_mfma_f32_16x16x32_bf16 v[46:49], v[142:145], v[188:191], v[46:49]
	v_mfma_f32_16x16x32_bf16 v[42:45], v[156:159], v[188:191], v[42:45]
	v_mfma_f32_16x16x32_bf16 v[30:33], v[142:145], v[196:199], v[30:33]
	v_mfma_f32_16x16x32_bf16 v[26:29], v[156:159], v[196:199], v[26:29]
	v_mfma_f32_16x16x32_bf16 v[14:17], v[142:145], v[204:207], v[14:17]
	v_mfma_f32_16x16x32_bf16 v[10:13], v[156:159], v[204:207], v[10:13]
	v_mfma_f32_16x16x32_bf16 v[62:65], v[152:155], v[184:187], v[62:65]
	v_mfma_f32_16x16x32_bf16 v[58:61], v[160:163], v[184:187], v[58:61]
	v_mfma_f32_16x16x32_bf16 v[46:49], v[152:155], v[192:195], v[46:49]
	v_mfma_f32_16x16x32_bf16 v[42:45], v[160:163], v[192:195], v[42:45]
	v_mfma_f32_16x16x32_bf16 v[30:33], v[152:155], v[200:203], v[30:33]
	v_mfma_f32_16x16x32_bf16 v[26:29], v[160:163], v[200:203], v[26:29]
	v_mfma_f32_16x16x32_bf16 v[14:17], v[152:155], v[208:211], v[14:17]
	v_mfma_f32_16x16x32_bf16 v[10:13], v[160:163], v[208:211], v[10:13]
	s_setprio 0
	s_setprio 1
	v_mfma_f32_16x16x32_bf16 v[54:57], v[164:167], v[180:183], v[54:57]
	v_mfma_f32_16x16x32_bf16 v[50:53], v[172:175], v[180:183], v[50:53]
	v_mfma_f32_16x16x32_bf16 v[38:41], v[164:167], v[188:191], v[38:41]
	v_mfma_f32_16x16x32_bf16 v[34:37], v[172:175], v[188:191], v[34:37]
	v_mfma_f32_16x16x32_bf16 v[22:25], v[164:167], v[196:199], v[22:25]
	v_mfma_f32_16x16x32_bf16 v[18:21], v[172:175], v[196:199], v[18:21]
	v_mfma_f32_16x16x32_bf16 v[6:9], v[164:167], v[204:207], v[6:9]
	v_mfma_f32_16x16x32_bf16 v[2:5], v[172:175], v[204:207], v[2:5]
	v_mfma_f32_16x16x32_bf16 v[54:57], v[168:171], v[184:187], v[54:57]
	v_mfma_f32_16x16x32_bf16 v[50:53], v[176:179], v[184:187], v[50:53]
	v_mfma_f32_16x16x32_bf16 v[38:41], v[168:171], v[192:195], v[38:41]
	v_mfma_f32_16x16x32_bf16 v[34:37], v[176:179], v[192:195], v[34:37]
	v_mfma_f32_16x16x32_bf16 v[22:25], v[168:171], v[200:203], v[22:25]
	v_mfma_f32_16x16x32_bf16 v[18:21], v[176:179], v[200:203], v[18:21]
	v_mfma_f32_16x16x32_bf16 v[6:9], v[168:171], v[208:211], v[6:9]
	v_mfma_f32_16x16x32_bf16 v[2:5], v[176:179], v[208:211], v[2:5]
	s_barrier
	s_setprio 0
	s_add_i32 s55, s55, 2
	s_add_u32 s53, s53, 0x100
	s_addc_u32 s54, s54, 0
	s_cmp_gt_u32 s55, 29
	s_mov_b64 s[24:25], s[26:27]
	s_cbranch_scc0 .LBB0_3114
	s_and_b64 vcc, exec, s[14:15]
	s_cbranch_vccz .LBB0_3117
	s_barrier

.LBB0_3201:
	s_waitcnt lgkmcnt(0)
	s_add_u32 s40, s8, 0xfff80080
	s_addc_u32 s41, s9, -1
	s_cmp_eq_u32 s66, 28
	s_cselect_b32 s43, s7, s41
	s_cselect_b32 s42, s35, s40
	s_cselect_b32 s41, s31, s65
	s_cselect_b32 s40, s63, s64
	v_lshl_add_u64 v[216:217], s[8:9], 0, v[138:139]
	s_add_i32 m0, s46, 0xc000
	s_nop 0
	global_load_lds_dwordx4 v[216:217], off
	v_lshl_add_u64 v[216:217], s[8:9], 0, v[140:141]
	s_add_i32 m0, s46, 0xe000
	s_nop 0
	global_load_lds_dwordx4 v[216:217], off
	ds_read_b128 v[146:149], v164
	ds_read_b128 v[150:153], v164 offset:1024
	ds_read_b128 v[154:157], v164 offset:2048
	ds_read_b128 v[158:161], v164 offset:3072
	ds_read_b128 v[168:171], v165
	ds_read_b128 v[172:175], v165 offset:1024
	ds_read_b128 v[176:179], v165 offset:2048
	ds_read_b128 v[180:183], v165 offset:3072
	ds_read_b128 v[184:187], v166
	ds_read_b128 v[188:191], v166 offset:1024
	ds_read_b128 v[192:195], v166 offset:2048
	ds_read_b128 v[196:199], v166 offset:3072
	ds_read_b128 v[200:203], v166 offset:4096
	ds_read_b128 v[204:207], v166 offset:5120
	ds_read_b128 v[208:211], v166 offset:6144
	ds_read_b128 v[212:215], v166 offset:7168
	s_waitcnt vmcnt(8)
	s_waitcnt lgkmcnt(0)
	s_barrier
	s_setprio 1
	v_mfma_f32_16x16x32_bf16 v[126:129], v[146:149], v[184:187], v[126:129]
	v_mfma_f32_16x16x32_bf16 v[122:125], v[154:157], v[184:187], v[122:125]
	v_mfma_f32_16x16x32_bf16 v[118:121], v[146:149], v[192:195], v[118:121]
	v_mfma_f32_16x16x32_bf16 v[110:113], v[154:157], v[192:195], v[110:113]
	v_mfma_f32_16x16x32_bf16 v[102:105], v[146:149], v[200:203], v[102:105]
	v_mfma_f32_16x16x32_bf16 v[94:97], v[154:157], v[200:203], v[94:97]
	v_mfma_f32_16x16x32_bf16 v[86:89], v[146:149], v[208:211], v[86:89]
	v_mfma_f32_16x16x32_bf16 v[78:81], v[154:157], v[208:211], v[78:81]
	v_mfma_f32_16x16x32_bf16 v[126:129], v[150:153], v[188:191], v[126:129]
	v_mfma_f32_16x16x32_bf16 v[122:125], v[158:161], v[188:191], v[122:125]
	v_mfma_f32_16x16x32_bf16 v[118:121], v[150:153], v[196:199], v[118:121]
	v_mfma_f32_16x16x32_bf16 v[110:113], v[158:161], v[196:199], v[110:113]
	v_mfma_f32_16x16x32_bf16 v[102:105], v[150:153], v[204:207], v[102:105]
	v_mfma_f32_16x16x32_bf16 v[94:97], v[158:161], v[204:207], v[94:97]
	v_mfma_f32_16x16x32_bf16 v[86:89], v[150:153], v[212:215], v[86:89]
	v_mfma_f32_16x16x32_bf16 v[78:81], v[158:161], v[212:215], v[78:81]
	s_setprio 0
	s_setprio 1
	v_mfma_f32_16x16x32_bf16 v[114:117], v[168:171], v[184:187], v[114:117]
	v_mfma_f32_16x16x32_bf16 v[106:109], v[176:179], v[184:187], v[106:109]
	v_mfma_f32_16x16x32_bf16 v[98:101], v[168:171], v[192:195], v[98:101]
	v_mfma_f32_16x16x32_bf16 v[90:93], v[176:179], v[192:195], v[90:93]
	v_mfma_f32_16x16x32_bf16 v[82:85], v[168:171], v[200:203], v[82:85]
	v_mfma_f32_16x16x32_bf16 v[74:77], v[176:179], v[200:203], v[74:77]
	v_mfma_f32_16x16x32_bf16 v[70:73], v[168:171], v[208:211], v[70:73]
	v_mfma_f32_16x16x32_bf16 v[66:69], v[176:179], v[208:211], v[66:69]
	v_mfma_f32_16x16x32_bf16 v[114:117], v[172:175], v[188:191], v[114:117]
	v_mfma_f32_16x16x32_bf16 v[106:109], v[180:183], v[188:191], v[106:109]
	v_mfma_f32_16x16x32_bf16 v[98:101], v[172:175], v[196:199], v[98:101]
	v_mfma_f32_16x16x32_bf16 v[90:93], v[180:183], v[196:199], v[90:93]
	v_mfma_f32_16x16x32_bf16 v[82:85], v[172:175], v[204:207], v[82:85]
	v_mfma_f32_16x16x32_bf16 v[74:77], v[180:183], v[204:207], v[74:77]
	v_mfma_f32_16x16x32_bf16 v[70:73], v[172:175], v[212:215], v[70:73]
	v_mfma_f32_16x16x32_bf16 v[66:69], v[180:183], v[212:215], v[66:69]
	s_barrier
	s_setprio 0
	s_add_i32 s67, s56, s33
	v_lshl_add_u64 v[216:217], s[40:41], 0, v[134:135]
	s_mov_b32 m0, s67
	s_nop 0
	global_load_lds_dwordx4 v[216:217], off
	s_add_i32 m0, s67, 0x2000
	s_add_u32 s68, s40, 0x80000
	v_lshl_add_u64 v[218:219], s[40:41], 0, v[130:131]
	s_addc_u32 s69, s41, 0
	s_add_i32 s67, s57, s33
	global_load_lds_dwordx4 v[218:219], off
	v_lshl_add_u64 v[220:221], s[68:69], 0, v[134:135]
	s_mov_b32 m0, s67
	v_lshl_add_u64 v[222:223], s[42:43], 0, v[132:133]
	global_load_lds_dwordx4 v[220:221], off
	v_lshl_add_u64 v[220:221], s[68:69], 0, v[130:131]
	s_add_i32 m0, s67, 0x2000
	s_nop 0
	global_load_lds_dwordx4 v[220:221], off
	v_lshl_add_u64 v[220:221], s[42:43], 0, v[136:137]
	s_mov_b32 m0, s46
	s_nop 0
	global_load_lds_dwordx4 v[220:221], off
	s_mov_b32 m0, s47
	s_nop 0
	global_load_lds_dwordx4 v[222:223], off
	ds_read_b128 v[184:187], v166 offset:16384
	ds_read_b128 v[188:191], v166 offset:17408
	ds_read_b128 v[192:195], v166 offset:18432
	ds_read_b128 v[196:199], v166 offset:19456
	ds_read_b128 v[200:203], v166 offset:20480
	ds_read_b128 v[204:207], v166 offset:21504
	ds_read_b128 v[208:211], v166 offset:22528
	ds_read_b128 v[212:215], v166 offset:23552
	s_waitcnt vmcnt(8)
	s_waitcnt lgkmcnt(0)
	s_barrier
	s_setprio 1
	v_mfma_f32_16x16x32_bf16 v[62:65], v[146:149], v[184:187], v[62:65]
	v_mfma_f32_16x16x32_bf16 v[58:61], v[154:157], v[184:187], v[58:61]
	v_mfma_f32_16x16x32_bf16 v[54:57], v[146:149], v[192:195], v[54:57]
	v_mfma_f32_16x16x32_bf16 v[46:49], v[154:157], v[192:195], v[46:49]
	v_mfma_f32_16x16x32_bf16 v[38:41], v[146:149], v[200:203], v[38:41]
	v_mfma_f32_16x16x32_bf16 v[30:33], v[154:157], v[200:203], v[30:33]
	v_mfma_f32_16x16x32_bf16 v[22:25], v[146:149], v[208:211], v[22:25]
	v_mfma_f32_16x16x32_bf16 v[14:17], v[154:157], v[208:211], v[14:17]
	v_mfma_f32_16x16x32_bf16 v[62:65], v[150:153], v[188:191], v[62:65]
	v_mfma_f32_16x16x32_bf16 v[58:61], v[158:161], v[188:191], v[58:61]
	v_mfma_f32_16x16x32_bf16 v[54:57], v[150:153], v[196:199], v[54:57]
	v_mfma_f32_16x16x32_bf16 v[46:49], v[158:161], v[196:199], v[46:49]
	v_mfma_f32_16x16x32_bf16 v[38:41], v[150:153], v[204:207], v[38:41]
	v_mfma_f32_16x16x32_bf16 v[30:33], v[158:161], v[204:207], v[30:33]
	v_mfma_f32_16x16x32_bf16 v[22:25], v[150:153], v[212:215], v[22:25]
	v_mfma_f32_16x16x32_bf16 v[14:17], v[158:161], v[212:215], v[14:17]
	s_setprio 0
	s_setprio 1
	v_mfma_f32_16x16x32_bf16 v[50:53], v[168:171], v[184:187], v[50:53]
	v_mfma_f32_16x16x32_bf16 v[42:45], v[176:179], v[184:187], v[42:45]
	v_mfma_f32_16x16x32_bf16 v[34:37], v[168:171], v[192:195], v[34:37]
	v_mfma_f32_16x16x32_bf16 v[26:29], v[176:179], v[192:195], v[26:29]
	v_mfma_f32_16x16x32_bf16 v[18:21], v[168:171], v[200:203], v[18:21]
	v_mfma_f32_16x16x32_bf16 v[10:13], v[176:179], v[200:203], v[10:13]
	v_mfma_f32_16x16x32_bf16 v[6:9], v[168:171], v[208:211], v[6:9]
	v_mfma_f32_16x16x32_bf16 v[2:5], v[176:179], v[208:211], v[2:5]
	v_mfma_f32_16x16x32_bf16 v[50:53], v[172:175], v[188:191], v[50:53]
	v_mfma_f32_16x16x32_bf16 v[42:45], v[180:183], v[188:191], v[42:45]
	v_mfma_f32_16x16x32_bf16 v[34:37], v[172:175], v[196:199], v[34:37]
	v_mfma_f32_16x16x32_bf16 v[26:29], v[180:183], v[196:199], v[26:29]
	v_mfma_f32_16x16x32_bf16 v[18:21], v[172:175], v[204:207], v[18:21]
	v_mfma_f32_16x16x32_bf16 v[10:13], v[180:183], v[204:207], v[10:13]
	v_mfma_f32_16x16x32_bf16 v[6:9], v[172:175], v[212:215], v[6:9]
	v_mfma_f32_16x16x32_bf16 v[2:5], v[180:183], v[212:215], v[2:5]
	s_barrier
	s_setprio 0
	s_add_i32 s67, 0, 0x18000
	s_add_i32 s68, 0, 0x1c000
	v_add_u32_e32 v158, s67, v163
	v_add_u32_e32 v180, s68, v163
	s_add_u32 s42, s42, 0x80000
	s_addc_u32 s43, s43, 0
	s_mov_b32 m0, s48
	v_lshl_add_u64 v[224:225], s[42:43], 0, v[136:137]
	global_load_lds_dwordx4 v[224:225], off
	v_lshl_add_u64 v[224:225], s[42:43], 0, v[132:133]
	s_mov_b32 m0, s49
	s_nop 0
	global_load_lds_dwordx4 v[224:225], off
	ds_read_b128 v[146:149], v158
	ds_read_b128 v[150:153], v158 offset:1024
	ds_read_b128 v[154:157], v158 offset:2048
	ds_read_b128 v[158:161], v158 offset:3072
	ds_read_b128 v[168:171], v180
	ds_read_b128 v[172:175], v180 offset:1024
	ds_read_b128 v[176:179], v180 offset:2048
	ds_read_b128 v[180:183], v180 offset:3072
	ds_read_b128 v[184:187], v166 offset:32768
	ds_read_b128 v[188:191], v166 offset:33792
	ds_read_b128 v[192:195], v166 offset:34816
	ds_read_b128 v[196:199], v166 offset:35840
	ds_read_b128 v[200:203], v166 offset:36864
	ds_read_b128 v[204:207], v166 offset:37888
	ds_read_b128 v[208:211], v166 offset:38912
	ds_read_b128 v[212:215], v166 offset:39936
	s_waitcnt vmcnt(8)
	s_waitcnt lgkmcnt(0)
	s_barrier
	s_setprio 1
	v_mfma_f32_16x16x32_bf16 v[126:129], v[146:149], v[184:187], v[126:129]
	v_mfma_f32_16x16x32_bf16 v[122:125], v[154:157], v[184:187], v[122:125]
	v_mfma_f32_16x16x32_bf16 v[118:121], v[146:149], v[192:195], v[118:121]
	v_mfma_f32_16x16x32_bf16 v[110:113], v[154:157], v[192:195], v[110:113]
	v_mfma_f32_16x16x32_bf16 v[102:105], v[146:149], v[200:203], v[102:105]
	v_mfma_f32_16x16x32_bf16 v[94:97], v[154:157], v[200:203], v[94:97]
	v_mfma_f32_16x16x32_bf16 v[86:89], v[146:149], v[208:211], v[86:89]
	v_mfma_f32_16x16x32_bf16 v[78:81], v[154:157], v[208:211], v[78:81]
	v_mfma_f32_16x16x32_bf16 v[126:129], v[150:153], v[188:191], v[126:129]
	v_mfma_f32_16x16x32_bf16 v[122:125], v[158:161], v[188:191], v[122:125]
	v_mfma_f32_16x16x32_bf16 v[118:121], v[150:153], v[196:199], v[118:121]
	v_mfma_f32_16x16x32_bf16 v[110:113], v[158:161], v[196:199], v[110:113]
	v_mfma_f32_16x16x32_bf16 v[102:105], v[150:153], v[204:207], v[102:105]
	v_mfma_f32_16x16x32_bf16 v[94:97], v[158:161], v[204:207], v[94:97]
	v_mfma_f32_16x16x32_bf16 v[86:89], v[150:153], v[212:215], v[86:89]
	v_mfma_f32_16x16x32_bf16 v[78:81], v[158:161], v[212:215], v[78:81]
	s_setprio 0
	s_setprio 1
	v_mfma_f32_16x16x32_bf16 v[114:117], v[168:171], v[184:187], v[114:117]
	v_mfma_f32_16x16x32_bf16 v[106:109], v[176:179], v[184:187], v[106:109]
	v_mfma_f32_16x16x32_bf16 v[98:101], v[168:171], v[192:195], v[98:101]
	v_mfma_f32_16x16x32_bf16 v[90:93], v[176:179], v[192:195], v[90:93]
	v_mfma_f32_16x16x32_bf16 v[82:85], v[168:171], v[200:203], v[82:85]
	v_mfma_f32_16x16x32_bf16 v[74:77], v[176:179], v[200:203], v[74:77]
	v_mfma_f32_16x16x32_bf16 v[70:73], v[168:171], v[208:211], v[70:73]
	v_mfma_f32_16x16x32_bf16 v[66:69], v[176:179], v[208:211], v[66:69]
	v_mfma_f32_16x16x32_bf16 v[114:117], v[172:175], v[188:191], v[114:117]
	v_mfma_f32_16x16x32_bf16 v[106:109], v[180:183], v[188:191], v[106:109]
	v_mfma_f32_16x16x32_bf16 v[98:101], v[172:175], v[196:199], v[98:101]
	v_mfma_f32_16x16x32_bf16 v[90:93], v[180:183], v[196:199], v[90:93]
	v_mfma_f32_16x16x32_bf16 v[82:85], v[172:175], v[204:207], v[82:85]
	v_mfma_f32_16x16x32_bf16 v[74:77], v[180:183], v[204:207], v[74:77]
	v_mfma_f32_16x16x32_bf16 v[70:73], v[172:175], v[212:215], v[70:73]
	v_mfma_f32_16x16x32_bf16 v[66:69], v[180:183], v[212:215], v[66:69]
	s_barrier
	s_setprio 0
	s_add_i32 s42, s67, s33
	v_lshl_add_u64 v[216:217], v[216:217], 0, s[12:13]
	s_mov_b32 m0, s42
	s_nop 0
	global_load_lds_dwordx4 v[216:217], off
	s_add_i32 m0, s42, 0x2000
	s_add_u32 s40, s40, 0x80080
	v_lshl_add_u64 v[216:217], v[218:219], 0, s[12:13]
	s_addc_u32 s41, s41, 0
	s_add_i32 s42, s68, s33
	global_load_lds_dwordx4 v[216:217], off
	v_lshl_add_u64 v[216:217], s[40:41], 0, v[134:135]
	s_mov_b32 m0, s42
	s_nop 0
	global_load_lds_dwordx4 v[216:217], off
	v_lshl_add_u64 v[216:217], s[40:41], 0, v[130:131]
	s_add_i32 m0, s42, 0x2000
	s_nop 0
	global_load_lds_dwordx4 v[216:217], off
	v_lshl_add_u64 v[216:217], v[220:221], 0, s[12:13]
	s_mov_b32 m0, s53
	s_nop 0
	global_load_lds_dwordx4 v[216:217], off
	v_lshl_add_u64 v[216:217], v[222:223], 0, s[12:13]
	s_mov_b32 m0, s54
	s_nop 0
	global_load_lds_dwordx4 v[216:217], off
	ds_read_b128 v[184:187], v166 offset:49152
	ds_read_b128 v[188:191], v166 offset:50176
	ds_read_b128 v[192:195], v166 offset:51200
	ds_read_b128 v[196:199], v166 offset:52224
	ds_read_b128 v[200:203], v166 offset:53248
	ds_read_b128 v[204:207], v166 offset:54272
	ds_read_b128 v[208:211], v166 offset:55296
	ds_read_b128 v[212:215], v166 offset:56320
	s_waitcnt vmcnt(8)
	s_waitcnt lgkmcnt(0)
	s_barrier
	s_setprio 1
	v_mfma_f32_16x16x32_bf16 v[62:65], v[146:149], v[184:187], v[62:65]
	v_mfma_f32_16x16x32_bf16 v[58:61], v[154:157], v[184:187], v[58:61]
	v_mfma_f32_16x16x32_bf16 v[54:57], v[146:149], v[192:195], v[54:57]
	v_mfma_f32_16x16x32_bf16 v[46:49], v[154:157], v[192:195], v[46:49]
	v_mfma_f32_16x16x32_bf16 v[38:41], v[146:149], v[200:203], v[38:41]
	v_mfma_f32_16x16x32_bf16 v[30:33], v[154:157], v[200:203], v[30:33]
	v_mfma_f32_16x16x32_bf16 v[22:25], v[146:149], v[208:211], v[22:25]
	v_mfma_f32_16x16x32_bf16 v[14:17], v[154:157], v[208:211], v[14:17]
	v_mfma_f32_16x16x32_bf16 v[62:65], v[150:153], v[188:191], v[62:65]
	v_mfma_f32_16x16x32_bf16 v[58:61], v[158:161], v[188:191], v[58:61]
	v_mfma_f32_16x16x32_bf16 v[54:57], v[150:153], v[196:199], v[54:57]
	v_mfma_f32_16x16x32_bf16 v[46:49], v[158:161], v[196:199], v[46:49]
	v_mfma_f32_16x16x32_bf16 v[38:41], v[150:153], v[204:207], v[38:41]
	v_mfma_f32_16x16x32_bf16 v[30:33], v[158:161], v[204:207], v[30:33]
	v_mfma_f32_16x16x32_bf16 v[22:25], v[150:153], v[212:215], v[22:25]
	v_mfma_f32_16x16x32_bf16 v[14:17], v[158:161], v[212:215], v[14:17]
	s_setprio 0
	s_setprio 1
	v_mfma_f32_16x16x32_bf16 v[50:53], v[168:171], v[184:187], v[50:53]
	v_mfma_f32_16x16x32_bf16 v[42:45], v[176:179], v[184:187], v[42:45]
	v_mfma_f32_16x16x32_bf16 v[34:37], v[168:171], v[192:195], v[34:37]
	v_mfma_f32_16x16x32_bf16 v[26:29], v[176:179], v[192:195], v[26:29]
	v_mfma_f32_16x16x32_bf16 v[18:21], v[168:171], v[200:203], v[18:21]
	v_mfma_f32_16x16x32_bf16 v[10:13], v[176:179], v[200:203], v[10:13]
	v_mfma_f32_16x16x32_bf16 v[6:9], v[168:171], v[208:211], v[6:9]
	v_mfma_f32_16x16x32_bf16 v[2:5], v[176:179], v[208:211], v[2:5]
	v_mfma_f32_16x16x32_bf16 v[50:53], v[172:175], v[188:191], v[50:53]
	v_mfma_f32_16x16x32_bf16 v[42:45], v[180:183], v[188:191], v[42:45]
	v_mfma_f32_16x16x32_bf16 v[34:37], v[172:175], v[196:199], v[34:37]
	v_mfma_f32_16x16x32_bf16 v[26:29], v[180:183], v[196:199], v[26:29]
	v_mfma_f32_16x16x32_bf16 v[18:21], v[172:175], v[204:207], v[18:21]
	v_mfma_f32_16x16x32_bf16 v[10:13], v[180:183], v[204:207], v[10:13]
	v_mfma_f32_16x16x32_bf16 v[6:9], v[172:175], v[212:215], v[6:9]
	v_mfma_f32_16x16x32_bf16 v[2:5], v[180:183], v[212:215], v[2:5]
	s_barrier
	s_setprio 0
	s_add_i32 s66, s66, 2
	s_add_u32 s8, s8, 0x100
	s_addc_u32 s9, s9, 0
	s_add_u32 s64, s64, 0x100
	s_addc_u32 s65, s65, 0
	s_cmp_gt_u32 s66, 29
	s_cbranch_scc0 .LBB0_3201
	s_and_b64 vcc, exec, s[14:15]
	s_cbranch_vccz .LBB0_3204
	s_barrier

.LBB0_3378:
	ds_read_b128 v[142:145], v148
	ds_read_b128 v[152:155], v148 offset:1024
	ds_read_b128 v[156:159], v148 offset:2048
	ds_read_b128 v[160:163], v148 offset:3072
	ds_read_b128 v[164:167], v149
	ds_read_b128 v[168:171], v149 offset:1024
	ds_read_b128 v[172:175], v149 offset:2048
	ds_read_b128 v[176:179], v149 offset:3072
	s_add_u32 s20, s18, 0x100
	s_addc_u32 s21, s19, 0
	s_cmpk_eq_i32 s49, 0x54
	s_cselect_b32 s25, s7, s21
	s_cselect_b32 s24, s6, s20
	s_cselect_b32 s23, s17, s48
	s_cselect_b32 s22, s16, s47
	v_lshl_add_u64 v[212:213], s[18:19], 0, v[134:135]
	s_add_i32 m0, s28, 0xc000
	ds_read_b128 v[180:183], v150
	ds_read_b128 v[184:187], v150 offset:1024
	ds_read_b128 v[188:191], v150 offset:2048
	ds_read_b128 v[192:195], v150 offset:3072
	ds_read_b128 v[196:199], v150 offset:4096
	ds_read_b128 v[200:203], v150 offset:5120
	ds_read_b128 v[204:207], v150 offset:6144
	ds_read_b128 v[208:211], v150 offset:7168
	global_load_lds_dwordx4 v[212:213], off
	v_lshl_add_u64 v[212:213], s[18:19], 0, v[136:137]
	s_add_i32 m0, s28, 0xe000
	s_nop 0
	global_load_lds_dwordx4 v[212:213], off
	s_waitcnt vmcnt(8)
	s_waitcnt lgkmcnt(0)
	s_barrier
	s_setprio 1
	v_mfma_f32_16x16x32_bf16 v[126:129], v[142:145], v[180:183], v[126:129]
	v_mfma_f32_16x16x32_bf16 v[122:125], v[156:159], v[180:183], v[122:125]
	v_mfma_f32_16x16x32_bf16 v[110:113], v[142:145], v[188:191], v[110:113]
	v_mfma_f32_16x16x32_bf16 v[106:109], v[156:159], v[188:191], v[106:109]
	v_mfma_f32_16x16x32_bf16 v[94:97], v[142:145], v[196:199], v[94:97]
	v_mfma_f32_16x16x32_bf16 v[90:93], v[156:159], v[196:199], v[90:93]
	v_mfma_f32_16x16x32_bf16 v[78:81], v[142:145], v[204:207], v[78:81]
	v_mfma_f32_16x16x32_bf16 v[74:77], v[156:159], v[204:207], v[74:77]
	v_mfma_f32_16x16x32_bf16 v[126:129], v[152:155], v[184:187], v[126:129]
	v_mfma_f32_16x16x32_bf16 v[122:125], v[160:163], v[184:187], v[122:125]
	v_mfma_f32_16x16x32_bf16 v[110:113], v[152:155], v[192:195], v[110:113]
	v_mfma_f32_16x16x32_bf16 v[106:109], v[160:163], v[192:195], v[106:109]
	v_mfma_f32_16x16x32_bf16 v[94:97], v[152:155], v[200:203], v[94:97]
	v_mfma_f32_16x16x32_bf16 v[90:93], v[160:163], v[200:203], v[90:93]
	v_mfma_f32_16x16x32_bf16 v[78:81], v[152:155], v[208:211], v[78:81]
	v_mfma_f32_16x16x32_bf16 v[74:77], v[160:163], v[208:211], v[74:77]
	s_setprio 0
	s_setprio 1
	v_mfma_f32_16x16x32_bf16 v[118:121], v[164:167], v[180:183], v[118:121]
	v_mfma_f32_16x16x32_bf16 v[114:117], v[172:175], v[180:183], v[114:117]
	v_mfma_f32_16x16x32_bf16 v[102:105], v[164:167], v[188:191], v[102:105]
	v_mfma_f32_16x16x32_bf16 v[98:101], v[172:175], v[188:191], v[98:101]
	v_mfma_f32_16x16x32_bf16 v[86:89], v[164:167], v[196:199], v[86:89]
	v_mfma_f32_16x16x32_bf16 v[82:85], v[172:175], v[196:199], v[82:85]
	v_mfma_f32_16x16x32_bf16 v[70:73], v[164:167], v[204:207], v[70:73]
	v_mfma_f32_16x16x32_bf16 v[66:69], v[172:175], v[204:207], v[66:69]
	v_mfma_f32_16x16x32_bf16 v[118:121], v[168:171], v[184:187], v[118:121]
	v_mfma_f32_16x16x32_bf16 v[114:117], v[176:179], v[184:187], v[114:117]
	v_mfma_f32_16x16x32_bf16 v[102:105], v[168:171], v[192:195], v[102:105]
	v_mfma_f32_16x16x32_bf16 v[98:101], v[176:179], v[192:195], v[98:101]
	v_mfma_f32_16x16x32_bf16 v[86:89], v[168:171], v[200:203], v[86:89]
	v_mfma_f32_16x16x32_bf16 v[82:85], v[176:179], v[200:203], v[82:85]
	v_mfma_f32_16x16x32_bf16 v[70:73], v[168:171], v[208:211], v[70:73]
	v_mfma_f32_16x16x32_bf16 v[66:69], v[176:179], v[208:211], v[66:69]
	s_barrier
	s_setprio 0
	s_add_i32 s18, s41, s27
	v_lshl_add_u64 v[212:213], s[22:23], 0, v[130:131]
	s_mov_b32 m0, s18
	ds_read_b128 v[180:183], v150 offset:16384
	ds_read_b128 v[184:187], v150 offset:17408
	ds_read_b128 v[188:191], v150 offset:18432
	ds_read_b128 v[192:195], v150 offset:19456
	ds_read_b128 v[196:199], v150 offset:20480
	ds_read_b128 v[200:203], v150 offset:21504
	ds_read_b128 v[204:207], v150 offset:22528
	ds_read_b128 v[208:211], v150 offset:23552
	global_load_lds_dwordx4 v[212:213], off
	s_add_i32 m0, s18, 0x2000
	s_add_u32 s18, s22, 0x160000
	v_lshl_add_u64 v[214:215], s[22:23], 0, v[132:133]
	s_addc_u32 s19, s23, 0
	s_add_i32 s50, s42, s27
	global_load_lds_dwordx4 v[214:215], off
	v_lshl_add_u64 v[216:217], s[18:19], 0, v[130:131]
	s_mov_b32 m0, s50
	v_lshl_add_u64 v[218:219], s[24:25], 0, v[132:133]
	global_load_lds_dwordx4 v[216:217], off
	v_lshl_add_u64 v[216:217], s[18:19], 0, v[132:133]
	s_add_i32 m0, s50, 0x2000
	s_nop 0
	global_load_lds_dwordx4 v[216:217], off
	v_lshl_add_u64 v[216:217], s[24:25], 0, v[130:131]
	s_mov_b32 m0, s28
	s_nop 0
	global_load_lds_dwordx4 v[216:217], off
	s_mov_b32 m0, s29
	s_nop 0
	global_load_lds_dwordx4 v[218:219], off
	s_waitcnt vmcnt(8)
	s_waitcnt lgkmcnt(0)
	s_barrier
	s_setprio 1
	v_mfma_f32_16x16x32_bf16 v[62:65], v[142:145], v[180:183], v[62:65]
	v_mfma_f32_16x16x32_bf16 v[58:61], v[156:159], v[180:183], v[58:61]
	v_mfma_f32_16x16x32_bf16 v[46:49], v[142:145], v[188:191], v[46:49]
	v_mfma_f32_16x16x32_bf16 v[42:45], v[156:159], v[188:191], v[42:45]
	v_mfma_f32_16x16x32_bf16 v[30:33], v[142:145], v[196:199], v[30:33]
	v_mfma_f32_16x16x32_bf16 v[26:29], v[156:159], v[196:199], v[26:29]
	v_mfma_f32_16x16x32_bf16 v[14:17], v[142:145], v[204:207], v[14:17]
	v_mfma_f32_16x16x32_bf16 v[10:13], v[156:159], v[204:207], v[10:13]
	v_mfma_f32_16x16x32_bf16 v[62:65], v[152:155], v[184:187], v[62:65]
	v_mfma_f32_16x16x32_bf16 v[58:61], v[160:163], v[184:187], v[58:61]
	v_mfma_f32_16x16x32_bf16 v[46:49], v[152:155], v[192:195], v[46:49]
	v_mfma_f32_16x16x32_bf16 v[42:45], v[160:163], v[192:195], v[42:45]
	v_mfma_f32_16x16x32_bf16 v[30:33], v[152:155], v[200:203], v[30:33]
	v_mfma_f32_16x16x32_bf16 v[26:29], v[160:163], v[200:203], v[26:29]
	v_mfma_f32_16x16x32_bf16 v[14:17], v[152:155], v[208:211], v[14:17]
	v_mfma_f32_16x16x32_bf16 v[10:13], v[160:163], v[208:211], v[10:13]
	s_setprio 0
	s_setprio 1
	v_mfma_f32_16x16x32_bf16 v[54:57], v[164:167], v[180:183], v[54:57]
	v_mfma_f32_16x16x32_bf16 v[50:53], v[172:175], v[180:183], v[50:53]
	v_mfma_f32_16x16x32_bf16 v[38:41], v[164:167], v[188:191], v[38:41]
	v_mfma_f32_16x16x32_bf16 v[34:37], v[172:175], v[188:191], v[34:37]
	v_mfma_f32_16x16x32_bf16 v[22:25], v[164:167], v[196:199], v[22:25]
	v_mfma_f32_16x16x32_bf16 v[18:21], v[172:175], v[196:199], v[18:21]
	v_mfma_f32_16x16x32_bf16 v[6:9], v[164:167], v[204:207], v[6:9]
	v_mfma_f32_16x16x32_bf16 v[2:5], v[172:175], v[204:207], v[2:5]
	v_mfma_f32_16x16x32_bf16 v[54:57], v[168:171], v[184:187], v[54:57]
	v_mfma_f32_16x16x32_bf16 v[50:53], v[176:179], v[184:187], v[50:53]
	v_mfma_f32_16x16x32_bf16 v[38:41], v[168:171], v[192:195], v[38:41]
	v_mfma_f32_16x16x32_bf16 v[34:37], v[176:179], v[192:195], v[34:37]
	v_mfma_f32_16x16x32_bf16 v[22:25], v[168:171], v[200:203], v[22:25]
	v_mfma_f32_16x16x32_bf16 v[18:21], v[176:179], v[200:203], v[18:21]
	v_mfma_f32_16x16x32_bf16 v[6:9], v[168:171], v[208:211], v[6:9]
	v_mfma_f32_16x16x32_bf16 v[2:5], v[176:179], v[208:211], v[2:5]
	s_barrier
	s_setprio 0
	s_add_i32 s50, 0, 0x18000
	s_add_i32 s51, 0, 0x1c000
	v_add_u32_e32 v160, s50, v147
	v_add_u32_e32 v176, s51, v147
	ds_read_b128 v[142:145], v160
	ds_read_b128 v[152:155], v160 offset:1024
	ds_read_b128 v[156:159], v160 offset:2048
	ds_read_b128 v[160:163], v160 offset:3072
	ds_read_b128 v[164:167], v176
	ds_read_b128 v[168:171], v176 offset:1024
	ds_read_b128 v[172:175], v176 offset:2048
	ds_read_b128 v[176:179], v176 offset:3072
	s_add_u32 s18, s24, 0x160000
	s_addc_u32 s19, s25, 0
	s_mov_b32 m0, s30
	v_lshl_add_u64 v[220:221], s[18:19], 0, v[130:131]
	ds_read_b128 v[180:183], v150 offset:32768
	ds_read_b128 v[184:187], v150 offset:33792
	ds_read_b128 v[188:191], v150 offset:34816
	ds_read_b128 v[192:195], v150 offset:35840
	ds_read_b128 v[196:199], v150 offset:36864
	ds_read_b128 v[200:203], v150 offset:37888
	ds_read_b128 v[204:207], v150 offset:38912
	ds_read_b128 v[208:211], v150 offset:39936
	global_load_lds_dwordx4 v[220:221], off
	v_lshl_add_u64 v[220:221], s[18:19], 0, v[132:133]
	s_mov_b32 m0, s31
	s_nop 0
	global_load_lds_dwordx4 v[220:221], off
	s_waitcnt vmcnt(8)
	s_waitcnt lgkmcnt(0)
	s_barrier
	s_setprio 1
	v_mfma_f32_16x16x32_bf16 v[126:129], v[142:145], v[180:183], v[126:129]
	v_mfma_f32_16x16x32_bf16 v[122:125], v[156:159], v[180:183], v[122:125]
	v_mfma_f32_16x16x32_bf16 v[110:113], v[142:145], v[188:191], v[110:113]
	v_mfma_f32_16x16x32_bf16 v[106:109], v[156:159], v[188:191], v[106:109]
	v_mfma_f32_16x16x32_bf16 v[94:97], v[142:145], v[196:199], v[94:97]
	v_mfma_f32_16x16x32_bf16 v[90:93], v[156:159], v[196:199], v[90:93]
	v_mfma_f32_16x16x32_bf16 v[78:81], v[142:145], v[204:207], v[78:81]
	v_mfma_f32_16x16x32_bf16 v[74:77], v[156:159], v[204:207], v[74:77]
	v_mfma_f32_16x16x32_bf16 v[126:129], v[152:155], v[184:187], v[126:129]
	v_mfma_f32_16x16x32_bf16 v[122:125], v[160:163], v[184:187], v[122:125]
	v_mfma_f32_16x16x32_bf16 v[110:113], v[152:155], v[192:195], v[110:113]
	v_mfma_f32_16x16x32_bf16 v[106:109], v[160:163], v[192:195], v[106:109]
	v_mfma_f32_16x16x32_bf16 v[94:97], v[152:155], v[200:203], v[94:97]
	v_mfma_f32_16x16x32_bf16 v[90:93], v[160:163], v[200:203], v[90:93]
	v_mfma_f32_16x16x32_bf16 v[78:81], v[152:155], v[208:211], v[78:81]
	v_mfma_f32_16x16x32_bf16 v[74:77], v[160:163], v[208:211], v[74:77]
	s_setprio 0
	s_setprio 1
	v_mfma_f32_16x16x32_bf16 v[118:121], v[164:167], v[180:183], v[118:121]
	v_mfma_f32_16x16x32_bf16 v[114:117], v[172:175], v[180:183], v[114:117]
	v_mfma_f32_16x16x32_bf16 v[102:105], v[164:167], v[188:191], v[102:105]
	v_mfma_f32_16x16x32_bf16 v[98:101], v[172:175], v[188:191], v[98:101]
	v_mfma_f32_16x16x32_bf16 v[86:89], v[164:167], v[196:199], v[86:89]
	v_mfma_f32_16x16x32_bf16 v[82:85], v[172:175], v[196:199], v[82:85]
	v_mfma_f32_16x16x32_bf16 v[70:73], v[164:167], v[204:207], v[70:73]
	v_mfma_f32_16x16x32_bf16 v[66:69], v[172:175], v[204:207], v[66:69]
	v_mfma_f32_16x16x32_bf16 v[118:121], v[168:171], v[184:187], v[118:121]
	v_mfma_f32_16x16x32_bf16 v[114:117], v[176:179], v[184:187], v[114:117]
	v_mfma_f32_16x16x32_bf16 v[102:105], v[168:171], v[192:195], v[102:105]
	v_mfma_f32_16x16x32_bf16 v[98:101], v[176:179], v[192:195], v[98:101]
	v_mfma_f32_16x16x32_bf16 v[86:89], v[168:171], v[200:203], v[86:89]
	v_mfma_f32_16x16x32_bf16 v[82:85], v[176:179], v[200:203], v[82:85]
	v_mfma_f32_16x16x32_bf16 v[70:73], v[168:171], v[208:211], v[70:73]
	v_mfma_f32_16x16x32_bf16 v[66:69], v[176:179], v[208:211], v[66:69]
	s_barrier
	s_setprio 0
	s_add_i32 s18, s50, s27
	v_lshl_add_u64 v[212:213], v[212:213], 0, s[12:13]
	s_mov_b32 m0, s18
	ds_read_b128 v[180:183], v150 offset:49152
	ds_read_b128 v[184:187], v150 offset:50176
	ds_read_b128 v[188:191], v150 offset:51200
	ds_read_b128 v[192:195], v150 offset:52224
	ds_read_b128 v[196:199], v150 offset:53248
	ds_read_b128 v[200:203], v150 offset:54272
	ds_read_b128 v[204:207], v150 offset:55296
	ds_read_b128 v[208:211], v150 offset:56320
	global_load_lds_dwordx4 v[212:213], off
	s_add_i32 m0, s18, 0x2000
	s_add_u32 s18, s22, 0x160080
	v_lshl_add_u64 v[212:213], v[214:215], 0, s[12:13]
	s_addc_u32 s19, s23, 0
	s_add_i32 s22, s51, s27
	global_load_lds_dwordx4 v[212:213], off
	v_lshl_add_u64 v[212:213], s[18:19], 0, v[130:131]
	s_mov_b32 m0, s22
	s_nop 0
	global_load_lds_dwordx4 v[212:213], off
	v_lshl_add_u64 v[212:213], s[18:19], 0, v[132:133]
	s_add_i32 m0, s22, 0x2000
	s_nop 0
	global_load_lds_dwordx4 v[212:213], off
	v_lshl_add_u64 v[212:213], v[216:217], 0, s[12:13]
	s_mov_b32 m0, s37
	s_nop 0
	global_load_lds_dwordx4 v[212:213], off
	v_lshl_add_u64 v[212:213], v[218:219], 0, s[12:13]
	s_mov_b32 m0, s38
	s_nop 0
	global_load_lds_dwordx4 v[212:213], off
	s_waitcnt vmcnt(8)
	s_waitcnt lgkmcnt(0)
	s_barrier
	s_setprio 1
	v_mfma_f32_16x16x32_bf16 v[62:65], v[142:145], v[180:183], v[62:65]
	v_mfma_f32_16x16x32_bf16 v[58:61], v[156:159], v[180:183], v[58:61]
	v_mfma_f32_16x16x32_bf16 v[46:49], v[142:145], v[188:191], v[46:49]
	v_mfma_f32_16x16x32_bf16 v[42:45], v[156:159], v[188:191], v[42:45]
	v_mfma_f32_16x16x32_bf16 v[30:33], v[142:145], v[196:199], v[30:33]
	v_mfma_f32_16x16x32_bf16 v[26:29], v[156:159], v[196:199], v[26:29]
	v_mfma_f32_16x16x32_bf16 v[14:17], v[142:145], v[204:207], v[14:17]
	v_mfma_f32_16x16x32_bf16 v[10:13], v[156:159], v[204:207], v[10:13]
	v_mfma_f32_16x16x32_bf16 v[62:65], v[152:155], v[184:187], v[62:65]
	v_mfma_f32_16x16x32_bf16 v[58:61], v[160:163], v[184:187], v[58:61]
	v_mfma_f32_16x16x32_bf16 v[46:49], v[152:155], v[192:195], v[46:49]
	v_mfma_f32_16x16x32_bf16 v[42:45], v[160:163], v[192:195], v[42:45]
	v_mfma_f32_16x16x32_bf16 v[30:33], v[152:155], v[200:203], v[30:33]
	v_mfma_f32_16x16x32_bf16 v[26:29], v[160:163], v[200:203], v[26:29]
	v_mfma_f32_16x16x32_bf16 v[14:17], v[152:155], v[208:211], v[14:17]
	v_mfma_f32_16x16x32_bf16 v[10:13], v[160:163], v[208:211], v[10:13]
	s_setprio 0
	s_setprio 1
	v_mfma_f32_16x16x32_bf16 v[54:57], v[164:167], v[180:183], v[54:57]
	v_mfma_f32_16x16x32_bf16 v[50:53], v[172:175], v[180:183], v[50:53]
	v_mfma_f32_16x16x32_bf16 v[38:41], v[164:167], v[188:191], v[38:41]
	v_mfma_f32_16x16x32_bf16 v[34:37], v[172:175], v[188:191], v[34:37]
	v_mfma_f32_16x16x32_bf16 v[22:25], v[164:167], v[196:199], v[22:25]
	v_mfma_f32_16x16x32_bf16 v[18:21], v[172:175], v[196:199], v[18:21]
	v_mfma_f32_16x16x32_bf16 v[6:9], v[164:167], v[204:207], v[6:9]
	v_mfma_f32_16x16x32_bf16 v[2:5], v[172:175], v[204:207], v[2:5]
	v_mfma_f32_16x16x32_bf16 v[54:57], v[168:171], v[184:187], v[54:57]
	v_mfma_f32_16x16x32_bf16 v[50:53], v[176:179], v[184:187], v[50:53]
	v_mfma_f32_16x16x32_bf16 v[38:41], v[168:171], v[192:195], v[38:41]
	v_mfma_f32_16x16x32_bf16 v[34:37], v[176:179], v[192:195], v[34:37]
	v_mfma_f32_16x16x32_bf16 v[22:25], v[168:171], v[200:203], v[22:25]
	v_mfma_f32_16x16x32_bf16 v[18:21], v[176:179], v[200:203], v[18:21]
	v_mfma_f32_16x16x32_bf16 v[6:9], v[168:171], v[208:211], v[6:9]
	v_mfma_f32_16x16x32_bf16 v[2:5], v[176:179], v[208:211], v[2:5]
	s_barrier
	s_setprio 0
	s_add_i32 s49, s49, 2
	s_add_u32 s47, s47, 0x100
	s_addc_u32 s48, s48, 0
	s_cmpk_gt_u32 s49, 0x55
	s_mov_b64 s[18:19], s[20:21]
	s_cbranch_scc0 .LBB0_3378
	s_and_b64 vcc, exec, s[14:15]
	s_cbranch_vccz .LBB0_3381
	s_barrier

.LBB0_3426:
	ds_read_b128 v[140:143], v181
	ds_read_b128 v[144:147], v181 offset:1024
	ds_read_b128 v[148:151], v181 offset:2048
	ds_read_b128 v[152:155], v181 offset:3072
	ds_read_b128 v[156:159], v182
	ds_read_b128 v[160:163], v182 offset:1024
	ds_read_b128 v[164:167], v182 offset:2048
	ds_read_b128 v[168:171], v182 offset:3072
	s_add_u32 s6, s40, 0x100
	s_addc_u32 s7, s41, 0
	s_cmpk_eq_i32 s68, 0x54
	s_cselect_b32 s45, s37, s7
	s_cselect_b32 s44, s36, s6
	s_cselect_b32 s43, s39, s67
	s_cselect_b32 s42, s38, s66
	v_lshl_add_u64 v[176:177], s[40:41], 0, v[132:133]
	s_add_i32 m0, s23, 0xc000
	ds_read_b128 v[172:175], v183
	ds_read_b128 v[186:189], v183 offset:1024
	ds_read_b128 v[190:193], v183 offset:2048
	ds_read_b128 v[194:197], v183 offset:3072
	ds_read_b128 v[198:201], v183 offset:4096
	ds_read_b128 v[202:205], v183 offset:5120
	ds_read_b128 v[206:209], v183 offset:6144
	ds_read_b128 v[210:213], v183 offset:7168
	global_load_lds_dwordx4 v[176:177], off
	v_lshl_add_u64 v[176:177], s[40:41], 0, v[134:135]
	s_add_i32 m0, s23, 0xe000
	s_nop 0
	global_load_lds_dwordx4 v[176:177], off
	s_waitcnt vmcnt(8)
	s_waitcnt lgkmcnt(0)
	s_barrier
	s_setprio 1
	v_mfma_f32_16x16x32_bf16 v[124:127], v[140:143], v[172:175], v[124:127]
	v_mfma_f32_16x16x32_bf16 v[120:123], v[148:151], v[172:175], v[120:123]
	v_mfma_f32_16x16x32_bf16 v[108:111], v[140:143], v[190:193], v[108:111]
	v_mfma_f32_16x16x32_bf16 v[104:107], v[148:151], v[190:193], v[104:107]
	v_mfma_f32_16x16x32_bf16 v[92:95], v[140:143], v[198:201], v[92:95]
	v_mfma_f32_16x16x32_bf16 v[88:91], v[148:151], v[198:201], v[88:91]
	v_mfma_f32_16x16x32_bf16 v[76:79], v[140:143], v[206:209], v[76:79]
	v_mfma_f32_16x16x32_bf16 v[72:75], v[148:151], v[206:209], v[72:75]
	v_mfma_f32_16x16x32_bf16 v[124:127], v[144:147], v[186:189], v[124:127]
	v_mfma_f32_16x16x32_bf16 v[120:123], v[152:155], v[186:189], v[120:123]
	v_mfma_f32_16x16x32_bf16 v[108:111], v[144:147], v[194:197], v[108:111]
	v_mfma_f32_16x16x32_bf16 v[104:107], v[152:155], v[194:197], v[104:107]
	v_mfma_f32_16x16x32_bf16 v[92:95], v[144:147], v[202:205], v[92:95]
	v_mfma_f32_16x16x32_bf16 v[88:91], v[152:155], v[202:205], v[88:91]
	v_mfma_f32_16x16x32_bf16 v[76:79], v[144:147], v[210:213], v[76:79]
	v_mfma_f32_16x16x32_bf16 v[72:75], v[152:155], v[210:213], v[72:75]
	s_setprio 0
	s_setprio 1
	v_mfma_f32_16x16x32_bf16 v[116:119], v[156:159], v[172:175], v[116:119]
	v_mfma_f32_16x16x32_bf16 v[112:115], v[164:167], v[172:175], v[112:115]
	v_mfma_f32_16x16x32_bf16 v[100:103], v[156:159], v[190:193], v[100:103]
	v_mfma_f32_16x16x32_bf16 v[96:99], v[164:167], v[190:193], v[96:99]
	v_mfma_f32_16x16x32_bf16 v[84:87], v[156:159], v[198:201], v[84:87]
	v_mfma_f32_16x16x32_bf16 v[80:83], v[164:167], v[198:201], v[80:83]
	v_mfma_f32_16x16x32_bf16 v[68:71], v[156:159], v[206:209], v[68:71]
	v_mfma_f32_16x16x32_bf16 v[64:67], v[164:167], v[206:209], v[64:67]
	v_mfma_f32_16x16x32_bf16 v[116:119], v[160:163], v[186:189], v[116:119]
	v_mfma_f32_16x16x32_bf16 v[112:115], v[168:171], v[186:189], v[112:115]
	v_mfma_f32_16x16x32_bf16 v[100:103], v[160:163], v[194:197], v[100:103]
	v_mfma_f32_16x16x32_bf16 v[96:99], v[168:171], v[194:197], v[96:99]
	v_mfma_f32_16x16x32_bf16 v[84:87], v[160:163], v[202:205], v[84:87]
	v_mfma_f32_16x16x32_bf16 v[80:83], v[168:171], v[202:205], v[80:83]
	v_mfma_f32_16x16x32_bf16 v[68:71], v[160:163], v[210:213], v[68:71]
	v_mfma_f32_16x16x32_bf16 v[64:67], v[168:171], v[210:213], v[64:67]
	s_barrier
	s_setprio 0
	s_add_i32 s40, s59, s21
	v_lshl_add_u64 v[176:177], s[42:43], 0, v[128:129]
	s_mov_b32 m0, s40
	ds_read_b128 v[172:175], v183 offset:16384
	ds_read_b128 v[186:189], v183 offset:17408
	ds_read_b128 v[190:193], v183 offset:18432
	ds_read_b128 v[194:197], v183 offset:19456
	ds_read_b128 v[198:201], v183 offset:20480
	ds_read_b128 v[202:205], v183 offset:21504
	ds_read_b128 v[206:209], v183 offset:22528
	ds_read_b128 v[210:213], v183 offset:23552
	global_load_lds_dwordx4 v[176:177], off
	s_add_i32 m0, s40, 0x2000
	s_add_u32 s40, s42, 0x160000
	v_lshl_add_u64 v[214:215], s[42:43], 0, v[130:131]
	s_addc_u32 s41, s43, 0
	s_add_i32 s69, s60, s21
	global_load_lds_dwordx4 v[214:215], off
	v_lshl_add_u64 v[216:217], s[40:41], 0, v[128:129]
	s_mov_b32 m0, s69
	v_lshl_add_u64 v[218:219], s[44:45], 0, v[130:131]
	global_load_lds_dwordx4 v[216:217], off
	v_lshl_add_u64 v[216:217], s[40:41], 0, v[130:131]
	s_add_i32 m0, s69, 0x2000
	s_nop 0
	global_load_lds_dwordx4 v[216:217], off
	v_lshl_add_u64 v[216:217], s[44:45], 0, v[128:129]
	s_mov_b32 m0, s23
	s_nop 0
	global_load_lds_dwordx4 v[216:217], off
	s_mov_b32 m0, s47
	s_nop 0
	global_load_lds_dwordx4 v[218:219], off
	s_waitcnt vmcnt(8)
	s_waitcnt lgkmcnt(0)
	s_barrier
	s_setprio 1
	v_mfma_f32_16x16x32_bf16 v[60:63], v[140:143], v[172:175], v[60:63]
	v_mfma_f32_16x16x32_bf16 v[56:59], v[148:151], v[172:175], v[56:59]
	v_mfma_f32_16x16x32_bf16 v[44:47], v[140:143], v[190:193], v[44:47]
	v_mfma_f32_16x16x32_bf16 v[40:43], v[148:151], v[190:193], v[40:43]
	v_mfma_f32_16x16x32_bf16 v[28:31], v[140:143], v[198:201], v[28:31]
	v_mfma_f32_16x16x32_bf16 v[24:27], v[148:151], v[198:201], v[24:27]
	v_mfma_f32_16x16x32_bf16 v[12:15], v[140:143], v[206:209], v[12:15]
	v_mfma_f32_16x16x32_bf16 v[8:11], v[148:151], v[206:209], v[8:11]
	v_mfma_f32_16x16x32_bf16 v[60:63], v[144:147], v[186:189], v[60:63]
	v_mfma_f32_16x16x32_bf16 v[56:59], v[152:155], v[186:189], v[56:59]
	v_mfma_f32_16x16x32_bf16 v[44:47], v[144:147], v[194:197], v[44:47]
	v_mfma_f32_16x16x32_bf16 v[40:43], v[152:155], v[194:197], v[40:43]
	v_mfma_f32_16x16x32_bf16 v[28:31], v[144:147], v[202:205], v[28:31]
	v_mfma_f32_16x16x32_bf16 v[24:27], v[152:155], v[202:205], v[24:27]
	v_mfma_f32_16x16x32_bf16 v[12:15], v[144:147], v[210:213], v[12:15]
	v_mfma_f32_16x16x32_bf16 v[8:11], v[152:155], v[210:213], v[8:11]
	s_setprio 0
	s_setprio 1
	v_mfma_f32_16x16x32_bf16 v[52:55], v[156:159], v[172:175], v[52:55]
	v_mfma_f32_16x16x32_bf16 v[48:51], v[164:167], v[172:175], v[48:51]
	v_mfma_f32_16x16x32_bf16 v[36:39], v[156:159], v[190:193], v[36:39]
	v_mfma_f32_16x16x32_bf16 v[32:35], v[164:167], v[190:193], v[32:35]
	v_mfma_f32_16x16x32_bf16 v[20:23], v[156:159], v[198:201], v[20:23]
	v_mfma_f32_16x16x32_bf16 v[16:19], v[164:167], v[198:201], v[16:19]
	v_mfma_f32_16x16x32_bf16 v[4:7], v[156:159], v[206:209], v[4:7]
	v_mfma_f32_16x16x32_bf16 v[0:3], v[164:167], v[206:209], v[0:3]
	v_mfma_f32_16x16x32_bf16 v[52:55], v[160:163], v[186:189], v[52:55]
	v_mfma_f32_16x16x32_bf16 v[48:51], v[168:171], v[186:189], v[48:51]
	v_mfma_f32_16x16x32_bf16 v[36:39], v[160:163], v[194:197], v[36:39]
	v_mfma_f32_16x16x32_bf16 v[32:35], v[168:171], v[194:197], v[32:35]
	v_mfma_f32_16x16x32_bf16 v[20:23], v[160:163], v[202:205], v[20:23]
	v_mfma_f32_16x16x32_bf16 v[16:19], v[168:171], v[202:205], v[16:19]
	v_mfma_f32_16x16x32_bf16 v[4:7], v[160:163], v[210:213], v[4:7]
	v_mfma_f32_16x16x32_bf16 v[0:3], v[168:171], v[210:213], v[0:3]
	s_barrier
	s_setprio 0
	s_add_i32 s69, 0, 0x18000
	s_add_i32 s70, 0, 0x1c000
	v_add_u32_e32 v152, s69, v180
	v_add_u32_e32 v168, s70, v180
	ds_read_b128 v[140:143], v152
	ds_read_b128 v[144:147], v152 offset:1024
	ds_read_b128 v[148:151], v152 offset:2048
	ds_read_b128 v[152:155], v152 offset:3072
	ds_read_b128 v[156:159], v168
	ds_read_b128 v[160:163], v168 offset:1024
	ds_read_b128 v[164:167], v168 offset:2048
	ds_read_b128 v[168:171], v168 offset:3072
	s_add_u32 s40, s44, 0x160000
	s_addc_u32 s41, s45, 0
	s_mov_b32 m0, s48
	v_lshl_add_u64 v[220:221], s[40:41], 0, v[128:129]
	ds_read_b128 v[172:175], v183 offset:32768
	ds_read_b128 v[186:189], v183 offset:33792
	ds_read_b128 v[190:193], v183 offset:34816
	ds_read_b128 v[194:197], v183 offset:35840
	ds_read_b128 v[198:201], v183 offset:36864
	ds_read_b128 v[202:205], v183 offset:37888
	ds_read_b128 v[206:209], v183 offset:38912
	ds_read_b128 v[210:213], v183 offset:39936
	global_load_lds_dwordx4 v[220:221], off
	v_lshl_add_u64 v[220:221], s[40:41], 0, v[130:131]
	s_mov_b32 m0, s49
	s_nop 0
	global_load_lds_dwordx4 v[220:221], off
	s_waitcnt vmcnt(8)
	s_waitcnt lgkmcnt(0)
	s_barrier
	s_setprio 1
	v_mfma_f32_16x16x32_bf16 v[124:127], v[140:143], v[172:175], v[124:127]
	v_mfma_f32_16x16x32_bf16 v[120:123], v[148:151], v[172:175], v[120:123]
	v_mfma_f32_16x16x32_bf16 v[108:111], v[140:143], v[190:193], v[108:111]
	v_mfma_f32_16x16x32_bf16 v[104:107], v[148:151], v[190:193], v[104:107]
	v_mfma_f32_16x16x32_bf16 v[92:95], v[140:143], v[198:201], v[92:95]
	v_mfma_f32_16x16x32_bf16 v[88:91], v[148:151], v[198:201], v[88:91]
	v_mfma_f32_16x16x32_bf16 v[76:79], v[140:143], v[206:209], v[76:79]
	v_mfma_f32_16x16x32_bf16 v[72:75], v[148:151], v[206:209], v[72:75]
	v_mfma_f32_16x16x32_bf16 v[124:127], v[144:147], v[186:189], v[124:127]
	v_mfma_f32_16x16x32_bf16 v[120:123], v[152:155], v[186:189], v[120:123]
	v_mfma_f32_16x16x32_bf16 v[108:111], v[144:147], v[194:197], v[108:111]
	v_mfma_f32_16x16x32_bf16 v[104:107], v[152:155], v[194:197], v[104:107]
	v_mfma_f32_16x16x32_bf16 v[92:95], v[144:147], v[202:205], v[92:95]
	v_mfma_f32_16x16x32_bf16 v[88:91], v[152:155], v[202:205], v[88:91]
	v_mfma_f32_16x16x32_bf16 v[76:79], v[144:147], v[210:213], v[76:79]
	v_mfma_f32_16x16x32_bf16 v[72:75], v[152:155], v[210:213], v[72:75]
	s_setprio 0
	s_setprio 1
	v_mfma_f32_16x16x32_bf16 v[116:119], v[156:159], v[172:175], v[116:119]
	v_mfma_f32_16x16x32_bf16 v[112:115], v[164:167], v[172:175], v[112:115]
	v_mfma_f32_16x16x32_bf16 v[100:103], v[156:159], v[190:193], v[100:103]
	v_mfma_f32_16x16x32_bf16 v[96:99], v[164:167], v[190:193], v[96:99]
	v_mfma_f32_16x16x32_bf16 v[84:87], v[156:159], v[198:201], v[84:87]
	v_mfma_f32_16x16x32_bf16 v[80:83], v[164:167], v[198:201], v[80:83]
	v_mfma_f32_16x16x32_bf16 v[68:71], v[156:159], v[206:209], v[68:71]
	v_mfma_f32_16x16x32_bf16 v[64:67], v[164:167], v[206:209], v[64:67]
	v_mfma_f32_16x16x32_bf16 v[116:119], v[160:163], v[186:189], v[116:119]
	v_mfma_f32_16x16x32_bf16 v[112:115], v[168:171], v[186:189], v[112:115]
	v_mfma_f32_16x16x32_bf16 v[100:103], v[160:163], v[194:197], v[100:103]
	v_mfma_f32_16x16x32_bf16 v[96:99], v[168:171], v[194:197], v[96:99]
	v_mfma_f32_16x16x32_bf16 v[84:87], v[160:163], v[202:205], v[84:87]
	v_mfma_f32_16x16x32_bf16 v[80:83], v[168:171], v[202:205], v[80:83]
	v_mfma_f32_16x16x32_bf16 v[68:71], v[160:163], v[210:213], v[68:71]
	v_mfma_f32_16x16x32_bf16 v[64:67], v[168:171], v[210:213], v[64:67]
	s_barrier
	s_setprio 0
	s_add_i32 s40, s69, s21
	v_lshl_add_u64 v[176:177], v[176:177], 0, s[14:15]
	s_mov_b32 m0, s40
	ds_read_b128 v[172:175], v183 offset:49152
	ds_read_b128 v[186:189], v183 offset:50176
	ds_read_b128 v[190:193], v183 offset:51200
	ds_read_b128 v[194:197], v183 offset:52224
	ds_read_b128 v[198:201], v183 offset:53248
	ds_read_b128 v[202:205], v183 offset:54272
	ds_read_b128 v[206:209], v183 offset:55296
	ds_read_b128 v[210:213], v183 offset:56320
	global_load_lds_dwordx4 v[176:177], off
	s_add_i32 m0, s40, 0x2000
	s_add_u32 s40, s42, 0x160080
	v_lshl_add_u64 v[176:177], v[214:215], 0, s[14:15]
	s_addc_u32 s41, s43, 0
	s_add_i32 s42, s70, s21
	global_load_lds_dwordx4 v[176:177], off
	v_lshl_add_u64 v[176:177], s[40:41], 0, v[128:129]
	s_mov_b32 m0, s42
	s_nop 0
	global_load_lds_dwordx4 v[176:177], off
	v_lshl_add_u64 v[176:177], s[40:41], 0, v[130:131]
	s_add_i32 m0, s42, 0x2000
	s_nop 0
	global_load_lds_dwordx4 v[176:177], off
	v_lshl_add_u64 v[176:177], v[216:217], 0, s[14:15]
	s_mov_b32 m0, s56
	s_nop 0
	global_load_lds_dwordx4 v[176:177], off
	v_lshl_add_u64 v[176:177], v[218:219], 0, s[14:15]
	s_mov_b32 m0, s57
	s_nop 0
	global_load_lds_dwordx4 v[176:177], off
	s_waitcnt vmcnt(8)
	s_waitcnt lgkmcnt(0)
	s_barrier
	s_setprio 1
	v_mfma_f32_16x16x32_bf16 v[60:63], v[140:143], v[172:175], v[60:63]
	v_mfma_f32_16x16x32_bf16 v[56:59], v[148:151], v[172:175], v[56:59]
	v_mfma_f32_16x16x32_bf16 v[44:47], v[140:143], v[190:193], v[44:47]
	v_mfma_f32_16x16x32_bf16 v[40:43], v[148:151], v[190:193], v[40:43]
	v_mfma_f32_16x16x32_bf16 v[28:31], v[140:143], v[198:201], v[28:31]
	v_mfma_f32_16x16x32_bf16 v[24:27], v[148:151], v[198:201], v[24:27]
	v_mfma_f32_16x16x32_bf16 v[12:15], v[140:143], v[206:209], v[12:15]
	v_mfma_f32_16x16x32_bf16 v[8:11], v[148:151], v[206:209], v[8:11]
	v_mfma_f32_16x16x32_bf16 v[60:63], v[144:147], v[186:189], v[60:63]
	v_mfma_f32_16x16x32_bf16 v[56:59], v[152:155], v[186:189], v[56:59]
	v_mfma_f32_16x16x32_bf16 v[44:47], v[144:147], v[194:197], v[44:47]
	v_mfma_f32_16x16x32_bf16 v[40:43], v[152:155], v[194:197], v[40:43]
	v_mfma_f32_16x16x32_bf16 v[28:31], v[144:147], v[202:205], v[28:31]
	v_mfma_f32_16x16x32_bf16 v[24:27], v[152:155], v[202:205], v[24:27]
	v_mfma_f32_16x16x32_bf16 v[12:15], v[144:147], v[210:213], v[12:15]
	v_mfma_f32_16x16x32_bf16 v[8:11], v[152:155], v[210:213], v[8:11]
	s_setprio 0
	s_setprio 1
	v_mfma_f32_16x16x32_bf16 v[52:55], v[156:159], v[172:175], v[52:55]
	v_mfma_f32_16x16x32_bf16 v[48:51], v[164:167], v[172:175], v[48:51]
	v_mfma_f32_16x16x32_bf16 v[36:39], v[156:159], v[190:193], v[36:39]
	v_mfma_f32_16x16x32_bf16 v[32:35], v[164:167], v[190:193], v[32:35]
	v_mfma_f32_16x16x32_bf16 v[20:23], v[156:159], v[198:201], v[20:23]
	v_mfma_f32_16x16x32_bf16 v[16:19], v[164:167], v[198:201], v[16:19]
	v_mfma_f32_16x16x32_bf16 v[4:7], v[156:159], v[206:209], v[4:7]
	v_mfma_f32_16x16x32_bf16 v[0:3], v[164:167], v[206:209], v[0:3]
	v_mfma_f32_16x16x32_bf16 v[52:55], v[160:163], v[186:189], v[52:55]
	v_mfma_f32_16x16x32_bf16 v[48:51], v[168:171], v[186:189], v[48:51]
	v_mfma_f32_16x16x32_bf16 v[36:39], v[160:163], v[194:197], v[36:39]
	v_mfma_f32_16x16x32_bf16 v[32:35], v[168:171], v[194:197], v[32:35]
	v_mfma_f32_16x16x32_bf16 v[20:23], v[160:163], v[202:205], v[20:23]
	v_mfma_f32_16x16x32_bf16 v[16:19], v[168:171], v[202:205], v[16:19]
	v_mfma_f32_16x16x32_bf16 v[4:7], v[160:163], v[210:213], v[4:7]
	v_mfma_f32_16x16x32_bf16 v[0:3], v[168:171], v[210:213], v[0:3]
	s_barrier
	s_setprio 0
	s_add_i32 s68, s68, 2
	s_add_u32 s66, s66, 0x100
	s_addc_u32 s67, s67, 0
	s_cmpk_gt_u32 s68, 0x55
	s_mov_b64 s[40:41], s[6:7]
	s_cbranch_scc0 .LBB0_3426
	s_and_b64 vcc, exec, s[18:19]
	s_cbranch_vccz .LBB0_3429
	s_barrier
